# FF1, P1a, P1b K-loops: loader-wave LDS-DMA issue + 16x16x32 bf16 MFMA, bf16 epilogues in 16x16 layout
# speedup vs baseline: 1.1798x; 1.0260x over previous
; template <class AL, class BL>
; DEV void gemm_mainloop_p(Acc& acc, const AL& al, const BL& bl, int m0, int n0, int m0n, int n0n, int K, char* lds,
;                          GemmPipe& gp) {
;   const int tid = tidx_full();
;   const int wave = tid >> 6, lane = tid & 63;
;   const int wm = (wave >> 2) * 128, wn = (wave & 3) * 64;
;   const int lr = lane & 31, lh = lane >> 5;
;   const int nk = K / BK;
;   if (!gp.primed) {
;     gp.ra = al.load(tid, m0, 0);
;     gp.rb = bl.load(tid, n0, 0);
;     __syncthreads();
;     al.store(tid, lds, gp.ra);
;     bl.store(tid, lds + TILE_BYTES, gp.rb);
;     gp.ra = al.load(tid, m0, BK);
;     gp.rb = bl.load(tid, n0, BK);
;     __syncthreads();
;   }
; DEV void phase_p1(const Params& p, int g, char* smem) {
;     ...
;     for (int iter = 0;; ++iter) {
;       int mt, nt, mtn, ntn;
;       if (!tile_map(iter, 128, 18, mt, nt)) break;
;       const bool more = tile_map(iter + 1, 128, 18, mtn, ntn);
;       if (!more) { mtn = mt; ntn = nt; }
;       Acc acc;
;       acc_zero(acc);
;       const int m0 = mt * 256, n0 = nt * 256;
;       RowLoader al{H, 1024}, bl{WinT + (size_t)1536 * 1024, 1024};
;       gemm_mainloop_p(acc, al, bl, m0, n0, mtn * 256, ntn * 256, 1024, smem, gp);
.LBB0_278:
	s_and_b64 vcc, exec, s[2:3]
	s_lshl_b32 s5, s7, 8
	s_lshl_b32 s4, s8, 8
	v_lshrrev_b32_e32 v149, 6, v202
	v_and_b32_e32 v148, 63, v202
	s_nop 0
	v_readfirstlane_b32 s13, v149
	v_lshrrev_b32_e32 v150, 3, v148
	v_lshl_add_u32 v150, v149, 5, v150
	v_and_b32_e32 v151, 7, v148
	v_lshrrev_b32_e32 v128, 4, v148
	v_xor_b32_e32 v151, v128, v151
	v_lshlrev_b32_e32 v151, 4, v151
	s_lshl_b32 s13, s13, 12
	v_add_u32_e32 v128, s5, v150
	v_lshlrev_b32_e32 v128, 11, v128
	v_add_u32_e32 v128, v128, v151
	v_add_u32_e32 v129, 0x4000, v128
	v_add_u32_e32 v130, 0x8000, v128
	v_add_u32_e32 v131, 0xc000, v128
	v_xor_b32_e32 v129, 0x40, v129
	v_xor_b32_e32 v131, 0x40, v131
	v_add_u32_e32 v132, s4, v150
	v_lshlrev_b32_e32 v132, 11, v132
	v_add_u32_e32 v132, v132, v151
	v_add_u32_e32 v133, 0x4000, v132
	v_add_u32_e32 v134, 0x8000, v132
	v_add_u32_e32 v135, 0xc000, v132
	v_xor_b32_e32 v133, 0x40, v133
	v_xor_b32_e32 v135, 0x40, v135
	v_add_u32_e32 v136, 0x40000, v128
	v_add_u32_e32 v137, 0x40000, v129
	v_add_u32_e32 v138, 0x40000, v130
	v_add_u32_e32 v139, 0x40000, v131
	v_add_u32_e32 v140, 0x40000, v132
	v_add_u32_e32 v141, 0x40000, v133
	v_add_u32_e32 v142, 0x40000, v134
	v_add_u32_e32 v143, 0x40000, v135
	v_lshrrev_b32_e32 v161, 6, v202
	v_and_b32_e32 v160, 63, v202
	v_bfe_u32 v242, v160, 1, 3
	v_lshrrev_b32_e32 v243, 4, v160
	v_xor_b32_e32 v242, v242, v243
	v_lshlrev_b32_e32 v242, 4, v242
	v_and_b32_e32 v243, 15, v160
	v_lshlrev_b32_e32 v243, 7, v243
	v_lshrrev_b32_e32 v144, 2, v161
	v_lshl_add_u32 v144, v144, 14, v243
	v_and_b32_e32 v146, 3, v161
	v_lshl_add_u32 v146, v146, 13, v243
	v_add_u32_e32 v146, 0x10000, v146
	v_xor_b32_e32 v145, 0x40, v242
	v_add_u32_e32 v145, v144, v145
	v_add_u32_e32 v144, v144, v242
	v_xor_b32_e32 v147, 0x40, v242
	v_add_u32_e32 v147, v146, v147
	v_add_u32_e32 v146, v146, v242
	s_mov_b64 s[14:15], s[64:65]
	s_mov_b64 s[16:17], s[24:25]
	s_cbranch_vccnz .Lp1a_primed
	s_cmp_lt_u32 s13, 0x4000
	s_cbranch_scc0 .Lp1a_d1
	s_add_u32 m0, s13, 0x0
	s_nop 0
	global_load_lds_dwordx4 v128, s[14:15]
	s_add_u32 m0, m0, 0x400
	s_nop 0
	global_load_lds_dwordx4 v129, s[14:15]
	s_add_u32 m0, m0, 0x400
	s_nop 0
	global_load_lds_dwordx4 v130, s[14:15]
	s_add_u32 m0, m0, 0x400
	s_nop 0
	global_load_lds_dwordx4 v131, s[14:15]
	s_add_u32 m0, s13, 0x10000
	s_nop 0
	global_load_lds_dwordx4 v132, s[16:17]
	s_add_u32 m0, m0, 0x400
	s_nop 0
	global_load_lds_dwordx4 v133, s[16:17]
	s_add_u32 m0, m0, 0x400
	s_nop 0
	global_load_lds_dwordx4 v134, s[16:17]
	s_add_u32 m0, m0, 0x400
	s_nop 0
	global_load_lds_dwordx4 v135, s[16:17]
	s_add_u32 m0, s13, 0x4000
	s_nop 0
	global_load_lds_dwordx4 v136, s[14:15]
	s_add_u32 m0, m0, 0x400
	s_nop 0
	global_load_lds_dwordx4 v137, s[14:15]
	s_add_u32 m0, m0, 0x400
	s_nop 0
	global_load_lds_dwordx4 v138, s[14:15]
	s_add_u32 m0, m0, 0x400
	s_nop 0
	global_load_lds_dwordx4 v139, s[14:15]
	s_add_u32 m0, s13, 0x14000
	s_nop 0
	global_load_lds_dwordx4 v140, s[16:17]
	s_add_u32 m0, m0, 0x400
	s_nop 0
	global_load_lds_dwordx4 v141, s[16:17]
	s_add_u32 m0, m0, 0x400
	s_nop 0
	global_load_lds_dwordx4 v142, s[16:17]
	s_add_u32 m0, m0, 0x400
	s_nop 0
	global_load_lds_dwordx4 v143, s[16:17]
.Lp1a_d1:
.Lp1a_primed:
	s_add_u32 s14, s14, 0x80
	s_addc_u32 s15, s15, 0
	s_add_u32 s16, s16, 0x80
	s_addc_u32 s17, s17, 0
	v_mov_b32_e32 v0, 0
	v_mov_b32_e32 v1, 0
	v_mov_b64_e32 v[2:3], v[0:1]
	v_mov_b64_e32 v[4:5], v[0:1]
	v_mov_b64_e32 v[6:7], v[0:1]
	v_mov_b64_e32 v[8:9], v[0:1]
	v_mov_b64_e32 v[10:11], v[0:1]
	v_mov_b64_e32 v[12:13], v[0:1]
	v_mov_b64_e32 v[14:15], v[0:1]
	v_mov_b64_e32 v[16:17], v[0:1]
	v_mov_b64_e32 v[18:19], v[0:1]
	v_mov_b64_e32 v[20:21], v[0:1]
	v_mov_b64_e32 v[22:23], v[0:1]
	v_mov_b64_e32 v[24:25], v[0:1]
	v_mov_b64_e32 v[26:27], v[0:1]
	v_mov_b64_e32 v[28:29], v[0:1]
	v_mov_b64_e32 v[30:31], v[0:1]
	v_mov_b64_e32 v[32:33], v[0:1]
	v_mov_b64_e32 v[34:35], v[0:1]
	v_mov_b64_e32 v[36:37], v[0:1]
	v_mov_b64_e32 v[38:39], v[0:1]
	v_mov_b64_e32 v[40:41], v[0:1]
	v_mov_b64_e32 v[42:43], v[0:1]
	v_mov_b64_e32 v[44:45], v[0:1]
	v_mov_b64_e32 v[46:47], v[0:1]
	v_mov_b64_e32 v[48:49], v[0:1]
	v_mov_b64_e32 v[50:51], v[0:1]
	v_mov_b64_e32 v[52:53], v[0:1]
	v_mov_b64_e32 v[54:55], v[0:1]
	v_mov_b64_e32 v[56:57], v[0:1]
	v_mov_b64_e32 v[58:59], v[0:1]
	v_mov_b64_e32 v[60:61], v[0:1]
	v_mov_b64_e32 v[62:63], v[0:1]
	v_mov_b64_e32 v[64:65], v[0:1]
	v_mov_b64_e32 v[66:67], v[0:1]
	v_mov_b64_e32 v[68:69], v[0:1]
	v_mov_b64_e32 v[70:71], v[0:1]
	v_mov_b64_e32 v[72:73], v[0:1]
	v_mov_b64_e32 v[74:75], v[0:1]
	v_mov_b64_e32 v[76:77], v[0:1]
	v_mov_b64_e32 v[78:79], v[0:1]
	v_mov_b64_e32 v[80:81], v[0:1]
	v_mov_b64_e32 v[82:83], v[0:1]
	v_mov_b64_e32 v[84:85], v[0:1]
	v_mov_b64_e32 v[86:87], v[0:1]
	v_mov_b64_e32 v[88:89], v[0:1]
	v_mov_b64_e32 v[90:91], v[0:1]
	v_mov_b64_e32 v[92:93], v[0:1]
	v_mov_b64_e32 v[94:95], v[0:1]
	v_mov_b64_e32 v[96:97], v[0:1]
	v_mov_b64_e32 v[98:99], v[0:1]
	v_mov_b64_e32 v[100:101], v[0:1]
	v_mov_b64_e32 v[102:103], v[0:1]
	v_mov_b64_e32 v[104:105], v[0:1]
	v_mov_b64_e32 v[106:107], v[0:1]
	v_mov_b64_e32 v[108:109], v[0:1]
	v_mov_b64_e32 v[110:111], v[0:1]
	v_mov_b64_e32 v[112:113], v[0:1]
	v_mov_b64_e32 v[114:115], v[0:1]
	v_mov_b64_e32 v[116:117], v[0:1]
	v_mov_b64_e32 v[118:119], v[0:1]
	v_mov_b64_e32 v[120:121], v[0:1]
	v_mov_b64_e32 v[122:123], v[0:1]
	v_mov_b64_e32 v[124:125], v[0:1]
	v_mov_b64_e32 v[126:127], v[0:1]
	s_mov_b32 s18, 0
	s_waitcnt vmcnt(0)
	s_barrier
; template <class AL, class BL>
; DEV void gemm_ktile(Acc& acc, const char* A, const char* B, int wm, int wn, int lr, int lh, const AL& al, const BL& bl,
;                     int tid, int m0, int n0, int knext, char* nxt, R4& ra, R4& rb) {
;   bf16x8 a[2][4], b[2][2];
;   const char* pa = A + (wm + lr) * LDSROW + lh * 16;
;   const char* pb = B + (wn + lr) * LDSROW + lh * 16;
; #pragma unroll
;   for (int i = 0; i < 4; ++i) a[0][i] = *(const bf16x8*)(pa + 32 * i * LDSROW);
; #pragma unroll
;   for (int j = 0; j < 2; ++j) b[0][j] = *(const bf16x8*)(pb + 32 * j * LDSROW);
; #pragma unroll
;   for (int ks = 0; ks < 4; ++ks) {
;     const int cur = ks & 1, nx = cur ^ 1;
;     if (ks < 3) {
; #pragma unroll
;       for (int i = 0; i < 4; ++i) a[nx][i] = *(const bf16x8*)(pa + 32 * i * LDSROW + (ks + 1) * 32);
; #pragma unroll
;       for (int j = 0; j < 2; ++j) b[nx][j] = *(const bf16x8*)(pb + 32 * j * LDSROW + (ks + 1) * 32);
;     }
;     __builtin_amdgcn_sched_barrier(0);
; #pragma unroll
;     for (int i = 0; i < 4; ++i)
; #pragma unroll
;       for (int j = 0; j < 2; ++j)
;         acc[i][j] = __builtin_amdgcn_mfma_f32_32x32x16_bf16(a[cur][i], b[cur][j], acc[i][j], 0, 0, 0);
;     __builtin_amdgcn_sched_barrier(0);
;     if (ks == 1) {
;       al.store(tid, nxt, ra);
;       bl.store(tid, nxt + TILE_BYTES, rb);
;       __builtin_amdgcn_sched_barrier(0);
;       ra = al.load(tid, m0, knext);
;       rb = bl.load(tid, n0, knext);
;       __builtin_amdgcn_sched_barrier(0);
;     }
;   }
; template <class AL, class BL>
; DEV void gemm_mainloop_p(Acc& acc, const AL& al, const BL& bl, int m0, int n0, int m0n, int n0n, int K, char* lds,
;                          GemmPipe& gp) {
;     ...
;   for (int kt = 0; kt < nk; ++kt) {
;     const char* cur = lds + (kt & 1) * 2 * TILE_BYTES;
;     char* nxt = lds + ((kt + 1) & 1) * 2 * TILE_BYTES;
;     const bool wrap = (kt + 2 >= nk);
;     const int kk = (wrap ? kt + 2 - nk : kt + 2) * BK;
;     const int mr = wrap ? m0n : m0, nr = wrap ? n0n : n0;
;     __builtin_amdgcn_sched_barrier(0);
;     gemm_ktile(acc, cur, cur + TILE_BYTES, wm, wn, lr, lh, al, bl, tid, mr, nr, kk, nxt, gp.ra, gp.rb);
;     __builtin_amdgcn_sched_barrier(0);
;     __syncthreads();
;   }
.Lp1a_kloop:
	s_cmp_lt_u32 s13, 0x4000
	s_cbranch_scc0 .Lp1a_d2
	s_add_u32 m0, s13, 0x8000
	s_nop 0
	global_load_lds_dwordx4 v128, s[14:15]
	s_add_u32 m0, m0, 0x400
	s_nop 0
	global_load_lds_dwordx4 v129, s[14:15]
	s_add_u32 m0, m0, 0x400
	s_nop 0
	global_load_lds_dwordx4 v130, s[14:15]
	s_add_u32 m0, m0, 0x400
	s_nop 0
	global_load_lds_dwordx4 v131, s[14:15]
	s_add_u32 m0, s13, 0x18000
	s_nop 0
	global_load_lds_dwordx4 v132, s[16:17]
	s_add_u32 m0, m0, 0x400
	s_nop 0
	global_load_lds_dwordx4 v133, s[16:17]
	s_add_u32 m0, m0, 0x400
	s_nop 0
	global_load_lds_dwordx4 v134, s[16:17]
	s_add_u32 m0, m0, 0x400
	s_nop 0
	global_load_lds_dwordx4 v135, s[16:17]
	s_add_u32 m0, s13, 0xc000
	s_nop 0
	global_load_lds_dwordx4 v136, s[14:15]
	s_add_u32 m0, m0, 0x400
	s_nop 0
	global_load_lds_dwordx4 v137, s[14:15]
	s_add_u32 m0, m0, 0x400
	s_nop 0
	global_load_lds_dwordx4 v138, s[14:15]
	s_add_u32 m0, m0, 0x400
	s_nop 0
	global_load_lds_dwordx4 v139, s[14:15]
	s_add_u32 m0, s13, 0x1c000
	s_nop 0
	global_load_lds_dwordx4 v140, s[16:17]
	s_add_u32 m0, m0, 0x400
	s_nop 0
	global_load_lds_dwordx4 v141, s[16:17]
	s_add_u32 m0, m0, 0x400
	s_nop 0
	global_load_lds_dwordx4 v142, s[16:17]
	s_add_u32 m0, m0, 0x400
	s_nop 0
	global_load_lds_dwordx4 v143, s[16:17]
.Lp1a_d2:
	s_add_u32 s14, s14, 0x80
	s_addc_u32 s15, s15, 0
	s_add_u32 s16, s16, 0x80
	s_addc_u32 s17, s17, 0
	ds_read_b128 v[166:169], v146
	ds_read_b128 v[170:173], v146 offset:2048
	ds_read_b128 v[174:177], v146 offset:4096
	ds_read_b128 v[178:181], v146 offset:6144
	ds_read_b128 v[222:225], v144
	ds_read_b128 v[226:229], v144 offset:2048
	ds_read_b128 v[230:233], v144 offset:4096
	ds_read_b128 v[234:237], v144 offset:6144
	ds_read_b128 v[238:241], v144 offset:8192
	ds_read_b128 v[198:201], v144 offset:10240
	ds_read_b128 v[152:155], v144 offset:12288
	ds_read_b128 v[156:159], v144 offset:14336
	ds_read_b128 v[182:185], v147
	ds_read_b128 v[186:189], v147 offset:2048
	ds_read_b128 v[190:193], v147 offset:4096
	ds_read_b128 v[194:197], v147 offset:6144
	s_waitcnt lgkmcnt(8)
	v_mfma_f32_16x16x32_bf16 v[0:3], v[166:169], v[222:225], v[0:3]
	v_mfma_f32_16x16x32_bf16 v[4:7], v[170:173], v[222:225], v[4:7]
	v_mfma_f32_16x16x32_bf16 v[8:11], v[174:177], v[222:225], v[8:11]
	v_mfma_f32_16x16x32_bf16 v[12:15], v[178:181], v[222:225], v[12:15]
	v_mfma_f32_16x16x32_bf16 v[16:19], v[166:169], v[226:229], v[16:19]
	v_mfma_f32_16x16x32_bf16 v[20:23], v[170:173], v[226:229], v[20:23]
	v_mfma_f32_16x16x32_bf16 v[24:27], v[174:177], v[226:229], v[24:27]
	v_mfma_f32_16x16x32_bf16 v[28:31], v[178:181], v[226:229], v[28:31]
	v_mfma_f32_16x16x32_bf16 v[32:35], v[166:169], v[230:233], v[32:35]
	v_mfma_f32_16x16x32_bf16 v[36:39], v[170:173], v[230:233], v[36:39]
	v_mfma_f32_16x16x32_bf16 v[40:43], v[174:177], v[230:233], v[40:43]
	v_mfma_f32_16x16x32_bf16 v[44:47], v[178:181], v[230:233], v[44:47]
	v_mfma_f32_16x16x32_bf16 v[48:51], v[166:169], v[234:237], v[48:51]
	v_mfma_f32_16x16x32_bf16 v[52:55], v[170:173], v[234:237], v[52:55]
	v_mfma_f32_16x16x32_bf16 v[56:59], v[174:177], v[234:237], v[56:59]
	v_mfma_f32_16x16x32_bf16 v[60:63], v[178:181], v[234:237], v[60:63]
	ds_read_b128 v[222:225], v145
	ds_read_b128 v[226:229], v145 offset:2048
	ds_read_b128 v[230:233], v145 offset:4096
	ds_read_b128 v[234:237], v145 offset:6144
	s_waitcnt lgkmcnt(8)
	v_mfma_f32_16x16x32_bf16 v[64:67], v[166:169], v[238:241], v[64:67]
	v_mfma_f32_16x16x32_bf16 v[68:71], v[170:173], v[238:241], v[68:71]
	v_mfma_f32_16x16x32_bf16 v[72:75], v[174:177], v[238:241], v[72:75]
	v_mfma_f32_16x16x32_bf16 v[76:79], v[178:181], v[238:241], v[76:79]
	v_mfma_f32_16x16x32_bf16 v[80:83], v[166:169], v[198:201], v[80:83]
	v_mfma_f32_16x16x32_bf16 v[84:87], v[170:173], v[198:201], v[84:87]
	v_mfma_f32_16x16x32_bf16 v[88:91], v[174:177], v[198:201], v[88:91]
	v_mfma_f32_16x16x32_bf16 v[92:95], v[178:181], v[198:201], v[92:95]
	v_mfma_f32_16x16x32_bf16 v[96:99], v[166:169], v[152:155], v[96:99]
	v_mfma_f32_16x16x32_bf16 v[100:103], v[170:173], v[152:155], v[100:103]
	v_mfma_f32_16x16x32_bf16 v[104:107], v[174:177], v[152:155], v[104:107]
	v_mfma_f32_16x16x32_bf16 v[108:111], v[178:181], v[152:155], v[108:111]
	v_mfma_f32_16x16x32_bf16 v[112:115], v[166:169], v[156:159], v[112:115]
	v_mfma_f32_16x16x32_bf16 v[116:119], v[170:173], v[156:159], v[116:119]
	v_mfma_f32_16x16x32_bf16 v[120:123], v[174:177], v[156:159], v[120:123]
	v_mfma_f32_16x16x32_bf16 v[124:127], v[178:181], v[156:159], v[124:127]
	ds_read_b128 v[238:241], v145 offset:8192
	ds_read_b128 v[198:201], v145 offset:10240
	ds_read_b128 v[152:155], v145 offset:12288
	ds_read_b128 v[156:159], v145 offset:14336
	s_waitcnt lgkmcnt(4)
	v_mfma_f32_16x16x32_bf16 v[0:3], v[182:185], v[222:225], v[0:3]
	v_mfma_f32_16x16x32_bf16 v[4:7], v[186:189], v[222:225], v[4:7]
	v_mfma_f32_16x16x32_bf16 v[8:11], v[190:193], v[222:225], v[8:11]
	v_mfma_f32_16x16x32_bf16 v[12:15], v[194:197], v[222:225], v[12:15]
	v_mfma_f32_16x16x32_bf16 v[16:19], v[182:185], v[226:229], v[16:19]
	v_mfma_f32_16x16x32_bf16 v[20:23], v[186:189], v[226:229], v[20:23]
	v_mfma_f32_16x16x32_bf16 v[24:27], v[190:193], v[226:229], v[24:27]
	v_mfma_f32_16x16x32_bf16 v[28:31], v[194:197], v[226:229], v[28:31]
	v_mfma_f32_16x16x32_bf16 v[32:35], v[182:185], v[230:233], v[32:35]
	v_mfma_f32_16x16x32_bf16 v[36:39], v[186:189], v[230:233], v[36:39]
	v_mfma_f32_16x16x32_bf16 v[40:43], v[190:193], v[230:233], v[40:43]
	v_mfma_f32_16x16x32_bf16 v[44:47], v[194:197], v[230:233], v[44:47]
	v_mfma_f32_16x16x32_bf16 v[48:51], v[182:185], v[234:237], v[48:51]
	v_mfma_f32_16x16x32_bf16 v[52:55], v[186:189], v[234:237], v[52:55]
	v_mfma_f32_16x16x32_bf16 v[56:59], v[190:193], v[234:237], v[56:59]
	v_mfma_f32_16x16x32_bf16 v[60:63], v[194:197], v[234:237], v[60:63]
	s_waitcnt lgkmcnt(0)
	v_mfma_f32_16x16x32_bf16 v[64:67], v[182:185], v[238:241], v[64:67]
	v_mfma_f32_16x16x32_bf16 v[68:71], v[186:189], v[238:241], v[68:71]
	v_mfma_f32_16x16x32_bf16 v[72:75], v[190:193], v[238:241], v[72:75]
	v_mfma_f32_16x16x32_bf16 v[76:79], v[194:197], v[238:241], v[76:79]
	v_mfma_f32_16x16x32_bf16 v[80:83], v[182:185], v[198:201], v[80:83]
	v_mfma_f32_16x16x32_bf16 v[84:87], v[186:189], v[198:201], v[84:87]
	v_mfma_f32_16x16x32_bf16 v[88:91], v[190:193], v[198:201], v[88:91]
	v_mfma_f32_16x16x32_bf16 v[92:95], v[194:197], v[198:201], v[92:95]
	v_mfma_f32_16x16x32_bf16 v[96:99], v[182:185], v[152:155], v[96:99]
	v_mfma_f32_16x16x32_bf16 v[100:103], v[186:189], v[152:155], v[100:103]
	v_mfma_f32_16x16x32_bf16 v[104:107], v[190:193], v[152:155], v[104:107]
	v_mfma_f32_16x16x32_bf16 v[108:111], v[194:197], v[152:155], v[108:111]
	v_mfma_f32_16x16x32_bf16 v[112:115], v[182:185], v[156:159], v[112:115]
	v_mfma_f32_16x16x32_bf16 v[116:119], v[186:189], v[156:159], v[116:119]
	v_mfma_f32_16x16x32_bf16 v[120:123], v[190:193], v[156:159], v[120:123]
	v_mfma_f32_16x16x32_bf16 v[124:127], v[194:197], v[156:159], v[124:127]
	s_waitcnt vmcnt(0)
	s_barrier
; template <class AL, class BL>
; DEV void gemm_ktile(Acc& acc, const char* A, const char* B, int wm, int wn, int lr, int lh, const AL& al, const BL& bl,
;                     int tid, int m0, int n0, int knext, char* nxt, R4& ra, R4& rb) {
;   bf16x8 a[2][4], b[2][2];
;   const char* pa = A + (wm + lr) * LDSROW + lh * 16;
;   const char* pb = B + (wn + lr) * LDSROW + lh * 16;
; #pragma unroll
;   for (int i = 0; i < 4; ++i) a[0][i] = *(const bf16x8*)(pa + 32 * i * LDSROW);
; #pragma unroll
;   for (int j = 0; j < 2; ++j) b[0][j] = *(const bf16x8*)(pb + 32 * j * LDSROW);
; #pragma unroll
;   for (int ks = 0; ks < 4; ++ks) {
;     const int cur = ks & 1, nx = cur ^ 1;
;     if (ks < 3) {
; #pragma unroll
;       for (int i = 0; i < 4; ++i) a[nx][i] = *(const bf16x8*)(pa + 32 * i * LDSROW + (ks + 1) * 32);
; #pragma unroll
;       for (int j = 0; j < 2; ++j) b[nx][j] = *(const bf16x8*)(pb + 32 * j * LDSROW + (ks + 1) * 32);
;     }
;     __builtin_amdgcn_sched_barrier(0);
; #pragma unroll
;     for (int i = 0; i < 4; ++i)
; #pragma unroll
;       for (int j = 0; j < 2; ++j)
;         acc[i][j] = __builtin_amdgcn_mfma_f32_32x32x16_bf16(a[cur][i], b[cur][j], acc[i][j], 0, 0, 0);
;     __builtin_amdgcn_sched_barrier(0);
;     if (ks == 1) {
;       al.store(tid, nxt, ra);
;       bl.store(tid, nxt + TILE_BYTES, rb);
;       __builtin_amdgcn_sched_barrier(0);
;       ra = al.load(tid, m0, knext);
;       rb = bl.load(tid, n0, knext);
;       __builtin_amdgcn_sched_barrier(0);
;     }
;   }
; template <class AL, class BL>
; DEV void gemm_mainloop_p(Acc& acc, const AL& al, const BL& bl, int m0, int n0, int m0n, int n0n, int K, char* lds,
;                          GemmPipe& gp) {
;     ...
;   for (int kt = 0; kt < nk; ++kt) {
;     const char* cur = lds + (kt & 1) * 2 * TILE_BYTES;
;     char* nxt = lds + ((kt + 1) & 1) * 2 * TILE_BYTES;
;     const bool wrap = (kt + 2 >= nk);
;     const int kk = (wrap ? kt + 2 - nk : kt + 2) * BK;
;     const int mr = wrap ? m0n : m0, nr = wrap ? n0n : n0;
;     __builtin_amdgcn_sched_barrier(0);
;     gemm_ktile(acc, cur, cur + TILE_BYTES, wm, wn, lr, lh, al, bl, tid, mr, nr, kk, nxt, gp.ra, gp.rb);
;     __builtin_amdgcn_sched_barrier(0);
;     __syncthreads();
;   }
	s_cmp_eq_u32 s18, 7
	s_cbranch_scc1 .Lp1a_last
	s_cmp_lt_u32 s13, 0x4000
	s_cbranch_scc0 .Lp1a_d3
	s_add_u32 m0, s13, 0x0
	s_nop 0
	global_load_lds_dwordx4 v128, s[14:15]
	s_add_u32 m0, m0, 0x400
	s_nop 0
	global_load_lds_dwordx4 v129, s[14:15]
	s_add_u32 m0, m0, 0x400
	s_nop 0
	global_load_lds_dwordx4 v130, s[14:15]
	s_add_u32 m0, m0, 0x400
	s_nop 0
	global_load_lds_dwordx4 v131, s[14:15]
	s_add_u32 m0, s13, 0x10000
	s_nop 0
	global_load_lds_dwordx4 v132, s[16:17]
	s_add_u32 m0, m0, 0x400
	s_nop 0
	global_load_lds_dwordx4 v133, s[16:17]
	s_add_u32 m0, m0, 0x400
	s_nop 0
	global_load_lds_dwordx4 v134, s[16:17]
	s_add_u32 m0, m0, 0x400
	s_nop 0
	global_load_lds_dwordx4 v135, s[16:17]
	s_add_u32 m0, s13, 0x4000
	s_nop 0
	global_load_lds_dwordx4 v136, s[14:15]
	s_add_u32 m0, m0, 0x400
	s_nop 0
	global_load_lds_dwordx4 v137, s[14:15]
	s_add_u32 m0, m0, 0x400
	s_nop 0
	global_load_lds_dwordx4 v138, s[14:15]
	s_add_u32 m0, m0, 0x400
	s_nop 0
	global_load_lds_dwordx4 v139, s[14:15]
	s_add_u32 m0, s13, 0x14000
	s_nop 0
	global_load_lds_dwordx4 v140, s[16:17]
	s_add_u32 m0, m0, 0x400
	s_nop 0
	global_load_lds_dwordx4 v141, s[16:17]
	s_add_u32 m0, m0, 0x400
	s_nop 0
	global_load_lds_dwordx4 v142, s[16:17]
	s_add_u32 m0, m0, 0x400
	s_nop 0
	global_load_lds_dwordx4 v143, s[16:17]
.Lp1a_d3:
	s_add_u32 s14, s14, 0x80
	s_addc_u32 s15, s15, 0
	s_add_u32 s16, s16, 0x80
	s_addc_u32 s17, s17, 0
	ds_read_b128 v[166:169], v146 offset:32768
	ds_read_b128 v[170:173], v146 offset:34816
	ds_read_b128 v[174:177], v146 offset:36864
	ds_read_b128 v[178:181], v146 offset:38912
	ds_read_b128 v[222:225], v144 offset:32768
	ds_read_b128 v[226:229], v144 offset:34816
	ds_read_b128 v[230:233], v144 offset:36864
	ds_read_b128 v[234:237], v144 offset:38912
	ds_read_b128 v[238:241], v144 offset:40960
	ds_read_b128 v[198:201], v144 offset:43008
	ds_read_b128 v[152:155], v144 offset:45056
	ds_read_b128 v[156:159], v144 offset:47104
	ds_read_b128 v[182:185], v147 offset:32768
	ds_read_b128 v[186:189], v147 offset:34816
	ds_read_b128 v[190:193], v147 offset:36864
	ds_read_b128 v[194:197], v147 offset:38912
	s_waitcnt lgkmcnt(8)
	v_mfma_f32_16x16x32_bf16 v[0:3], v[166:169], v[222:225], v[0:3]
	v_mfma_f32_16x16x32_bf16 v[4:7], v[170:173], v[222:225], v[4:7]
	v_mfma_f32_16x16x32_bf16 v[8:11], v[174:177], v[222:225], v[8:11]
	v_mfma_f32_16x16x32_bf16 v[12:15], v[178:181], v[222:225], v[12:15]
	v_mfma_f32_16x16x32_bf16 v[16:19], v[166:169], v[226:229], v[16:19]
	v_mfma_f32_16x16x32_bf16 v[20:23], v[170:173], v[226:229], v[20:23]
	v_mfma_f32_16x16x32_bf16 v[24:27], v[174:177], v[226:229], v[24:27]
	v_mfma_f32_16x16x32_bf16 v[28:31], v[178:181], v[226:229], v[28:31]
	v_mfma_f32_16x16x32_bf16 v[32:35], v[166:169], v[230:233], v[32:35]
	v_mfma_f32_16x16x32_bf16 v[36:39], v[170:173], v[230:233], v[36:39]
	v_mfma_f32_16x16x32_bf16 v[40:43], v[174:177], v[230:233], v[40:43]
	v_mfma_f32_16x16x32_bf16 v[44:47], v[178:181], v[230:233], v[44:47]
	v_mfma_f32_16x16x32_bf16 v[48:51], v[166:169], v[234:237], v[48:51]
	v_mfma_f32_16x16x32_bf16 v[52:55], v[170:173], v[234:237], v[52:55]
	v_mfma_f32_16x16x32_bf16 v[56:59], v[174:177], v[234:237], v[56:59]
	v_mfma_f32_16x16x32_bf16 v[60:63], v[178:181], v[234:237], v[60:63]
	ds_read_b128 v[222:225], v145 offset:32768
	ds_read_b128 v[226:229], v145 offset:34816
	ds_read_b128 v[230:233], v145 offset:36864
	ds_read_b128 v[234:237], v145 offset:38912
	s_waitcnt lgkmcnt(8)
	v_mfma_f32_16x16x32_bf16 v[64:67], v[166:169], v[238:241], v[64:67]
	v_mfma_f32_16x16x32_bf16 v[68:71], v[170:173], v[238:241], v[68:71]
	v_mfma_f32_16x16x32_bf16 v[72:75], v[174:177], v[238:241], v[72:75]
	v_mfma_f32_16x16x32_bf16 v[76:79], v[178:181], v[238:241], v[76:79]
	v_mfma_f32_16x16x32_bf16 v[80:83], v[166:169], v[198:201], v[80:83]
	v_mfma_f32_16x16x32_bf16 v[84:87], v[170:173], v[198:201], v[84:87]
	v_mfma_f32_16x16x32_bf16 v[88:91], v[174:177], v[198:201], v[88:91]
	v_mfma_f32_16x16x32_bf16 v[92:95], v[178:181], v[198:201], v[92:95]
	v_mfma_f32_16x16x32_bf16 v[96:99], v[166:169], v[152:155], v[96:99]
	v_mfma_f32_16x16x32_bf16 v[100:103], v[170:173], v[152:155], v[100:103]
	v_mfma_f32_16x16x32_bf16 v[104:107], v[174:177], v[152:155], v[104:107]
	v_mfma_f32_16x16x32_bf16 v[108:111], v[178:181], v[152:155], v[108:111]
	v_mfma_f32_16x16x32_bf16 v[112:115], v[166:169], v[156:159], v[112:115]
	v_mfma_f32_16x16x32_bf16 v[116:119], v[170:173], v[156:159], v[116:119]
	v_mfma_f32_16x16x32_bf16 v[120:123], v[174:177], v[156:159], v[120:123]
	v_mfma_f32_16x16x32_bf16 v[124:127], v[178:181], v[156:159], v[124:127]
	ds_read_b128 v[238:241], v145 offset:40960
	ds_read_b128 v[198:201], v145 offset:43008
	ds_read_b128 v[152:155], v145 offset:45056
	ds_read_b128 v[156:159], v145 offset:47104
	s_waitcnt lgkmcnt(4)
	v_mfma_f32_16x16x32_bf16 v[0:3], v[182:185], v[222:225], v[0:3]
	v_mfma_f32_16x16x32_bf16 v[4:7], v[186:189], v[222:225], v[4:7]
	v_mfma_f32_16x16x32_bf16 v[8:11], v[190:193], v[222:225], v[8:11]
	v_mfma_f32_16x16x32_bf16 v[12:15], v[194:197], v[222:225], v[12:15]
	v_mfma_f32_16x16x32_bf16 v[16:19], v[182:185], v[226:229], v[16:19]
	v_mfma_f32_16x16x32_bf16 v[20:23], v[186:189], v[226:229], v[20:23]
	v_mfma_f32_16x16x32_bf16 v[24:27], v[190:193], v[226:229], v[24:27]
	v_mfma_f32_16x16x32_bf16 v[28:31], v[194:197], v[226:229], v[28:31]
	v_mfma_f32_16x16x32_bf16 v[32:35], v[182:185], v[230:233], v[32:35]
	v_mfma_f32_16x16x32_bf16 v[36:39], v[186:189], v[230:233], v[36:39]
	v_mfma_f32_16x16x32_bf16 v[40:43], v[190:193], v[230:233], v[40:43]
	v_mfma_f32_16x16x32_bf16 v[44:47], v[194:197], v[230:233], v[44:47]
	v_mfma_f32_16x16x32_bf16 v[48:51], v[182:185], v[234:237], v[48:51]
	v_mfma_f32_16x16x32_bf16 v[52:55], v[186:189], v[234:237], v[52:55]
	v_mfma_f32_16x16x32_bf16 v[56:59], v[190:193], v[234:237], v[56:59]
	v_mfma_f32_16x16x32_bf16 v[60:63], v[194:197], v[234:237], v[60:63]
	s_waitcnt lgkmcnt(0)
	v_mfma_f32_16x16x32_bf16 v[64:67], v[182:185], v[238:241], v[64:67]
	v_mfma_f32_16x16x32_bf16 v[68:71], v[186:189], v[238:241], v[68:71]
	v_mfma_f32_16x16x32_bf16 v[72:75], v[190:193], v[238:241], v[72:75]
	v_mfma_f32_16x16x32_bf16 v[76:79], v[194:197], v[238:241], v[76:79]
	v_mfma_f32_16x16x32_bf16 v[80:83], v[182:185], v[198:201], v[80:83]
	v_mfma_f32_16x16x32_bf16 v[84:87], v[186:189], v[198:201], v[84:87]
	v_mfma_f32_16x16x32_bf16 v[88:91], v[190:193], v[198:201], v[88:91]
	v_mfma_f32_16x16x32_bf16 v[92:95], v[194:197], v[198:201], v[92:95]
	v_mfma_f32_16x16x32_bf16 v[96:99], v[182:185], v[152:155], v[96:99]
	v_mfma_f32_16x16x32_bf16 v[100:103], v[186:189], v[152:155], v[100:103]
	v_mfma_f32_16x16x32_bf16 v[104:107], v[190:193], v[152:155], v[104:107]
	v_mfma_f32_16x16x32_bf16 v[108:111], v[194:197], v[152:155], v[108:111]
	v_mfma_f32_16x16x32_bf16 v[112:115], v[182:185], v[156:159], v[112:115]
	v_mfma_f32_16x16x32_bf16 v[116:119], v[186:189], v[156:159], v[116:119]
	v_mfma_f32_16x16x32_bf16 v[120:123], v[190:193], v[156:159], v[120:123]
	v_mfma_f32_16x16x32_bf16 v[124:127], v[194:197], v[156:159], v[124:127]
	s_add_i32 s18, s18, 1
	s_waitcnt vmcnt(0)
	s_barrier
; template <class AL, class BL>
; DEV void gemm_ktile(Acc& acc, const char* A, const char* B, int wm, int wn, int lr, int lh, const AL& al, const BL& bl,
;                     int tid, int m0, int n0, int knext, char* nxt, R4& ra, R4& rb) {
;   bf16x8 a[2][4], b[2][2];
;   const char* pa = A + (wm + lr) * LDSROW + lh * 16;
;   const char* pb = B + (wn + lr) * LDSROW + lh * 16;
; #pragma unroll
;   for (int i = 0; i < 4; ++i) a[0][i] = *(const bf16x8*)(pa + 32 * i * LDSROW);
; #pragma unroll
;   for (int j = 0; j < 2; ++j) b[0][j] = *(const bf16x8*)(pb + 32 * j * LDSROW);
; #pragma unroll
;   for (int ks = 0; ks < 4; ++ks) {
;     const int cur = ks & 1, nx = cur ^ 1;
;     if (ks < 3) {
; #pragma unroll
;       for (int i = 0; i < 4; ++i) a[nx][i] = *(const bf16x8*)(pa + 32 * i * LDSROW + (ks + 1) * 32);
; #pragma unroll
;       for (int j = 0; j < 2; ++j) b[nx][j] = *(const bf16x8*)(pb + 32 * j * LDSROW + (ks + 1) * 32);
;     }
;     __builtin_amdgcn_sched_barrier(0);
; #pragma unroll
;     for (int i = 0; i < 4; ++i)
; #pragma unroll
;       for (int j = 0; j < 2; ++j)
;         acc[i][j] = __builtin_amdgcn_mfma_f32_32x32x16_bf16(a[cur][i], b[cur][j], acc[i][j], 0, 0, 0);
;     __builtin_amdgcn_sched_barrier(0);
;     if (ks == 1) {
;       al.store(tid, nxt, ra);
;       bl.store(tid, nxt + TILE_BYTES, rb);
;       __builtin_amdgcn_sched_barrier(0);
;       ra = al.load(tid, m0, knext);
;       rb = bl.load(tid, n0, knext);
;       __builtin_amdgcn_sched_barrier(0);
;     }
;   }
	s_branch .Lp1a_kloop
.Lp1a_last:
	ds_read_b128 v[166:169], v146 offset:32768
	ds_read_b128 v[170:173], v146 offset:34816
	ds_read_b128 v[174:177], v146 offset:36864
	ds_read_b128 v[178:181], v146 offset:38912
	ds_read_b128 v[222:225], v144 offset:32768
	ds_read_b128 v[226:229], v144 offset:34816
	ds_read_b128 v[230:233], v144 offset:36864
	ds_read_b128 v[234:237], v144 offset:38912
	ds_read_b128 v[238:241], v144 offset:40960
	ds_read_b128 v[198:201], v144 offset:43008
	ds_read_b128 v[152:155], v144 offset:45056
	ds_read_b128 v[156:159], v144 offset:47104
	ds_read_b128 v[182:185], v147 offset:32768
	ds_read_b128 v[186:189], v147 offset:34816
	ds_read_b128 v[190:193], v147 offset:36864
	ds_read_b128 v[194:197], v147 offset:38912
	s_waitcnt lgkmcnt(8)
	v_mfma_f32_16x16x32_bf16 v[0:3], v[166:169], v[222:225], v[0:3]
	v_mfma_f32_16x16x32_bf16 v[4:7], v[170:173], v[222:225], v[4:7]
	v_mfma_f32_16x16x32_bf16 v[8:11], v[174:177], v[222:225], v[8:11]
	v_mfma_f32_16x16x32_bf16 v[12:15], v[178:181], v[222:225], v[12:15]
	v_mfma_f32_16x16x32_bf16 v[16:19], v[166:169], v[226:229], v[16:19]
	v_mfma_f32_16x16x32_bf16 v[20:23], v[170:173], v[226:229], v[20:23]
	v_mfma_f32_16x16x32_bf16 v[24:27], v[174:177], v[226:229], v[24:27]
	v_mfma_f32_16x16x32_bf16 v[28:31], v[178:181], v[226:229], v[28:31]
	v_mfma_f32_16x16x32_bf16 v[32:35], v[166:169], v[230:233], v[32:35]
	v_mfma_f32_16x16x32_bf16 v[36:39], v[170:173], v[230:233], v[36:39]
	v_mfma_f32_16x16x32_bf16 v[40:43], v[174:177], v[230:233], v[40:43]
	v_mfma_f32_16x16x32_bf16 v[44:47], v[178:181], v[230:233], v[44:47]
	v_mfma_f32_16x16x32_bf16 v[48:51], v[166:169], v[234:237], v[48:51]
	v_mfma_f32_16x16x32_bf16 v[52:55], v[170:173], v[234:237], v[52:55]
	v_mfma_f32_16x16x32_bf16 v[56:59], v[174:177], v[234:237], v[56:59]
	v_mfma_f32_16x16x32_bf16 v[60:63], v[178:181], v[234:237], v[60:63]
	ds_read_b128 v[222:225], v145 offset:32768
	ds_read_b128 v[226:229], v145 offset:34816
	ds_read_b128 v[230:233], v145 offset:36864
	ds_read_b128 v[234:237], v145 offset:38912
	s_waitcnt lgkmcnt(8)
	v_mfma_f32_16x16x32_bf16 v[64:67], v[166:169], v[238:241], v[64:67]
	v_mfma_f32_16x16x32_bf16 v[68:71], v[170:173], v[238:241], v[68:71]
	v_mfma_f32_16x16x32_bf16 v[72:75], v[174:177], v[238:241], v[72:75]
	v_mfma_f32_16x16x32_bf16 v[76:79], v[178:181], v[238:241], v[76:79]
	v_mfma_f32_16x16x32_bf16 v[80:83], v[166:169], v[198:201], v[80:83]
	v_mfma_f32_16x16x32_bf16 v[84:87], v[170:173], v[198:201], v[84:87]
	v_mfma_f32_16x16x32_bf16 v[88:91], v[174:177], v[198:201], v[88:91]
	v_mfma_f32_16x16x32_bf16 v[92:95], v[178:181], v[198:201], v[92:95]
	v_mfma_f32_16x16x32_bf16 v[96:99], v[166:169], v[152:155], v[96:99]
	v_mfma_f32_16x16x32_bf16 v[100:103], v[170:173], v[152:155], v[100:103]
	v_mfma_f32_16x16x32_bf16 v[104:107], v[174:177], v[152:155], v[104:107]
	v_mfma_f32_16x16x32_bf16 v[108:111], v[178:181], v[152:155], v[108:111]
	v_mfma_f32_16x16x32_bf16 v[112:115], v[166:169], v[156:159], v[112:115]
	v_mfma_f32_16x16x32_bf16 v[116:119], v[170:173], v[156:159], v[116:119]
	v_mfma_f32_16x16x32_bf16 v[120:123], v[174:177], v[156:159], v[120:123]
	v_mfma_f32_16x16x32_bf16 v[124:127], v[178:181], v[156:159], v[124:127]
	ds_read_b128 v[238:241], v145 offset:40960
	ds_read_b128 v[198:201], v145 offset:43008
	ds_read_b128 v[152:155], v145 offset:45056
	ds_read_b128 v[156:159], v145 offset:47104
	s_waitcnt lgkmcnt(4)
	v_mfma_f32_16x16x32_bf16 v[0:3], v[182:185], v[222:225], v[0:3]
	v_mfma_f32_16x16x32_bf16 v[4:7], v[186:189], v[222:225], v[4:7]
	v_mfma_f32_16x16x32_bf16 v[8:11], v[190:193], v[222:225], v[8:11]
	v_mfma_f32_16x16x32_bf16 v[12:15], v[194:197], v[222:225], v[12:15]
	v_mfma_f32_16x16x32_bf16 v[16:19], v[182:185], v[226:229], v[16:19]
	v_mfma_f32_16x16x32_bf16 v[20:23], v[186:189], v[226:229], v[20:23]
	v_mfma_f32_16x16x32_bf16 v[24:27], v[190:193], v[226:229], v[24:27]
	v_mfma_f32_16x16x32_bf16 v[28:31], v[194:197], v[226:229], v[28:31]
	v_mfma_f32_16x16x32_bf16 v[32:35], v[182:185], v[230:233], v[32:35]
	v_mfma_f32_16x16x32_bf16 v[36:39], v[186:189], v[230:233], v[36:39]
	v_mfma_f32_16x16x32_bf16 v[40:43], v[190:193], v[230:233], v[40:43]
	v_mfma_f32_16x16x32_bf16 v[44:47], v[194:197], v[230:233], v[44:47]
	v_mfma_f32_16x16x32_bf16 v[48:51], v[182:185], v[234:237], v[48:51]
	v_mfma_f32_16x16x32_bf16 v[52:55], v[186:189], v[234:237], v[52:55]
	v_mfma_f32_16x16x32_bf16 v[56:59], v[190:193], v[234:237], v[56:59]
	v_mfma_f32_16x16x32_bf16 v[60:63], v[194:197], v[234:237], v[60:63]
	s_waitcnt lgkmcnt(0)
	v_mfma_f32_16x16x32_bf16 v[64:67], v[182:185], v[238:241], v[64:67]
	v_mfma_f32_16x16x32_bf16 v[68:71], v[186:189], v[238:241], v[68:71]
	v_mfma_f32_16x16x32_bf16 v[72:75], v[190:193], v[238:241], v[72:75]
	v_mfma_f32_16x16x32_bf16 v[76:79], v[194:197], v[238:241], v[76:79]
	v_mfma_f32_16x16x32_bf16 v[80:83], v[182:185], v[198:201], v[80:83]
	v_mfma_f32_16x16x32_bf16 v[84:87], v[186:189], v[198:201], v[84:87]
	v_mfma_f32_16x16x32_bf16 v[88:91], v[190:193], v[198:201], v[88:91]
	v_mfma_f32_16x16x32_bf16 v[92:95], v[194:197], v[198:201], v[92:95]
	v_mfma_f32_16x16x32_bf16 v[96:99], v[182:185], v[152:155], v[96:99]
	v_mfma_f32_16x16x32_bf16 v[100:103], v[186:189], v[152:155], v[100:103]
	v_mfma_f32_16x16x32_bf16 v[104:107], v[190:193], v[152:155], v[104:107]
	v_mfma_f32_16x16x32_bf16 v[108:111], v[194:197], v[152:155], v[108:111]
	v_mfma_f32_16x16x32_bf16 v[112:115], v[182:185], v[156:159], v[112:115]
	v_mfma_f32_16x16x32_bf16 v[116:119], v[186:189], v[156:159], v[116:119]
	v_mfma_f32_16x16x32_bf16 v[120:123], v[190:193], v[156:159], v[120:123]
	v_mfma_f32_16x16x32_bf16 v[124:127], v[194:197], v[156:159], v[124:127]
	s_barrier
; DEV u16 f2bf(float f) { return (u16)(pack2(f, f) & 0xffffu); }
; DEV float silu_f(float x) { return x / (1.f + __expf(-x)); }
; template <class AL, class BL>
; DEV void gemm_mainloop_p(Acc& acc, const AL& al, const BL& bl, int m0, int n0, int m0n, int n0n, int K, char* lds,
;                          GemmPipe& gp) {
;     ...
;   if (!gp.primed) {
;     gp.ra = al.load(tid, m0, 0);
;     gp.rb = bl.load(tid, n0, 0);
;     __syncthreads();
;     al.store(tid, lds, gp.ra);
;     bl.store(tid, lds + TILE_BYTES, gp.rb);
;     gp.ra = al.load(tid, m0, BK);
;     gp.rb = bl.load(tid, n0, BK);
;     __syncthreads();
; DEV void phase_p1(const Params& p, int g, char* smem) {
;     ...
;       const bool more = tile_map(iter + 1, 128, 18, mtn, ntn);
;       if (!more) { mtn = mt; ntn = nt; }
;       Acc acc;
;       acc_zero(acc);
;       const int m0 = mt * 256, n0 = nt * 256;
;       RowLoader al{H, 1024}, bl{WinT + (size_t)1536 * 1024, 1024};
;       gemm_mainloop_p(acc, al, bl, m0, n0, mtn * 256, ntn * 256, 1024, smem, gp);
;       gp.primed = more;
;       if (n0 < 2560) {
;         const bool dosilu = (n0 < 512) || (n0 >= 2048);
;         acc_foreach(acc, m0, n0, [&](int m, int n, float& v) {
;           const float o = dosilu ? silu_f(v) : v;
;           PHG[(size_t)m * 2560 + n] = f2bf(o);
	s_and_b64 vcc, exec, s[0:1]
	s_cbranch_vccz .Lp1a_nomore
	s_lshl_b32 s9, s11, 8
	s_lshl_b32 s10, s12, 8
	v_add_u32_e32 v128, s9, v150
	v_lshlrev_b32_e32 v128, 11, v128
	v_add_u32_e32 v128, v128, v151
	v_add_u32_e32 v129, 0x4000, v128
	v_add_u32_e32 v130, 0x8000, v128
	v_add_u32_e32 v131, 0xc000, v128
	v_xor_b32_e32 v129, 0x40, v129
	v_xor_b32_e32 v131, 0x40, v131
	v_add_u32_e32 v132, s10, v150
	v_lshlrev_b32_e32 v132, 11, v132
	v_add_u32_e32 v132, v132, v151
	v_add_u32_e32 v133, 0x4000, v132
	v_add_u32_e32 v134, 0x8000, v132
	v_add_u32_e32 v135, 0xc000, v132
	v_xor_b32_e32 v133, 0x40, v133
	v_xor_b32_e32 v135, 0x40, v135
	v_add_u32_e32 v136, 0x40000, v128
	v_add_u32_e32 v137, 0x40000, v129
	v_add_u32_e32 v138, 0x40000, v130
	v_add_u32_e32 v139, 0x40000, v131
	v_add_u32_e32 v140, 0x40000, v132
	v_add_u32_e32 v141, 0x40000, v133
	v_add_u32_e32 v142, 0x40000, v134
	v_add_u32_e32 v143, 0x40000, v135
	s_mov_b64 s[14:15], s[64:65]
	s_mov_b64 s[16:17], s[24:25]
	s_cmp_lt_u32 s13, 0x4000
	s_cbranch_scc0 .Lp1a_d4
	s_add_u32 m0, s13, 0x0
	s_nop 0
	global_load_lds_dwordx4 v128, s[14:15]
	s_add_u32 m0, m0, 0x400
	s_nop 0
	global_load_lds_dwordx4 v129, s[14:15]
	s_add_u32 m0, m0, 0x400
	s_nop 0
	global_load_lds_dwordx4 v130, s[14:15]
	s_add_u32 m0, m0, 0x400
	s_nop 0
	global_load_lds_dwordx4 v131, s[14:15]
	s_add_u32 m0, s13, 0x10000
	s_nop 0
	global_load_lds_dwordx4 v132, s[16:17]
	s_add_u32 m0, m0, 0x400
	s_nop 0
	global_load_lds_dwordx4 v133, s[16:17]
	s_add_u32 m0, m0, 0x400
	s_nop 0
	global_load_lds_dwordx4 v134, s[16:17]
	s_add_u32 m0, m0, 0x400
	s_nop 0
	global_load_lds_dwordx4 v135, s[16:17]
	s_add_u32 m0, s13, 0x4000
	s_nop 0
	global_load_lds_dwordx4 v136, s[14:15]
	s_add_u32 m0, m0, 0x400
	s_nop 0
	global_load_lds_dwordx4 v137, s[14:15]
	s_add_u32 m0, m0, 0x400
	s_nop 0
	global_load_lds_dwordx4 v138, s[14:15]
	s_add_u32 m0, m0, 0x400
	s_nop 0
	global_load_lds_dwordx4 v139, s[14:15]
	s_add_u32 m0, s13, 0x14000
	s_nop 0
	global_load_lds_dwordx4 v140, s[16:17]
	s_add_u32 m0, m0, 0x400
	s_nop 0
	global_load_lds_dwordx4 v141, s[16:17]
	s_add_u32 m0, m0, 0x400
	s_nop 0
	global_load_lds_dwordx4 v142, s[16:17]
	s_add_u32 m0, m0, 0x400
	s_nop 0
	global_load_lds_dwordx4 v143, s[16:17]
.Lp1a_d4:
.Lp1a_nomore:
	s_cmp_gt_i32 s8, 9
	s_cbranch_scc1 .Lp1a_gt
	s_cmp_lt_u32 s8, 2
	s_cbranch_scc1 .Lp1a_silu
	s_cmp_gt_u32 s8, 7
	s_cbranch_scc1 .Lp1a_silu
	s_nop 7
	s_nop 7
	s_nop 3
	v_and_b32_e32 v160, 63, v202
	v_lshrrev_b32_e32 v161, 6, v202
	v_and_b32_e32 v164, 3, v161
	v_lshlrev_b32_e32 v164, 13, v164
	v_add_u32_e32 v164, 0x8000, v164
	v_lshrrev_b32_e32 v160, 2, v161
	v_lshl_add_u32 v164, v160, 16, v164
	v_and_b32_e32 v160, 63, v202
	v_and_b32_e32 v166, 15, v160
	v_lshrrev_b32_e32 v167, 4, v160
	v_lshl_add_u32 v168, v166, 7, v164
	v_and_b32_e32 v169, 1, v167
	v_lshl_add_u32 v168, v169, 3, v168
	v_lshrrev_b32_e32 v167, 1, v167
	v_and_b32_e32 v166, 7, v166
	v_xor_b32_e32 v166, v166, v167
	v_lshlrev_b32_e32 v166, 4, v166
	v_add_u32_e32 v170, v168, v166
	v_xor_b32_e32 v167, 0x20, v166
	v_add_u32_e32 v171, v168, v167
	v_xor_b32_e32 v167, 0x40, v166
	v_add_u32_e32 v172, v168, v167
	v_xor_b32_e32 v167, 0x60, v166
	v_add_u32_e32 v173, v168, v167
	v_and_b32_e32 v166, 31, v160
	v_lshrrev_b32_e32 v167, 5, v160
	v_lshlrev_b32_e32 v168, 7, v166
	v_lshl_add_u32 v168, v167, 3, v168
	v_add_u32_e32 v168, v164, v168
	v_and_b32_e32 v166, 7, v166
	v_lshlrev_b32_e32 v166, 4, v166
	v_lshrrev_b32_e32 v166, 3, v160
	v_and_b32_e32 v167, 7, v160
	v_lshrrev_b32_e32 v169, 2, v161
	v_lshl_add_u32 v169, v169, 7, v166
	v_add_u32_e32 v169, s5, v169
	v_mul_u32_u24_e32 v169, 0x1400, v169
	v_and_b32_e32 v168, 3, v161
	v_lshlrev_b32_e32 v168, 3, v168
	v_add_u32_e32 v168, v168, v167
	v_lshl_add_u32 v169, v168, 4, v169
	s_lshl_b32 s100, s4, 1
	v_add_u32_e32 v169, s100, v169
	v_xor_b32_e32 v167, v166, v167
	v_lshlrev_b32_e32 v167, 4, v167
	v_lshl_add_u32 v168, v166, 7, v167
	v_add_u32_e32 v168, v164, v168
	v_cvt_pk_bf16_f32 v0, v0, v1
	v_cvt_pk_bf16_f32 v1, v2, v3
	ds_write_b64 v170, v[0:1]
	v_cvt_pk_bf16_f32 v4, v4, v5
	v_cvt_pk_bf16_f32 v5, v6, v7
	ds_write_b64 v171, v[4:5]
	v_cvt_pk_bf16_f32 v8, v8, v9
	v_cvt_pk_bf16_f32 v9, v10, v11
	ds_write_b64 v172, v[8:9]
	v_cvt_pk_bf16_f32 v12, v12, v13
	v_cvt_pk_bf16_f32 v13, v14, v15
	ds_write_b64 v173, v[12:13]
	v_cvt_pk_bf16_f32 v16, v16, v17
	v_cvt_pk_bf16_f32 v17, v18, v19
	ds_write_b64 v170, v[16:17] offset:2048
	v_cvt_pk_bf16_f32 v20, v20, v21
	v_cvt_pk_bf16_f32 v21, v22, v23
	ds_write_b64 v171, v[20:21] offset:2048
	v_cvt_pk_bf16_f32 v24, v24, v25
	v_cvt_pk_bf16_f32 v25, v26, v27
	ds_write_b64 v172, v[24:25] offset:2048
	v_cvt_pk_bf16_f32 v28, v28, v29
	v_cvt_pk_bf16_f32 v29, v30, v31
	ds_write_b64 v173, v[28:29] offset:2048
	v_cvt_pk_bf16_f32 v32, v32, v33
	v_cvt_pk_bf16_f32 v33, v34, v35
	ds_write_b64 v170, v[32:33] offset:4096
	v_cvt_pk_bf16_f32 v36, v36, v37
	v_cvt_pk_bf16_f32 v37, v38, v39
	ds_write_b64 v171, v[36:37] offset:4096
	v_cvt_pk_bf16_f32 v40, v40, v41
	v_cvt_pk_bf16_f32 v41, v42, v43
	ds_write_b64 v172, v[40:41] offset:4096
	v_cvt_pk_bf16_f32 v44, v44, v45
	v_cvt_pk_bf16_f32 v45, v46, v47
	ds_write_b64 v173, v[44:45] offset:4096
	v_cvt_pk_bf16_f32 v48, v48, v49
	v_cvt_pk_bf16_f32 v49, v50, v51
	ds_write_b64 v170, v[48:49] offset:6144
	v_cvt_pk_bf16_f32 v52, v52, v53
	v_cvt_pk_bf16_f32 v53, v54, v55
	ds_write_b64 v171, v[52:53] offset:6144
	v_cvt_pk_bf16_f32 v56, v56, v57
	v_cvt_pk_bf16_f32 v57, v58, v59
	ds_write_b64 v172, v[56:57] offset:6144
	v_cvt_pk_bf16_f32 v60, v60, v61
	v_cvt_pk_bf16_f32 v61, v62, v63
	ds_write_b64 v173, v[60:61] offset:6144
	s_waitcnt lgkmcnt(0)
; DEV u16 f2bf(float f) { return (u16)(pack2(f, f) & 0xffffu); }
; DEV float silu_f(float x) { return x / (1.f + __expf(-x)); }
; template <class F>
; DEV void acc_foreach(Acc& acc, int m0, int n0, F f) {
;   asm volatile("s_nop 7\n\ts_nop 7\n\ts_nop 3" ::: "memory");
;   const int tid = tidx_full();
;   const int wave = tid >> 6, lane = tid & 63;
;   const int wm = (wave >> 2) * 128, wn = (wave & 3) * 64;
;   const int lr = lane & 31, lh = lane >> 5;
; #pragma unroll
;   for (int i = 0; i < 4; ++i)
; #pragma unroll
;     for (int j = 0; j < 2; ++j)
; #pragma unroll
;       for (int r = 0; r < 16; ++r) {
;         const int m = m0 + wm + 32 * i + (r & 3) + 8 * (r >> 2) + 4 * lh;
;         const int n = n0 + wn + 32 * j + lr;
;         float v = acc[i][j][r];
;         f(m, n, v);
;         acc[i][j][r] = v;
;       }
; DEV void phase_p1(const Params& p, int g, char* smem) {
;     ...
;         acc_foreach(acc, m0, n0, [&](int m, int n, float& v) {
;           const float o = dosilu ? silu_f(v) : v;
;           PHG[(size_t)m * 2560 + n] = f2bf(o);
;         });
	ds_read_b128 v[32:35], v168
	ds_read_b128 v[36:39], v168 offset:1024
	ds_read_b128 v[40:43], v168 offset:2048
	ds_read_b128 v[44:47], v168 offset:3072
	ds_read_b128 v[48:51], v168 offset:4096
	ds_read_b128 v[52:55], v168 offset:5120
	ds_read_b128 v[56:59], v168 offset:6144
	ds_read_b128 v[60:63], v168 offset:7168
	s_waitcnt lgkmcnt(7)
	global_store_dwordx4 v169, v[32:35], s[56:57]
	v_add_u32_e32 v169, 0xa000, v169
	s_waitcnt lgkmcnt(6)
	global_store_dwordx4 v169, v[36:39], s[56:57]
	v_add_u32_e32 v169, 0xa000, v169
	s_waitcnt lgkmcnt(5)
	global_store_dwordx4 v169, v[40:43], s[56:57]
	v_add_u32_e32 v169, 0xa000, v169
	s_waitcnt lgkmcnt(4)
	global_store_dwordx4 v169, v[44:47], s[56:57]
	v_add_u32_e32 v169, 0xa000, v169
	s_waitcnt lgkmcnt(3)
	global_store_dwordx4 v169, v[48:51], s[56:57]
	v_add_u32_e32 v169, 0xa000, v169
	s_waitcnt lgkmcnt(2)
	global_store_dwordx4 v169, v[52:55], s[56:57]
	v_add_u32_e32 v169, 0xa000, v169
	s_waitcnt lgkmcnt(1)
	global_store_dwordx4 v169, v[56:59], s[56:57]
	v_add_u32_e32 v169, 0xa000, v169
	s_waitcnt lgkmcnt(0)
	global_store_dwordx4 v169, v[60:63], s[56:57]
	v_add_u32_e32 v169, 0xa000, v169
	v_cvt_pk_bf16_f32 v64, v64, v65
	v_cvt_pk_bf16_f32 v65, v66, v67
	ds_write_b64 v170, v[64:65]
	v_cvt_pk_bf16_f32 v68, v68, v69
	v_cvt_pk_bf16_f32 v69, v70, v71
	ds_write_b64 v171, v[68:69]
	v_cvt_pk_bf16_f32 v72, v72, v73
	v_cvt_pk_bf16_f32 v73, v74, v75
	ds_write_b64 v172, v[72:73]
	v_cvt_pk_bf16_f32 v76, v76, v77
	v_cvt_pk_bf16_f32 v77, v78, v79
	ds_write_b64 v173, v[76:77]
	v_cvt_pk_bf16_f32 v80, v80, v81
	v_cvt_pk_bf16_f32 v81, v82, v83
	ds_write_b64 v170, v[80:81] offset:2048
	v_cvt_pk_bf16_f32 v84, v84, v85
	v_cvt_pk_bf16_f32 v85, v86, v87
	ds_write_b64 v171, v[84:85] offset:2048
	v_cvt_pk_bf16_f32 v88, v88, v89
	v_cvt_pk_bf16_f32 v89, v90, v91
	ds_write_b64 v172, v[88:89] offset:2048
	v_cvt_pk_bf16_f32 v92, v92, v93
	v_cvt_pk_bf16_f32 v93, v94, v95
	ds_write_b64 v173, v[92:93] offset:2048
	v_cvt_pk_bf16_f32 v96, v96, v97
	v_cvt_pk_bf16_f32 v97, v98, v99
	ds_write_b64 v170, v[96:97] offset:4096
	v_cvt_pk_bf16_f32 v100, v100, v101
	v_cvt_pk_bf16_f32 v101, v102, v103
	ds_write_b64 v171, v[100:101] offset:4096
	v_cvt_pk_bf16_f32 v104, v104, v105
	v_cvt_pk_bf16_f32 v105, v106, v107
	ds_write_b64 v172, v[104:105] offset:4096
	v_cvt_pk_bf16_f32 v108, v108, v109
	v_cvt_pk_bf16_f32 v109, v110, v111
	ds_write_b64 v173, v[108:109] offset:4096
	v_cvt_pk_bf16_f32 v112, v112, v113
	v_cvt_pk_bf16_f32 v113, v114, v115
	ds_write_b64 v170, v[112:113] offset:6144
	v_cvt_pk_bf16_f32 v116, v116, v117
	v_cvt_pk_bf16_f32 v117, v118, v119
	ds_write_b64 v171, v[116:117] offset:6144
	v_cvt_pk_bf16_f32 v120, v120, v121
	v_cvt_pk_bf16_f32 v121, v122, v123
	ds_write_b64 v172, v[120:121] offset:6144
	v_cvt_pk_bf16_f32 v124, v124, v125
	v_cvt_pk_bf16_f32 v125, v126, v127
	ds_write_b64 v173, v[124:125] offset:6144
	s_waitcnt lgkmcnt(0)
	ds_read_b128 v[64:67], v168
	ds_read_b128 v[68:71], v168 offset:1024
	ds_read_b128 v[72:75], v168 offset:2048
	ds_read_b128 v[76:79], v168 offset:3072
	ds_read_b128 v[80:83], v168 offset:4096
	ds_read_b128 v[84:87], v168 offset:5120
	ds_read_b128 v[88:91], v168 offset:6144
	ds_read_b128 v[92:95], v168 offset:7168
	s_waitcnt lgkmcnt(7)
	global_store_dwordx4 v169, v[64:67], s[56:57]
	v_add_u32_e32 v169, 0xa000, v169
	s_waitcnt lgkmcnt(6)
	global_store_dwordx4 v169, v[68:71], s[56:57]
	v_add_u32_e32 v169, 0xa000, v169
	s_waitcnt lgkmcnt(5)
	global_store_dwordx4 v169, v[72:75], s[56:57]
	v_add_u32_e32 v169, 0xa000, v169
	s_waitcnt lgkmcnt(4)
	global_store_dwordx4 v169, v[76:79], s[56:57]
	v_add_u32_e32 v169, 0xa000, v169
	s_waitcnt lgkmcnt(3)
	global_store_dwordx4 v169, v[80:83], s[56:57]
	v_add_u32_e32 v169, 0xa000, v169
	s_waitcnt lgkmcnt(2)
	global_store_dwordx4 v169, v[84:87], s[56:57]
	v_add_u32_e32 v169, 0xa000, v169
	s_waitcnt lgkmcnt(1)
	global_store_dwordx4 v169, v[88:91], s[56:57]
	v_add_u32_e32 v169, 0xa000, v169
	s_waitcnt lgkmcnt(0)
	s_barrier
	global_store_dwordx4 v169, v[92:95], s[56:57]
	v_add_u32_e32 v169, 0xa000, v169
	s_branch .LBB0_261
.Lp1a_silu:
	s_nop 7
	s_nop 7
	s_nop 3
	v_and_b32_e32 v160, 63, v202
	v_lshrrev_b32_e32 v161, 6, v202
	v_and_b32_e32 v164, 3, v161
	v_lshlrev_b32_e32 v164, 13, v164
	v_add_u32_e32 v164, 0x8000, v164
	v_lshrrev_b32_e32 v160, 2, v161
	v_lshl_add_u32 v164, v160, 16, v164
	v_and_b32_e32 v160, 63, v202
	v_and_b32_e32 v166, 15, v160
	v_lshrrev_b32_e32 v167, 4, v160
	v_lshl_add_u32 v168, v166, 7, v164
	v_and_b32_e32 v169, 1, v167
	v_lshl_add_u32 v168, v169, 3, v168
	v_lshrrev_b32_e32 v167, 1, v167
	v_and_b32_e32 v166, 7, v166
	v_xor_b32_e32 v166, v166, v167
	v_lshlrev_b32_e32 v166, 4, v166
	v_add_u32_e32 v170, v168, v166
	v_xor_b32_e32 v167, 0x20, v166
	v_add_u32_e32 v171, v168, v167
	v_xor_b32_e32 v167, 0x40, v166
	v_add_u32_e32 v172, v168, v167
	v_xor_b32_e32 v167, 0x60, v166
	v_add_u32_e32 v173, v168, v167
	v_and_b32_e32 v166, 31, v160
	v_lshrrev_b32_e32 v167, 5, v160
	v_lshlrev_b32_e32 v168, 7, v166
	v_lshl_add_u32 v168, v167, 3, v168
	v_add_u32_e32 v168, v164, v168
	v_and_b32_e32 v166, 7, v166
	v_lshlrev_b32_e32 v166, 4, v166
	v_lshrrev_b32_e32 v166, 3, v160
	v_and_b32_e32 v167, 7, v160
	v_lshrrev_b32_e32 v169, 2, v161
	v_lshl_add_u32 v169, v169, 7, v166
	v_add_u32_e32 v169, s5, v169
	v_mul_u32_u24_e32 v169, 0x1400, v169
	v_and_b32_e32 v168, 3, v161
	v_lshlrev_b32_e32 v168, 3, v168
	v_add_u32_e32 v168, v168, v167
	v_lshl_add_u32 v169, v168, 4, v169
	s_lshl_b32 s100, s4, 1
	v_add_u32_e32 v169, s100, v169
	v_xor_b32_e32 v167, v166, v167
	v_lshlrev_b32_e32 v167, 4, v167
	v_lshl_add_u32 v168, v166, 7, v167
	v_add_u32_e32 v168, v164, v168
	v_mul_f32_e32 v178, 0xbfb8aa3b, v0
; DEV u16 f2bf(float f) { return (u16)(pack2(f, f) & 0xffffu); }
; DEV float silu_f(float x) { return x / (1.f + __expf(-x)); }
; DEV void phase_p1(const Params& p, int g, char* smem) {
;     ...
;         acc_foreach(acc, m0, n0, [&](int m, int n, float& v) {
;           const float o = dosilu ? silu_f(v) : v;
;           PHG[(size_t)m * 2560 + n] = f2bf(o);
;         });
	v_mul_f32_e32 v179, 0xbfb8aa3b, v1
	v_mul_f32_e32 v180, 0xbfb8aa3b, v2
	v_mul_f32_e32 v181, 0xbfb8aa3b, v3
	v_exp_f32_e32 v178, v178
	v_exp_f32_e32 v179, v179
	v_exp_f32_e32 v180, v180
	v_exp_f32_e32 v181, v181
	v_add_f32_e32 v178, 1.0, v178
	v_add_f32_e32 v179, 1.0, v179
	v_add_f32_e32 v180, 1.0, v180
	v_add_f32_e32 v181, 1.0, v181
	v_rcp_f32_e32 v178, v178
	v_rcp_f32_e32 v179, v179
	v_rcp_f32_e32 v180, v180
	v_rcp_f32_e32 v181, v181
	v_mul_f32_e32 v0, v0, v178
	v_mul_f32_e32 v1, v1, v179
	v_mul_f32_e32 v2, v2, v180
	v_mul_f32_e32 v3, v3, v181
	v_cvt_pk_bf16_f32 v0, v0, v1
	v_cvt_pk_bf16_f32 v1, v2, v3
	ds_write_b64 v170, v[0:1]
	v_mul_f32_e32 v178, 0xbfb8aa3b, v4
	v_mul_f32_e32 v179, 0xbfb8aa3b, v5
	v_mul_f32_e32 v180, 0xbfb8aa3b, v6
	v_mul_f32_e32 v181, 0xbfb8aa3b, v7
	v_exp_f32_e32 v178, v178
	v_exp_f32_e32 v179, v179
	v_exp_f32_e32 v180, v180
	v_exp_f32_e32 v181, v181
	v_add_f32_e32 v178, 1.0, v178
	v_add_f32_e32 v179, 1.0, v179
	v_add_f32_e32 v180, 1.0, v180
	v_add_f32_e32 v181, 1.0, v181
	v_rcp_f32_e32 v178, v178
	v_rcp_f32_e32 v179, v179
	v_rcp_f32_e32 v180, v180
	v_rcp_f32_e32 v181, v181
	v_mul_f32_e32 v4, v4, v178
	v_mul_f32_e32 v5, v5, v179
	v_mul_f32_e32 v6, v6, v180
	v_mul_f32_e32 v7, v7, v181
	v_cvt_pk_bf16_f32 v4, v4, v5
	v_cvt_pk_bf16_f32 v5, v6, v7
	ds_write_b64 v171, v[4:5]
	v_mul_f32_e32 v178, 0xbfb8aa3b, v8
	v_mul_f32_e32 v179, 0xbfb8aa3b, v9
	v_mul_f32_e32 v180, 0xbfb8aa3b, v10
	v_mul_f32_e32 v181, 0xbfb8aa3b, v11
	v_exp_f32_e32 v178, v178
	v_exp_f32_e32 v179, v179
	v_exp_f32_e32 v180, v180
	v_exp_f32_e32 v181, v181
	v_add_f32_e32 v178, 1.0, v178
	v_add_f32_e32 v179, 1.0, v179
	v_add_f32_e32 v180, 1.0, v180
	v_add_f32_e32 v181, 1.0, v181
	v_rcp_f32_e32 v178, v178
	v_rcp_f32_e32 v179, v179
	v_rcp_f32_e32 v180, v180
	v_rcp_f32_e32 v181, v181
	v_mul_f32_e32 v8, v8, v178
	v_mul_f32_e32 v9, v9, v179
	v_mul_f32_e32 v10, v10, v180
	v_mul_f32_e32 v11, v11, v181
	v_cvt_pk_bf16_f32 v8, v8, v9
	v_cvt_pk_bf16_f32 v9, v10, v11
	ds_write_b64 v172, v[8:9]
	v_mul_f32_e32 v178, 0xbfb8aa3b, v12
	v_mul_f32_e32 v179, 0xbfb8aa3b, v13
	v_mul_f32_e32 v180, 0xbfb8aa3b, v14
	v_mul_f32_e32 v181, 0xbfb8aa3b, v15
	v_exp_f32_e32 v178, v178
	v_exp_f32_e32 v179, v179
	v_exp_f32_e32 v180, v180
	v_exp_f32_e32 v181, v181
	v_add_f32_e32 v178, 1.0, v178
	v_add_f32_e32 v179, 1.0, v179
	v_add_f32_e32 v180, 1.0, v180
	v_add_f32_e32 v181, 1.0, v181
	v_rcp_f32_e32 v178, v178
	v_rcp_f32_e32 v179, v179
	v_rcp_f32_e32 v180, v180
	v_rcp_f32_e32 v181, v181
	v_mul_f32_e32 v12, v12, v178
	v_mul_f32_e32 v13, v13, v179
	v_mul_f32_e32 v14, v14, v180
	v_mul_f32_e32 v15, v15, v181
	v_cvt_pk_bf16_f32 v12, v12, v13
	v_cvt_pk_bf16_f32 v13, v14, v15
	ds_write_b64 v173, v[12:13]
	v_mul_f32_e32 v178, 0xbfb8aa3b, v16
	v_mul_f32_e32 v179, 0xbfb8aa3b, v17
	v_mul_f32_e32 v180, 0xbfb8aa3b, v18
	v_mul_f32_e32 v181, 0xbfb8aa3b, v19
	v_exp_f32_e32 v178, v178
	v_exp_f32_e32 v179, v179
	v_exp_f32_e32 v180, v180
	v_exp_f32_e32 v181, v181
	v_add_f32_e32 v178, 1.0, v178
	v_add_f32_e32 v179, 1.0, v179
	v_add_f32_e32 v180, 1.0, v180
	v_add_f32_e32 v181, 1.0, v181
	v_rcp_f32_e32 v178, v178
	v_rcp_f32_e32 v179, v179
	v_rcp_f32_e32 v180, v180
	v_rcp_f32_e32 v181, v181
	v_mul_f32_e32 v16, v16, v178
	v_mul_f32_e32 v17, v17, v179
	v_mul_f32_e32 v18, v18, v180
	v_mul_f32_e32 v19, v19, v181
	v_cvt_pk_bf16_f32 v16, v16, v17
	v_cvt_pk_bf16_f32 v17, v18, v19
	ds_write_b64 v170, v[16:17] offset:2048
	v_mul_f32_e32 v178, 0xbfb8aa3b, v20
	v_mul_f32_e32 v179, 0xbfb8aa3b, v21
	v_mul_f32_e32 v180, 0xbfb8aa3b, v22
	v_mul_f32_e32 v181, 0xbfb8aa3b, v23
	v_exp_f32_e32 v178, v178
	v_exp_f32_e32 v179, v179
	v_exp_f32_e32 v180, v180
	v_exp_f32_e32 v181, v181
	v_add_f32_e32 v178, 1.0, v178
	v_add_f32_e32 v179, 1.0, v179
	v_add_f32_e32 v180, 1.0, v180
	v_add_f32_e32 v181, 1.0, v181
	v_rcp_f32_e32 v178, v178
	v_rcp_f32_e32 v179, v179
	v_rcp_f32_e32 v180, v180
	v_rcp_f32_e32 v181, v181
	v_mul_f32_e32 v20, v20, v178
	v_mul_f32_e32 v21, v21, v179
	v_mul_f32_e32 v22, v22, v180
	v_mul_f32_e32 v23, v23, v181
	v_cvt_pk_bf16_f32 v20, v20, v21
	v_cvt_pk_bf16_f32 v21, v22, v23
	ds_write_b64 v171, v[20:21] offset:2048
	v_mul_f32_e32 v178, 0xbfb8aa3b, v24
	v_mul_f32_e32 v179, 0xbfb8aa3b, v25
	v_mul_f32_e32 v180, 0xbfb8aa3b, v26
	v_mul_f32_e32 v181, 0xbfb8aa3b, v27
	v_exp_f32_e32 v178, v178
	v_exp_f32_e32 v179, v179
	v_exp_f32_e32 v180, v180
	v_exp_f32_e32 v181, v181
	v_add_f32_e32 v178, 1.0, v178
	v_add_f32_e32 v179, 1.0, v179
	v_add_f32_e32 v180, 1.0, v180
	v_add_f32_e32 v181, 1.0, v181
	v_rcp_f32_e32 v178, v178
	v_rcp_f32_e32 v179, v179
	v_rcp_f32_e32 v180, v180
	v_rcp_f32_e32 v181, v181
	v_mul_f32_e32 v24, v24, v178
	v_mul_f32_e32 v25, v25, v179
	v_mul_f32_e32 v26, v26, v180
	v_mul_f32_e32 v27, v27, v181
	v_cvt_pk_bf16_f32 v24, v24, v25
	v_cvt_pk_bf16_f32 v25, v26, v27
	ds_write_b64 v172, v[24:25] offset:2048
	v_mul_f32_e32 v178, 0xbfb8aa3b, v28
	v_mul_f32_e32 v179, 0xbfb8aa3b, v29
	v_mul_f32_e32 v180, 0xbfb8aa3b, v30
	v_mul_f32_e32 v181, 0xbfb8aa3b, v31
	v_exp_f32_e32 v178, v178
	v_exp_f32_e32 v179, v179
	v_exp_f32_e32 v180, v180
	v_exp_f32_e32 v181, v181
	v_add_f32_e32 v178, 1.0, v178
	v_add_f32_e32 v179, 1.0, v179
	v_add_f32_e32 v180, 1.0, v180
	v_add_f32_e32 v181, 1.0, v181
	v_rcp_f32_e32 v178, v178
	v_rcp_f32_e32 v179, v179
	v_rcp_f32_e32 v180, v180
	v_rcp_f32_e32 v181, v181
	v_mul_f32_e32 v28, v28, v178
	v_mul_f32_e32 v29, v29, v179
	v_mul_f32_e32 v30, v30, v180
	v_mul_f32_e32 v31, v31, v181
	v_cvt_pk_bf16_f32 v28, v28, v29
	v_cvt_pk_bf16_f32 v29, v30, v31
	ds_write_b64 v173, v[28:29] offset:2048
	v_mul_f32_e32 v178, 0xbfb8aa3b, v32
	v_mul_f32_e32 v179, 0xbfb8aa3b, v33
	v_mul_f32_e32 v180, 0xbfb8aa3b, v34
; DEV u16 f2bf(float f) { return (u16)(pack2(f, f) & 0xffffu); }
; DEV float silu_f(float x) { return x / (1.f + __expf(-x)); }
; DEV void phase_p1(const Params& p, int g, char* smem) {
;     ...
;         acc_foreach(acc, m0, n0, [&](int m, int n, float& v) {
;           const float o = dosilu ? silu_f(v) : v;
;           PHG[(size_t)m * 2560 + n] = f2bf(o);
;         });
	v_mul_f32_e32 v181, 0xbfb8aa3b, v35
	v_exp_f32_e32 v178, v178
	v_exp_f32_e32 v179, v179
	v_exp_f32_e32 v180, v180
	v_exp_f32_e32 v181, v181
	v_add_f32_e32 v178, 1.0, v178
	v_add_f32_e32 v179, 1.0, v179
	v_add_f32_e32 v180, 1.0, v180
	v_add_f32_e32 v181, 1.0, v181
	v_rcp_f32_e32 v178, v178
	v_rcp_f32_e32 v179, v179
	v_rcp_f32_e32 v180, v180
	v_rcp_f32_e32 v181, v181
	v_mul_f32_e32 v32, v32, v178
	v_mul_f32_e32 v33, v33, v179
	v_mul_f32_e32 v34, v34, v180
	v_mul_f32_e32 v35, v35, v181
	v_cvt_pk_bf16_f32 v32, v32, v33
	v_cvt_pk_bf16_f32 v33, v34, v35
	ds_write_b64 v170, v[32:33] offset:4096
	v_mul_f32_e32 v178, 0xbfb8aa3b, v36
	v_mul_f32_e32 v179, 0xbfb8aa3b, v37
	v_mul_f32_e32 v180, 0xbfb8aa3b, v38
	v_mul_f32_e32 v181, 0xbfb8aa3b, v39
	v_exp_f32_e32 v178, v178
	v_exp_f32_e32 v179, v179
	v_exp_f32_e32 v180, v180
	v_exp_f32_e32 v181, v181
	v_add_f32_e32 v178, 1.0, v178
	v_add_f32_e32 v179, 1.0, v179
	v_add_f32_e32 v180, 1.0, v180
	v_add_f32_e32 v181, 1.0, v181
	v_rcp_f32_e32 v178, v178
	v_rcp_f32_e32 v179, v179
	v_rcp_f32_e32 v180, v180
	v_rcp_f32_e32 v181, v181
	v_mul_f32_e32 v36, v36, v178
	v_mul_f32_e32 v37, v37, v179
	v_mul_f32_e32 v38, v38, v180
	v_mul_f32_e32 v39, v39, v181
	v_cvt_pk_bf16_f32 v36, v36, v37
	v_cvt_pk_bf16_f32 v37, v38, v39
	ds_write_b64 v171, v[36:37] offset:4096
	v_mul_f32_e32 v178, 0xbfb8aa3b, v40
	v_mul_f32_e32 v179, 0xbfb8aa3b, v41
	v_mul_f32_e32 v180, 0xbfb8aa3b, v42
	v_mul_f32_e32 v181, 0xbfb8aa3b, v43
	v_exp_f32_e32 v178, v178
	v_exp_f32_e32 v179, v179
	v_exp_f32_e32 v180, v180
	v_exp_f32_e32 v181, v181
	v_add_f32_e32 v178, 1.0, v178
	v_add_f32_e32 v179, 1.0, v179
	v_add_f32_e32 v180, 1.0, v180
	v_add_f32_e32 v181, 1.0, v181
	v_rcp_f32_e32 v178, v178
	v_rcp_f32_e32 v179, v179
	v_rcp_f32_e32 v180, v180
	v_rcp_f32_e32 v181, v181
	v_mul_f32_e32 v40, v40, v178
	v_mul_f32_e32 v41, v41, v179
	v_mul_f32_e32 v42, v42, v180
	v_mul_f32_e32 v43, v43, v181
	v_cvt_pk_bf16_f32 v40, v40, v41
	v_cvt_pk_bf16_f32 v41, v42, v43
	ds_write_b64 v172, v[40:41] offset:4096
	v_mul_f32_e32 v178, 0xbfb8aa3b, v44
	v_mul_f32_e32 v179, 0xbfb8aa3b, v45
	v_mul_f32_e32 v180, 0xbfb8aa3b, v46
	v_mul_f32_e32 v181, 0xbfb8aa3b, v47
	v_exp_f32_e32 v178, v178
	v_exp_f32_e32 v179, v179
	v_exp_f32_e32 v180, v180
	v_exp_f32_e32 v181, v181
	v_add_f32_e32 v178, 1.0, v178
	v_add_f32_e32 v179, 1.0, v179
	v_add_f32_e32 v180, 1.0, v180
	v_add_f32_e32 v181, 1.0, v181
	v_rcp_f32_e32 v178, v178
	v_rcp_f32_e32 v179, v179
	v_rcp_f32_e32 v180, v180
	v_rcp_f32_e32 v181, v181
	v_mul_f32_e32 v44, v44, v178
	v_mul_f32_e32 v45, v45, v179
	v_mul_f32_e32 v46, v46, v180
	v_mul_f32_e32 v47, v47, v181
	v_cvt_pk_bf16_f32 v44, v44, v45
	v_cvt_pk_bf16_f32 v45, v46, v47
	ds_write_b64 v173, v[44:45] offset:4096
	v_mul_f32_e32 v178, 0xbfb8aa3b, v48
	v_mul_f32_e32 v179, 0xbfb8aa3b, v49
	v_mul_f32_e32 v180, 0xbfb8aa3b, v50
	v_mul_f32_e32 v181, 0xbfb8aa3b, v51
	v_exp_f32_e32 v178, v178
	v_exp_f32_e32 v179, v179
	v_exp_f32_e32 v180, v180
	v_exp_f32_e32 v181, v181
	v_add_f32_e32 v178, 1.0, v178
	v_add_f32_e32 v179, 1.0, v179
	v_add_f32_e32 v180, 1.0, v180
	v_add_f32_e32 v181, 1.0, v181
	v_rcp_f32_e32 v178, v178
	v_rcp_f32_e32 v179, v179
	v_rcp_f32_e32 v180, v180
	v_rcp_f32_e32 v181, v181
	v_mul_f32_e32 v48, v48, v178
	v_mul_f32_e32 v49, v49, v179
	v_mul_f32_e32 v50, v50, v180
	v_mul_f32_e32 v51, v51, v181
	v_cvt_pk_bf16_f32 v48, v48, v49
	v_cvt_pk_bf16_f32 v49, v50, v51
	ds_write_b64 v170, v[48:49] offset:6144
	v_mul_f32_e32 v178, 0xbfb8aa3b, v52
	v_mul_f32_e32 v179, 0xbfb8aa3b, v53
	v_mul_f32_e32 v180, 0xbfb8aa3b, v54
	v_mul_f32_e32 v181, 0xbfb8aa3b, v55
	v_exp_f32_e32 v178, v178
	v_exp_f32_e32 v179, v179
	v_exp_f32_e32 v180, v180
	v_exp_f32_e32 v181, v181
	v_add_f32_e32 v178, 1.0, v178
	v_add_f32_e32 v179, 1.0, v179
	v_add_f32_e32 v180, 1.0, v180
	v_add_f32_e32 v181, 1.0, v181
	v_rcp_f32_e32 v178, v178
	v_rcp_f32_e32 v179, v179
	v_rcp_f32_e32 v180, v180
	v_rcp_f32_e32 v181, v181
	v_mul_f32_e32 v52, v52, v178
	v_mul_f32_e32 v53, v53, v179
	v_mul_f32_e32 v54, v54, v180
	v_mul_f32_e32 v55, v55, v181
	v_cvt_pk_bf16_f32 v52, v52, v53
	v_cvt_pk_bf16_f32 v53, v54, v55
	ds_write_b64 v171, v[52:53] offset:6144
	v_mul_f32_e32 v178, 0xbfb8aa3b, v56
	v_mul_f32_e32 v179, 0xbfb8aa3b, v57
	v_mul_f32_e32 v180, 0xbfb8aa3b, v58
	v_mul_f32_e32 v181, 0xbfb8aa3b, v59
	v_exp_f32_e32 v178, v178
	v_exp_f32_e32 v179, v179
	v_exp_f32_e32 v180, v180
	v_exp_f32_e32 v181, v181
	v_add_f32_e32 v178, 1.0, v178
	v_add_f32_e32 v179, 1.0, v179
	v_add_f32_e32 v180, 1.0, v180
	v_add_f32_e32 v181, 1.0, v181
	v_rcp_f32_e32 v178, v178
	v_rcp_f32_e32 v179, v179
	v_rcp_f32_e32 v180, v180
	v_rcp_f32_e32 v181, v181
	v_mul_f32_e32 v56, v56, v178
	v_mul_f32_e32 v57, v57, v179
	v_mul_f32_e32 v58, v58, v180
	v_mul_f32_e32 v59, v59, v181
	v_cvt_pk_bf16_f32 v56, v56, v57
	v_cvt_pk_bf16_f32 v57, v58, v59
	ds_write_b64 v172, v[56:57] offset:6144
	v_mul_f32_e32 v178, 0xbfb8aa3b, v60
	v_mul_f32_e32 v179, 0xbfb8aa3b, v61
	v_mul_f32_e32 v180, 0xbfb8aa3b, v62
	v_mul_f32_e32 v181, 0xbfb8aa3b, v63
	v_exp_f32_e32 v178, v178
	v_exp_f32_e32 v179, v179
	v_exp_f32_e32 v180, v180
	v_exp_f32_e32 v181, v181
	v_add_f32_e32 v178, 1.0, v178
	v_add_f32_e32 v179, 1.0, v179
	v_add_f32_e32 v180, 1.0, v180
	v_add_f32_e32 v181, 1.0, v181
	v_rcp_f32_e32 v178, v178
	v_rcp_f32_e32 v179, v179
	v_rcp_f32_e32 v180, v180
	v_rcp_f32_e32 v181, v181
	v_mul_f32_e32 v60, v60, v178
	v_mul_f32_e32 v61, v61, v179
	v_mul_f32_e32 v62, v62, v180
	v_mul_f32_e32 v63, v63, v181
	v_cvt_pk_bf16_f32 v60, v60, v61
	v_cvt_pk_bf16_f32 v61, v62, v63
	ds_write_b64 v173, v[60:61] offset:6144
	s_waitcnt lgkmcnt(0)
; DEV u16 f2bf(float f) { return (u16)(pack2(f, f) & 0xffffu); }
; DEV float silu_f(float x) { return x / (1.f + __expf(-x)); }
; DEV void phase_p1(const Params& p, int g, char* smem) {
;     ...
;         acc_foreach(acc, m0, n0, [&](int m, int n, float& v) {
;           const float o = dosilu ? silu_f(v) : v;
;           PHG[(size_t)m * 2560 + n] = f2bf(o);
;         });
	ds_read_b128 v[32:35], v168
	ds_read_b128 v[36:39], v168 offset:1024
	ds_read_b128 v[40:43], v168 offset:2048
	ds_read_b128 v[44:47], v168 offset:3072
	ds_read_b128 v[48:51], v168 offset:4096
	ds_read_b128 v[52:55], v168 offset:5120
	ds_read_b128 v[56:59], v168 offset:6144
	ds_read_b128 v[60:63], v168 offset:7168
	s_waitcnt lgkmcnt(7)
	global_store_dwordx4 v169, v[32:35], s[56:57]
	v_add_u32_e32 v169, 0xa000, v169
	s_waitcnt lgkmcnt(6)
	global_store_dwordx4 v169, v[36:39], s[56:57]
	v_add_u32_e32 v169, 0xa000, v169
	s_waitcnt lgkmcnt(5)
	global_store_dwordx4 v169, v[40:43], s[56:57]
	v_add_u32_e32 v169, 0xa000, v169
	s_waitcnt lgkmcnt(4)
	global_store_dwordx4 v169, v[44:47], s[56:57]
	v_add_u32_e32 v169, 0xa000, v169
	s_waitcnt lgkmcnt(3)
	global_store_dwordx4 v169, v[48:51], s[56:57]
	v_add_u32_e32 v169, 0xa000, v169
	s_waitcnt lgkmcnt(2)
	global_store_dwordx4 v169, v[52:55], s[56:57]
	v_add_u32_e32 v169, 0xa000, v169
	s_waitcnt lgkmcnt(1)
	global_store_dwordx4 v169, v[56:59], s[56:57]
	v_add_u32_e32 v169, 0xa000, v169
	s_waitcnt lgkmcnt(0)
	global_store_dwordx4 v169, v[60:63], s[56:57]
	v_add_u32_e32 v169, 0xa000, v169
	v_mul_f32_e32 v178, 0xbfb8aa3b, v64
	v_mul_f32_e32 v179, 0xbfb8aa3b, v65
	v_mul_f32_e32 v180, 0xbfb8aa3b, v66
	v_mul_f32_e32 v181, 0xbfb8aa3b, v67
	v_exp_f32_e32 v178, v178
	v_exp_f32_e32 v179, v179
	v_exp_f32_e32 v180, v180
	v_exp_f32_e32 v181, v181
	v_add_f32_e32 v178, 1.0, v178
	v_add_f32_e32 v179, 1.0, v179
	v_add_f32_e32 v180, 1.0, v180
	v_add_f32_e32 v181, 1.0, v181
	v_rcp_f32_e32 v178, v178
	v_rcp_f32_e32 v179, v179
	v_rcp_f32_e32 v180, v180
	v_rcp_f32_e32 v181, v181
	v_mul_f32_e32 v64, v64, v178
	v_mul_f32_e32 v65, v65, v179
	v_mul_f32_e32 v66, v66, v180
	v_mul_f32_e32 v67, v67, v181
	v_cvt_pk_bf16_f32 v64, v64, v65
	v_cvt_pk_bf16_f32 v65, v66, v67
	ds_write_b64 v170, v[64:65]
	v_mul_f32_e32 v178, 0xbfb8aa3b, v68
	v_mul_f32_e32 v179, 0xbfb8aa3b, v69
	v_mul_f32_e32 v180, 0xbfb8aa3b, v70
	v_mul_f32_e32 v181, 0xbfb8aa3b, v71
	v_exp_f32_e32 v178, v178
	v_exp_f32_e32 v179, v179
	v_exp_f32_e32 v180, v180
	v_exp_f32_e32 v181, v181
	v_add_f32_e32 v178, 1.0, v178
	v_add_f32_e32 v179, 1.0, v179
	v_add_f32_e32 v180, 1.0, v180
	v_add_f32_e32 v181, 1.0, v181
	v_rcp_f32_e32 v178, v178
	v_rcp_f32_e32 v179, v179
	v_rcp_f32_e32 v180, v180
	v_rcp_f32_e32 v181, v181
	v_mul_f32_e32 v68, v68, v178
	v_mul_f32_e32 v69, v69, v179
	v_mul_f32_e32 v70, v70, v180
	v_mul_f32_e32 v71, v71, v181
	v_cvt_pk_bf16_f32 v68, v68, v69
	v_cvt_pk_bf16_f32 v69, v70, v71
	ds_write_b64 v171, v[68:69]
	v_mul_f32_e32 v178, 0xbfb8aa3b, v72
	v_mul_f32_e32 v179, 0xbfb8aa3b, v73
	v_mul_f32_e32 v180, 0xbfb8aa3b, v74
	v_mul_f32_e32 v181, 0xbfb8aa3b, v75
	v_exp_f32_e32 v178, v178
	v_exp_f32_e32 v179, v179
	v_exp_f32_e32 v180, v180
	v_exp_f32_e32 v181, v181
	v_add_f32_e32 v178, 1.0, v178
	v_add_f32_e32 v179, 1.0, v179
	v_add_f32_e32 v180, 1.0, v180
	v_add_f32_e32 v181, 1.0, v181
	v_rcp_f32_e32 v178, v178
	v_rcp_f32_e32 v179, v179
	v_rcp_f32_e32 v180, v180
	v_rcp_f32_e32 v181, v181
	v_mul_f32_e32 v72, v72, v178
	v_mul_f32_e32 v73, v73, v179
	v_mul_f32_e32 v74, v74, v180
	v_mul_f32_e32 v75, v75, v181
	v_cvt_pk_bf16_f32 v72, v72, v73
	v_cvt_pk_bf16_f32 v73, v74, v75
	ds_write_b64 v172, v[72:73]
	v_mul_f32_e32 v178, 0xbfb8aa3b, v76
	v_mul_f32_e32 v179, 0xbfb8aa3b, v77
	v_mul_f32_e32 v180, 0xbfb8aa3b, v78
	v_mul_f32_e32 v181, 0xbfb8aa3b, v79
	v_exp_f32_e32 v178, v178
	v_exp_f32_e32 v179, v179
	v_exp_f32_e32 v180, v180
	v_exp_f32_e32 v181, v181
	v_add_f32_e32 v178, 1.0, v178
	v_add_f32_e32 v179, 1.0, v179
	v_add_f32_e32 v180, 1.0, v180
	v_add_f32_e32 v181, 1.0, v181
	v_rcp_f32_e32 v178, v178
	v_rcp_f32_e32 v179, v179
	v_rcp_f32_e32 v180, v180
	v_rcp_f32_e32 v181, v181
	v_mul_f32_e32 v76, v76, v178
	v_mul_f32_e32 v77, v77, v179
	v_mul_f32_e32 v78, v78, v180
	v_mul_f32_e32 v79, v79, v181
	v_cvt_pk_bf16_f32 v76, v76, v77
	v_cvt_pk_bf16_f32 v77, v78, v79
	ds_write_b64 v173, v[76:77]
	v_mul_f32_e32 v178, 0xbfb8aa3b, v80
	v_mul_f32_e32 v179, 0xbfb8aa3b, v81
	v_mul_f32_e32 v180, 0xbfb8aa3b, v82
	v_mul_f32_e32 v181, 0xbfb8aa3b, v83
	v_exp_f32_e32 v178, v178
	v_exp_f32_e32 v179, v179
	v_exp_f32_e32 v180, v180
	v_exp_f32_e32 v181, v181
	v_add_f32_e32 v178, 1.0, v178
	v_add_f32_e32 v179, 1.0, v179
	v_add_f32_e32 v180, 1.0, v180
	v_add_f32_e32 v181, 1.0, v181
	v_rcp_f32_e32 v178, v178
	v_rcp_f32_e32 v179, v179
	v_rcp_f32_e32 v180, v180
	v_rcp_f32_e32 v181, v181
	v_mul_f32_e32 v80, v80, v178
	v_mul_f32_e32 v81, v81, v179
	v_mul_f32_e32 v82, v82, v180
	v_mul_f32_e32 v83, v83, v181
	v_cvt_pk_bf16_f32 v80, v80, v81
	v_cvt_pk_bf16_f32 v81, v82, v83
	ds_write_b64 v170, v[80:81] offset:2048
	v_mul_f32_e32 v178, 0xbfb8aa3b, v84
	v_mul_f32_e32 v179, 0xbfb8aa3b, v85
	v_mul_f32_e32 v180, 0xbfb8aa3b, v86
	v_mul_f32_e32 v181, 0xbfb8aa3b, v87
	v_exp_f32_e32 v178, v178
	v_exp_f32_e32 v179, v179
	v_exp_f32_e32 v180, v180
	v_exp_f32_e32 v181, v181
	v_add_f32_e32 v178, 1.0, v178
	v_add_f32_e32 v179, 1.0, v179
	v_add_f32_e32 v180, 1.0, v180
	v_add_f32_e32 v181, 1.0, v181
	v_rcp_f32_e32 v178, v178
	v_rcp_f32_e32 v179, v179
	v_rcp_f32_e32 v180, v180
	v_rcp_f32_e32 v181, v181
	v_mul_f32_e32 v84, v84, v178
	v_mul_f32_e32 v85, v85, v179
	v_mul_f32_e32 v86, v86, v180
	v_mul_f32_e32 v87, v87, v181
	v_cvt_pk_bf16_f32 v84, v84, v85
	v_cvt_pk_bf16_f32 v85, v86, v87
	ds_write_b64 v171, v[84:85] offset:2048
	v_mul_f32_e32 v178, 0xbfb8aa3b, v88
	v_mul_f32_e32 v179, 0xbfb8aa3b, v89
	v_mul_f32_e32 v180, 0xbfb8aa3b, v90
	v_mul_f32_e32 v181, 0xbfb8aa3b, v91
	v_exp_f32_e32 v178, v178
	v_exp_f32_e32 v179, v179
	v_exp_f32_e32 v180, v180
	v_exp_f32_e32 v181, v181
	v_add_f32_e32 v178, 1.0, v178
	v_add_f32_e32 v179, 1.0, v179
; DEV u16 f2bf(float f) { return (u16)(pack2(f, f) & 0xffffu); }
; DEV float silu_f(float x) { return x / (1.f + __expf(-x)); }
; DEV void phase_p1(const Params& p, int g, char* smem) {
;     ...
;         acc_foreach(acc, m0, n0, [&](int m, int n, float& v) {
;           const float o = dosilu ? silu_f(v) : v;
;           PHG[(size_t)m * 2560 + n] = f2bf(o);
;         });
	v_add_f32_e32 v180, 1.0, v180
	v_add_f32_e32 v181, 1.0, v181
	v_rcp_f32_e32 v178, v178
	v_rcp_f32_e32 v179, v179
	v_rcp_f32_e32 v180, v180
	v_rcp_f32_e32 v181, v181
	v_mul_f32_e32 v88, v88, v178
	v_mul_f32_e32 v89, v89, v179
	v_mul_f32_e32 v90, v90, v180
	v_mul_f32_e32 v91, v91, v181
	v_cvt_pk_bf16_f32 v88, v88, v89
	v_cvt_pk_bf16_f32 v89, v90, v91
	ds_write_b64 v172, v[88:89] offset:2048
	v_mul_f32_e32 v178, 0xbfb8aa3b, v92
	v_mul_f32_e32 v179, 0xbfb8aa3b, v93
	v_mul_f32_e32 v180, 0xbfb8aa3b, v94
	v_mul_f32_e32 v181, 0xbfb8aa3b, v95
	v_exp_f32_e32 v178, v178
	v_exp_f32_e32 v179, v179
	v_exp_f32_e32 v180, v180
	v_exp_f32_e32 v181, v181
	v_add_f32_e32 v178, 1.0, v178
	v_add_f32_e32 v179, 1.0, v179
	v_add_f32_e32 v180, 1.0, v180
	v_add_f32_e32 v181, 1.0, v181
	v_rcp_f32_e32 v178, v178
	v_rcp_f32_e32 v179, v179
	v_rcp_f32_e32 v180, v180
	v_rcp_f32_e32 v181, v181
	v_mul_f32_e32 v92, v92, v178
	v_mul_f32_e32 v93, v93, v179
	v_mul_f32_e32 v94, v94, v180
	v_mul_f32_e32 v95, v95, v181
	v_cvt_pk_bf16_f32 v92, v92, v93
	v_cvt_pk_bf16_f32 v93, v94, v95
	ds_write_b64 v173, v[92:93] offset:2048
	v_mul_f32_e32 v178, 0xbfb8aa3b, v96
	v_mul_f32_e32 v179, 0xbfb8aa3b, v97
	v_mul_f32_e32 v180, 0xbfb8aa3b, v98
	v_mul_f32_e32 v181, 0xbfb8aa3b, v99
	v_exp_f32_e32 v178, v178
	v_exp_f32_e32 v179, v179
	v_exp_f32_e32 v180, v180
	v_exp_f32_e32 v181, v181
	v_add_f32_e32 v178, 1.0, v178
	v_add_f32_e32 v179, 1.0, v179
	v_add_f32_e32 v180, 1.0, v180
	v_add_f32_e32 v181, 1.0, v181
	v_rcp_f32_e32 v178, v178
	v_rcp_f32_e32 v179, v179
	v_rcp_f32_e32 v180, v180
	v_rcp_f32_e32 v181, v181
	v_mul_f32_e32 v96, v96, v178
	v_mul_f32_e32 v97, v97, v179
	v_mul_f32_e32 v98, v98, v180
	v_mul_f32_e32 v99, v99, v181
	v_cvt_pk_bf16_f32 v96, v96, v97
	v_cvt_pk_bf16_f32 v97, v98, v99
	ds_write_b64 v170, v[96:97] offset:4096
	v_mul_f32_e32 v178, 0xbfb8aa3b, v100
	v_mul_f32_e32 v179, 0xbfb8aa3b, v101
	v_mul_f32_e32 v180, 0xbfb8aa3b, v102
	v_mul_f32_e32 v181, 0xbfb8aa3b, v103
	v_exp_f32_e32 v178, v178
	v_exp_f32_e32 v179, v179
	v_exp_f32_e32 v180, v180
	v_exp_f32_e32 v181, v181
	v_add_f32_e32 v178, 1.0, v178
	v_add_f32_e32 v179, 1.0, v179
	v_add_f32_e32 v180, 1.0, v180
	v_add_f32_e32 v181, 1.0, v181
	v_rcp_f32_e32 v178, v178
	v_rcp_f32_e32 v179, v179
	v_rcp_f32_e32 v180, v180
	v_rcp_f32_e32 v181, v181
	v_mul_f32_e32 v100, v100, v178
	v_mul_f32_e32 v101, v101, v179
	v_mul_f32_e32 v102, v102, v180
	v_mul_f32_e32 v103, v103, v181
	v_cvt_pk_bf16_f32 v100, v100, v101
	v_cvt_pk_bf16_f32 v101, v102, v103
	ds_write_b64 v171, v[100:101] offset:4096
	v_mul_f32_e32 v178, 0xbfb8aa3b, v104
	v_mul_f32_e32 v179, 0xbfb8aa3b, v105
	v_mul_f32_e32 v180, 0xbfb8aa3b, v106
	v_mul_f32_e32 v181, 0xbfb8aa3b, v107
	v_exp_f32_e32 v178, v178
	v_exp_f32_e32 v179, v179
	v_exp_f32_e32 v180, v180
	v_exp_f32_e32 v181, v181
	v_add_f32_e32 v178, 1.0, v178
	v_add_f32_e32 v179, 1.0, v179
	v_add_f32_e32 v180, 1.0, v180
	v_add_f32_e32 v181, 1.0, v181
	v_rcp_f32_e32 v178, v178
	v_rcp_f32_e32 v179, v179
	v_rcp_f32_e32 v180, v180
	v_rcp_f32_e32 v181, v181
	v_mul_f32_e32 v104, v104, v178
	v_mul_f32_e32 v105, v105, v179
	v_mul_f32_e32 v106, v106, v180
	v_mul_f32_e32 v107, v107, v181
	v_cvt_pk_bf16_f32 v104, v104, v105
	v_cvt_pk_bf16_f32 v105, v106, v107
	ds_write_b64 v172, v[104:105] offset:4096
	v_mul_f32_e32 v178, 0xbfb8aa3b, v108
	v_mul_f32_e32 v179, 0xbfb8aa3b, v109
	v_mul_f32_e32 v180, 0xbfb8aa3b, v110
	v_mul_f32_e32 v181, 0xbfb8aa3b, v111
	v_exp_f32_e32 v178, v178
	v_exp_f32_e32 v179, v179
	v_exp_f32_e32 v180, v180
	v_exp_f32_e32 v181, v181
	v_add_f32_e32 v178, 1.0, v178
	v_add_f32_e32 v179, 1.0, v179
	v_add_f32_e32 v180, 1.0, v180
	v_add_f32_e32 v181, 1.0, v181
	v_rcp_f32_e32 v178, v178
	v_rcp_f32_e32 v179, v179
	v_rcp_f32_e32 v180, v180
	v_rcp_f32_e32 v181, v181
	v_mul_f32_e32 v108, v108, v178
	v_mul_f32_e32 v109, v109, v179
	v_mul_f32_e32 v110, v110, v180
	v_mul_f32_e32 v111, v111, v181
	v_cvt_pk_bf16_f32 v108, v108, v109
	v_cvt_pk_bf16_f32 v109, v110, v111
	ds_write_b64 v173, v[108:109] offset:4096
	v_mul_f32_e32 v178, 0xbfb8aa3b, v112
	v_mul_f32_e32 v179, 0xbfb8aa3b, v113
	v_mul_f32_e32 v180, 0xbfb8aa3b, v114
	v_mul_f32_e32 v181, 0xbfb8aa3b, v115
	v_exp_f32_e32 v178, v178
	v_exp_f32_e32 v179, v179
	v_exp_f32_e32 v180, v180
	v_exp_f32_e32 v181, v181
	v_add_f32_e32 v178, 1.0, v178
	v_add_f32_e32 v179, 1.0, v179
	v_add_f32_e32 v180, 1.0, v180
	v_add_f32_e32 v181, 1.0, v181
	v_rcp_f32_e32 v178, v178
	v_rcp_f32_e32 v179, v179
	v_rcp_f32_e32 v180, v180
	v_rcp_f32_e32 v181, v181
	v_mul_f32_e32 v112, v112, v178
	v_mul_f32_e32 v113, v113, v179
	v_mul_f32_e32 v114, v114, v180
	v_mul_f32_e32 v115, v115, v181
	v_cvt_pk_bf16_f32 v112, v112, v113
	v_cvt_pk_bf16_f32 v113, v114, v115
	ds_write_b64 v170, v[112:113] offset:6144
	v_mul_f32_e32 v178, 0xbfb8aa3b, v116
	v_mul_f32_e32 v179, 0xbfb8aa3b, v117
	v_mul_f32_e32 v180, 0xbfb8aa3b, v118
	v_mul_f32_e32 v181, 0xbfb8aa3b, v119
	v_exp_f32_e32 v178, v178
	v_exp_f32_e32 v179, v179
	v_exp_f32_e32 v180, v180
	v_exp_f32_e32 v181, v181
	v_add_f32_e32 v178, 1.0, v178
	v_add_f32_e32 v179, 1.0, v179
	v_add_f32_e32 v180, 1.0, v180
	v_add_f32_e32 v181, 1.0, v181
	v_rcp_f32_e32 v178, v178
	v_rcp_f32_e32 v179, v179
	v_rcp_f32_e32 v180, v180
	v_rcp_f32_e32 v181, v181
	v_mul_f32_e32 v116, v116, v178
	v_mul_f32_e32 v117, v117, v179
	v_mul_f32_e32 v118, v118, v180
	v_mul_f32_e32 v119, v119, v181
	v_cvt_pk_bf16_f32 v116, v116, v117
	v_cvt_pk_bf16_f32 v117, v118, v119
	ds_write_b64 v171, v[116:117] offset:6144
	v_mul_f32_e32 v178, 0xbfb8aa3b, v120
	v_mul_f32_e32 v179, 0xbfb8aa3b, v121
	v_mul_f32_e32 v180, 0xbfb8aa3b, v122
	v_mul_f32_e32 v181, 0xbfb8aa3b, v123
	v_exp_f32_e32 v178, v178
	v_exp_f32_e32 v179, v179
	v_exp_f32_e32 v180, v180
	v_exp_f32_e32 v181, v181
	v_add_f32_e32 v178, 1.0, v178
	v_add_f32_e32 v179, 1.0, v179
	v_add_f32_e32 v180, 1.0, v180
	v_add_f32_e32 v181, 1.0, v181
	v_rcp_f32_e32 v178, v178
	v_rcp_f32_e32 v179, v179
	v_rcp_f32_e32 v180, v180
	v_rcp_f32_e32 v181, v181
	v_mul_f32_e32 v120, v120, v178
	v_mul_f32_e32 v121, v121, v179
	v_mul_f32_e32 v122, v122, v180
	v_mul_f32_e32 v123, v123, v181
	v_cvt_pk_bf16_f32 v120, v120, v121
	v_cvt_pk_bf16_f32 v121, v122, v123
	ds_write_b64 v172, v[120:121] offset:6144
	v_mul_f32_e32 v178, 0xbfb8aa3b, v124
	v_mul_f32_e32 v179, 0xbfb8aa3b, v125
	v_mul_f32_e32 v180, 0xbfb8aa3b, v126
	v_mul_f32_e32 v181, 0xbfb8aa3b, v127
	v_exp_f32_e32 v178, v178
	v_exp_f32_e32 v179, v179
	v_exp_f32_e32 v180, v180
	v_exp_f32_e32 v181, v181
	v_add_f32_e32 v178, 1.0, v178
	v_add_f32_e32 v179, 1.0, v179
	v_add_f32_e32 v180, 1.0, v180
	v_add_f32_e32 v181, 1.0, v181
	v_rcp_f32_e32 v178, v178
	v_rcp_f32_e32 v179, v179
	v_rcp_f32_e32 v180, v180
	v_rcp_f32_e32 v181, v181
	v_mul_f32_e32 v124, v124, v178
	v_mul_f32_e32 v125, v125, v179
	v_mul_f32_e32 v126, v126, v180
	v_mul_f32_e32 v127, v127, v181
	v_cvt_pk_bf16_f32 v124, v124, v125
	v_cvt_pk_bf16_f32 v125, v126, v127
	ds_write_b64 v173, v[124:125] offset:6144
	s_waitcnt lgkmcnt(0)
; DEV u16 f2bf(float f) { return (u16)(pack2(f, f) & 0xffffu); }
; DEV float sigmoid_f(float x) { return __builtin_amdgcn_rcpf(1.f + __expf(-x)); }
; DEV void phase_p1(const Params& p, int g, char* smem) {
;     ...
;       } else {
;         acc_foreach(acc, m0, n0, [&](int m, int n, float& v) { GT[(size_t)m * 2048 + (n - 2560)] = f2bf(sigmoid_f(v)); });
	ds_read_b128 v[64:67], v168
	ds_read_b128 v[68:71], v168 offset:1024
	ds_read_b128 v[72:75], v168 offset:2048
	ds_read_b128 v[76:79], v168 offset:3072
	ds_read_b128 v[80:83], v168 offset:4096
	ds_read_b128 v[84:87], v168 offset:5120
	ds_read_b128 v[88:91], v168 offset:6144
	ds_read_b128 v[92:95], v168 offset:7168
	s_waitcnt lgkmcnt(7)
	global_store_dwordx4 v169, v[64:67], s[56:57]
	v_add_u32_e32 v169, 0xa000, v169
	s_waitcnt lgkmcnt(6)
	global_store_dwordx4 v169, v[68:71], s[56:57]
	v_add_u32_e32 v169, 0xa000, v169
	s_waitcnt lgkmcnt(5)
	global_store_dwordx4 v169, v[72:75], s[56:57]
	v_add_u32_e32 v169, 0xa000, v169
	s_waitcnt lgkmcnt(4)
	global_store_dwordx4 v169, v[76:79], s[56:57]
	v_add_u32_e32 v169, 0xa000, v169
	s_waitcnt lgkmcnt(3)
	global_store_dwordx4 v169, v[80:83], s[56:57]
	v_add_u32_e32 v169, 0xa000, v169
	s_waitcnt lgkmcnt(2)
	global_store_dwordx4 v169, v[84:87], s[56:57]
	v_add_u32_e32 v169, 0xa000, v169
	s_waitcnt lgkmcnt(1)
	global_store_dwordx4 v169, v[88:91], s[56:57]
	v_add_u32_e32 v169, 0xa000, v169
	s_waitcnt lgkmcnt(0)
	s_barrier
	global_store_dwordx4 v169, v[92:95], s[56:57]
	v_add_u32_e32 v169, 0xa000, v169
	s_branch .LBB0_261
.Lp1a_gt:
	s_nop 7
	s_nop 7
	s_nop 3
	v_and_b32_e32 v160, 63, v202
	v_lshrrev_b32_e32 v161, 6, v202
	v_and_b32_e32 v164, 3, v161
	v_lshlrev_b32_e32 v164, 13, v164
	v_add_u32_e32 v164, 0x8000, v164
	v_lshrrev_b32_e32 v160, 2, v161
	v_lshl_add_u32 v164, v160, 16, v164
	v_and_b32_e32 v160, 63, v202
	v_and_b32_e32 v166, 15, v160
	v_lshrrev_b32_e32 v167, 4, v160
	v_lshl_add_u32 v168, v166, 7, v164
	v_and_b32_e32 v169, 1, v167
	v_lshl_add_u32 v168, v169, 3, v168
	v_lshrrev_b32_e32 v167, 1, v167
	v_and_b32_e32 v166, 7, v166
	v_xor_b32_e32 v166, v166, v167
	v_lshlrev_b32_e32 v166, 4, v166
	v_add_u32_e32 v170, v168, v166
	v_xor_b32_e32 v167, 0x20, v166
	v_add_u32_e32 v171, v168, v167
	v_xor_b32_e32 v167, 0x40, v166
	v_add_u32_e32 v172, v168, v167
	v_xor_b32_e32 v167, 0x60, v166
	v_add_u32_e32 v173, v168, v167
	v_and_b32_e32 v166, 31, v160
	v_lshrrev_b32_e32 v167, 5, v160
	v_lshlrev_b32_e32 v168, 7, v166
	v_lshl_add_u32 v168, v167, 3, v168
	v_add_u32_e32 v168, v164, v168
	v_and_b32_e32 v166, 7, v166
	v_lshlrev_b32_e32 v166, 4, v166
	v_lshrrev_b32_e32 v166, 3, v160
	v_and_b32_e32 v167, 7, v160
	v_lshrrev_b32_e32 v169, 2, v161
	v_lshl_add_u32 v169, v169, 7, v166
	v_add_u32_e32 v169, s5, v169
	v_mul_u32_u24_e32 v169, 0x1000, v169
	v_and_b32_e32 v168, 3, v161
	v_lshlrev_b32_e32 v168, 3, v168
	v_add_u32_e32 v168, v168, v167
	v_lshl_add_u32 v169, v168, 4, v169
	s_lshl_b32 s100, s4, 1
	s_sub_u32 s100, s100, 0x1400
	v_add_u32_e32 v169, s100, v169
	v_xor_b32_e32 v167, v166, v167
	v_lshlrev_b32_e32 v167, 4, v167
	v_lshl_add_u32 v168, v166, 7, v167
	v_add_u32_e32 v168, v164, v168
	v_mul_f32_e32 v0, 0xbfb8aa3b, v0
	v_mul_f32_e32 v1, 0xbfb8aa3b, v1
	v_mul_f32_e32 v2, 0xbfb8aa3b, v2
	v_mul_f32_e32 v3, 0xbfb8aa3b, v3
	v_exp_f32_e32 v0, v0
	v_exp_f32_e32 v1, v1
	v_exp_f32_e32 v2, v2
	v_exp_f32_e32 v3, v3
	v_add_f32_e32 v0, 1.0, v0
	v_add_f32_e32 v1, 1.0, v1
	v_add_f32_e32 v2, 1.0, v2
	v_add_f32_e32 v3, 1.0, v3
	v_rcp_f32_e32 v0, v0
	v_rcp_f32_e32 v1, v1
	v_rcp_f32_e32 v2, v2
	v_rcp_f32_e32 v3, v3
	v_cvt_pk_bf16_f32 v0, v0, v1
	v_cvt_pk_bf16_f32 v1, v2, v3
	ds_write_b64 v170, v[0:1]
	v_mul_f32_e32 v4, 0xbfb8aa3b, v4
	v_mul_f32_e32 v5, 0xbfb8aa3b, v5
	v_mul_f32_e32 v6, 0xbfb8aa3b, v6
	v_mul_f32_e32 v7, 0xbfb8aa3b, v7
	v_exp_f32_e32 v4, v4
	v_exp_f32_e32 v5, v5
	v_exp_f32_e32 v6, v6
	v_exp_f32_e32 v7, v7
	v_add_f32_e32 v4, 1.0, v4
	v_add_f32_e32 v5, 1.0, v5
	v_add_f32_e32 v6, 1.0, v6
	v_add_f32_e32 v7, 1.0, v7
	v_rcp_f32_e32 v4, v4
	v_rcp_f32_e32 v5, v5
	v_rcp_f32_e32 v6, v6
	v_rcp_f32_e32 v7, v7
	v_cvt_pk_bf16_f32 v4, v4, v5
	v_cvt_pk_bf16_f32 v5, v6, v7
	ds_write_b64 v171, v[4:5]
	v_mul_f32_e32 v8, 0xbfb8aa3b, v8
	v_mul_f32_e32 v9, 0xbfb8aa3b, v9
	v_mul_f32_e32 v10, 0xbfb8aa3b, v10
	v_mul_f32_e32 v11, 0xbfb8aa3b, v11
	v_exp_f32_e32 v8, v8
	v_exp_f32_e32 v9, v9
	v_exp_f32_e32 v10, v10
	v_exp_f32_e32 v11, v11
	v_add_f32_e32 v8, 1.0, v8
	v_add_f32_e32 v9, 1.0, v9
	v_add_f32_e32 v10, 1.0, v10
	v_add_f32_e32 v11, 1.0, v11
	v_rcp_f32_e32 v8, v8
	v_rcp_f32_e32 v9, v9
	v_rcp_f32_e32 v10, v10
	v_rcp_f32_e32 v11, v11
	v_cvt_pk_bf16_f32 v8, v8, v9
	v_cvt_pk_bf16_f32 v9, v10, v11
	ds_write_b64 v172, v[8:9]
	v_mul_f32_e32 v12, 0xbfb8aa3b, v12
	v_mul_f32_e32 v13, 0xbfb8aa3b, v13
	v_mul_f32_e32 v14, 0xbfb8aa3b, v14
	v_mul_f32_e32 v15, 0xbfb8aa3b, v15
	v_exp_f32_e32 v12, v12
	v_exp_f32_e32 v13, v13
	v_exp_f32_e32 v14, v14
	v_exp_f32_e32 v15, v15
	v_add_f32_e32 v12, 1.0, v12
	v_add_f32_e32 v13, 1.0, v13
	v_add_f32_e32 v14, 1.0, v14
	v_add_f32_e32 v15, 1.0, v15
	v_rcp_f32_e32 v12, v12
	v_rcp_f32_e32 v13, v13
	v_rcp_f32_e32 v14, v14
	v_rcp_f32_e32 v15, v15
	v_cvt_pk_bf16_f32 v12, v12, v13
	v_cvt_pk_bf16_f32 v13, v14, v15
	ds_write_b64 v173, v[12:13]
	v_mul_f32_e32 v16, 0xbfb8aa3b, v16
	v_mul_f32_e32 v17, 0xbfb8aa3b, v17
	v_mul_f32_e32 v18, 0xbfb8aa3b, v18
	v_mul_f32_e32 v19, 0xbfb8aa3b, v19
	v_exp_f32_e32 v16, v16
	v_exp_f32_e32 v17, v17
	v_exp_f32_e32 v18, v18
	v_exp_f32_e32 v19, v19
	v_add_f32_e32 v16, 1.0, v16
	v_add_f32_e32 v17, 1.0, v17
	v_add_f32_e32 v18, 1.0, v18
	v_add_f32_e32 v19, 1.0, v19
	v_rcp_f32_e32 v16, v16
	v_rcp_f32_e32 v17, v17
	v_rcp_f32_e32 v18, v18
	v_rcp_f32_e32 v19, v19
	v_cvt_pk_bf16_f32 v16, v16, v17
	v_cvt_pk_bf16_f32 v17, v18, v19
	ds_write_b64 v170, v[16:17] offset:2048
	v_mul_f32_e32 v20, 0xbfb8aa3b, v20
	v_mul_f32_e32 v21, 0xbfb8aa3b, v21
	v_mul_f32_e32 v22, 0xbfb8aa3b, v22
	v_mul_f32_e32 v23, 0xbfb8aa3b, v23
	v_exp_f32_e32 v20, v20
	v_exp_f32_e32 v21, v21
	v_exp_f32_e32 v22, v22
	v_exp_f32_e32 v23, v23
; DEV u16 f2bf(float f) { return (u16)(pack2(f, f) & 0xffffu); }
; DEV float sigmoid_f(float x) { return __builtin_amdgcn_rcpf(1.f + __expf(-x)); }
; DEV void phase_p1(const Params& p, int g, char* smem) {
;     ...
;         acc_foreach(acc, m0, n0, [&](int m, int n, float& v) { GT[(size_t)m * 2048 + (n - 2560)] = f2bf(sigmoid_f(v)); });
	v_add_f32_e32 v20, 1.0, v20
	v_add_f32_e32 v21, 1.0, v21
	v_add_f32_e32 v22, 1.0, v22
	v_add_f32_e32 v23, 1.0, v23
	v_rcp_f32_e32 v20, v20
	v_rcp_f32_e32 v21, v21
	v_rcp_f32_e32 v22, v22
	v_rcp_f32_e32 v23, v23
	v_cvt_pk_bf16_f32 v20, v20, v21
	v_cvt_pk_bf16_f32 v21, v22, v23
	ds_write_b64 v171, v[20:21] offset:2048
	v_mul_f32_e32 v24, 0xbfb8aa3b, v24
	v_mul_f32_e32 v25, 0xbfb8aa3b, v25
	v_mul_f32_e32 v26, 0xbfb8aa3b, v26
	v_mul_f32_e32 v27, 0xbfb8aa3b, v27
	v_exp_f32_e32 v24, v24
	v_exp_f32_e32 v25, v25
	v_exp_f32_e32 v26, v26
	v_exp_f32_e32 v27, v27
	v_add_f32_e32 v24, 1.0, v24
	v_add_f32_e32 v25, 1.0, v25
	v_add_f32_e32 v26, 1.0, v26
	v_add_f32_e32 v27, 1.0, v27
	v_rcp_f32_e32 v24, v24
	v_rcp_f32_e32 v25, v25
	v_rcp_f32_e32 v26, v26
	v_rcp_f32_e32 v27, v27
	v_cvt_pk_bf16_f32 v24, v24, v25
	v_cvt_pk_bf16_f32 v25, v26, v27
	ds_write_b64 v172, v[24:25] offset:2048
	v_mul_f32_e32 v28, 0xbfb8aa3b, v28
	v_mul_f32_e32 v29, 0xbfb8aa3b, v29
	v_mul_f32_e32 v30, 0xbfb8aa3b, v30
	v_mul_f32_e32 v31, 0xbfb8aa3b, v31
	v_exp_f32_e32 v28, v28
	v_exp_f32_e32 v29, v29
	v_exp_f32_e32 v30, v30
	v_exp_f32_e32 v31, v31
	v_add_f32_e32 v28, 1.0, v28
	v_add_f32_e32 v29, 1.0, v29
	v_add_f32_e32 v30, 1.0, v30
	v_add_f32_e32 v31, 1.0, v31
	v_rcp_f32_e32 v28, v28
	v_rcp_f32_e32 v29, v29
	v_rcp_f32_e32 v30, v30
	v_rcp_f32_e32 v31, v31
	v_cvt_pk_bf16_f32 v28, v28, v29
	v_cvt_pk_bf16_f32 v29, v30, v31
	ds_write_b64 v173, v[28:29] offset:2048
	v_mul_f32_e32 v32, 0xbfb8aa3b, v32
	v_mul_f32_e32 v33, 0xbfb8aa3b, v33
	v_mul_f32_e32 v34, 0xbfb8aa3b, v34
	v_mul_f32_e32 v35, 0xbfb8aa3b, v35
	v_exp_f32_e32 v32, v32
	v_exp_f32_e32 v33, v33
	v_exp_f32_e32 v34, v34
	v_exp_f32_e32 v35, v35
	v_add_f32_e32 v32, 1.0, v32
	v_add_f32_e32 v33, 1.0, v33
	v_add_f32_e32 v34, 1.0, v34
	v_add_f32_e32 v35, 1.0, v35
	v_rcp_f32_e32 v32, v32
	v_rcp_f32_e32 v33, v33
	v_rcp_f32_e32 v34, v34
	v_rcp_f32_e32 v35, v35
	v_cvt_pk_bf16_f32 v32, v32, v33
	v_cvt_pk_bf16_f32 v33, v34, v35
	ds_write_b64 v170, v[32:33] offset:4096
	v_mul_f32_e32 v36, 0xbfb8aa3b, v36
	v_mul_f32_e32 v37, 0xbfb8aa3b, v37
	v_mul_f32_e32 v38, 0xbfb8aa3b, v38
	v_mul_f32_e32 v39, 0xbfb8aa3b, v39
	v_exp_f32_e32 v36, v36
	v_exp_f32_e32 v37, v37
	v_exp_f32_e32 v38, v38
	v_exp_f32_e32 v39, v39
	v_add_f32_e32 v36, 1.0, v36
	v_add_f32_e32 v37, 1.0, v37
	v_add_f32_e32 v38, 1.0, v38
	v_add_f32_e32 v39, 1.0, v39
	v_rcp_f32_e32 v36, v36
	v_rcp_f32_e32 v37, v37
	v_rcp_f32_e32 v38, v38
	v_rcp_f32_e32 v39, v39
	v_cvt_pk_bf16_f32 v36, v36, v37
	v_cvt_pk_bf16_f32 v37, v38, v39
	ds_write_b64 v171, v[36:37] offset:4096
	v_mul_f32_e32 v40, 0xbfb8aa3b, v40
	v_mul_f32_e32 v41, 0xbfb8aa3b, v41
	v_mul_f32_e32 v42, 0xbfb8aa3b, v42
	v_mul_f32_e32 v43, 0xbfb8aa3b, v43
	v_exp_f32_e32 v40, v40
	v_exp_f32_e32 v41, v41
	v_exp_f32_e32 v42, v42
	v_exp_f32_e32 v43, v43
	v_add_f32_e32 v40, 1.0, v40
	v_add_f32_e32 v41, 1.0, v41
	v_add_f32_e32 v42, 1.0, v42
	v_add_f32_e32 v43, 1.0, v43
	v_rcp_f32_e32 v40, v40
	v_rcp_f32_e32 v41, v41
	v_rcp_f32_e32 v42, v42
	v_rcp_f32_e32 v43, v43
	v_cvt_pk_bf16_f32 v40, v40, v41
	v_cvt_pk_bf16_f32 v41, v42, v43
	ds_write_b64 v172, v[40:41] offset:4096
	v_mul_f32_e32 v44, 0xbfb8aa3b, v44
	v_mul_f32_e32 v45, 0xbfb8aa3b, v45
	v_mul_f32_e32 v46, 0xbfb8aa3b, v46
	v_mul_f32_e32 v47, 0xbfb8aa3b, v47
	v_exp_f32_e32 v44, v44
	v_exp_f32_e32 v45, v45
	v_exp_f32_e32 v46, v46
	v_exp_f32_e32 v47, v47
	v_add_f32_e32 v44, 1.0, v44
	v_add_f32_e32 v45, 1.0, v45
	v_add_f32_e32 v46, 1.0, v46
	v_add_f32_e32 v47, 1.0, v47
	v_rcp_f32_e32 v44, v44
	v_rcp_f32_e32 v45, v45
	v_rcp_f32_e32 v46, v46
	v_rcp_f32_e32 v47, v47
	v_cvt_pk_bf16_f32 v44, v44, v45
	v_cvt_pk_bf16_f32 v45, v46, v47
	ds_write_b64 v173, v[44:45] offset:4096
	v_mul_f32_e32 v48, 0xbfb8aa3b, v48
	v_mul_f32_e32 v49, 0xbfb8aa3b, v49
	v_mul_f32_e32 v50, 0xbfb8aa3b, v50
	v_mul_f32_e32 v51, 0xbfb8aa3b, v51
	v_exp_f32_e32 v48, v48
	v_exp_f32_e32 v49, v49
	v_exp_f32_e32 v50, v50
	v_exp_f32_e32 v51, v51
	v_add_f32_e32 v48, 1.0, v48
	v_add_f32_e32 v49, 1.0, v49
	v_add_f32_e32 v50, 1.0, v50
	v_add_f32_e32 v51, 1.0, v51
	v_rcp_f32_e32 v48, v48
	v_rcp_f32_e32 v49, v49
	v_rcp_f32_e32 v50, v50
	v_rcp_f32_e32 v51, v51
	v_cvt_pk_bf16_f32 v48, v48, v49
	v_cvt_pk_bf16_f32 v49, v50, v51
	ds_write_b64 v170, v[48:49] offset:6144
	v_mul_f32_e32 v52, 0xbfb8aa3b, v52
	v_mul_f32_e32 v53, 0xbfb8aa3b, v53
	v_mul_f32_e32 v54, 0xbfb8aa3b, v54
	v_mul_f32_e32 v55, 0xbfb8aa3b, v55
	v_exp_f32_e32 v52, v52
	v_exp_f32_e32 v53, v53
	v_exp_f32_e32 v54, v54
	v_exp_f32_e32 v55, v55
	v_add_f32_e32 v52, 1.0, v52
	v_add_f32_e32 v53, 1.0, v53
	v_add_f32_e32 v54, 1.0, v54
	v_add_f32_e32 v55, 1.0, v55
	v_rcp_f32_e32 v52, v52
	v_rcp_f32_e32 v53, v53
	v_rcp_f32_e32 v54, v54
	v_rcp_f32_e32 v55, v55
	v_cvt_pk_bf16_f32 v52, v52, v53
	v_cvt_pk_bf16_f32 v53, v54, v55
	ds_write_b64 v171, v[52:53] offset:6144
	v_mul_f32_e32 v56, 0xbfb8aa3b, v56
	v_mul_f32_e32 v57, 0xbfb8aa3b, v57
	v_mul_f32_e32 v58, 0xbfb8aa3b, v58
	v_mul_f32_e32 v59, 0xbfb8aa3b, v59
	v_exp_f32_e32 v56, v56
	v_exp_f32_e32 v57, v57
	v_exp_f32_e32 v58, v58
	v_exp_f32_e32 v59, v59
	v_add_f32_e32 v56, 1.0, v56
	v_add_f32_e32 v57, 1.0, v57
	v_add_f32_e32 v58, 1.0, v58
	v_add_f32_e32 v59, 1.0, v59
	v_rcp_f32_e32 v56, v56
	v_rcp_f32_e32 v57, v57
	v_rcp_f32_e32 v58, v58
	v_rcp_f32_e32 v59, v59
	v_cvt_pk_bf16_f32 v56, v56, v57
	v_cvt_pk_bf16_f32 v57, v58, v59
	ds_write_b64 v172, v[56:57] offset:6144
	v_mul_f32_e32 v60, 0xbfb8aa3b, v60
	v_mul_f32_e32 v61, 0xbfb8aa3b, v61
	v_mul_f32_e32 v62, 0xbfb8aa3b, v62
	v_mul_f32_e32 v63, 0xbfb8aa3b, v63
	v_exp_f32_e32 v60, v60
	v_exp_f32_e32 v61, v61
	v_exp_f32_e32 v62, v62
	v_exp_f32_e32 v63, v63
	v_add_f32_e32 v60, 1.0, v60
	v_add_f32_e32 v61, 1.0, v61
	v_add_f32_e32 v62, 1.0, v62
	v_add_f32_e32 v63, 1.0, v63
	v_rcp_f32_e32 v60, v60
	v_rcp_f32_e32 v61, v61
	v_rcp_f32_e32 v62, v62
	v_rcp_f32_e32 v63, v63
	v_cvt_pk_bf16_f32 v60, v60, v61
	v_cvt_pk_bf16_f32 v61, v62, v63
	ds_write_b64 v173, v[60:61] offset:6144
	s_waitcnt lgkmcnt(0)
; DEV u16 f2bf(float f) { return (u16)(pack2(f, f) & 0xffffu); }
; DEV float sigmoid_f(float x) { return __builtin_amdgcn_rcpf(1.f + __expf(-x)); }
; DEV void phase_p1(const Params& p, int g, char* smem) {
;     ...
;         acc_foreach(acc, m0, n0, [&](int m, int n, float& v) { GT[(size_t)m * 2048 + (n - 2560)] = f2bf(sigmoid_f(v)); });
	ds_read_b128 v[32:35], v168
	ds_read_b128 v[36:39], v168 offset:1024
	ds_read_b128 v[40:43], v168 offset:2048
	ds_read_b128 v[44:47], v168 offset:3072
	ds_read_b128 v[48:51], v168 offset:4096
	ds_read_b128 v[52:55], v168 offset:5120
	ds_read_b128 v[56:59], v168 offset:6144
	ds_read_b128 v[60:63], v168 offset:7168
	s_waitcnt lgkmcnt(7)
	global_store_dwordx4 v169, v[32:35], s[20:21]
	v_add_u32_e32 v169, 0x8000, v169
	s_waitcnt lgkmcnt(6)
	global_store_dwordx4 v169, v[36:39], s[20:21]
	v_add_u32_e32 v169, 0x8000, v169
	s_waitcnt lgkmcnt(5)
	global_store_dwordx4 v169, v[40:43], s[20:21]
	v_add_u32_e32 v169, 0x8000, v169
	s_waitcnt lgkmcnt(4)
	global_store_dwordx4 v169, v[44:47], s[20:21]
	v_add_u32_e32 v169, 0x8000, v169
	s_waitcnt lgkmcnt(3)
	global_store_dwordx4 v169, v[48:51], s[20:21]
	v_add_u32_e32 v169, 0x8000, v169
	s_waitcnt lgkmcnt(2)
	global_store_dwordx4 v169, v[52:55], s[20:21]
	v_add_u32_e32 v169, 0x8000, v169
	s_waitcnt lgkmcnt(1)
	global_store_dwordx4 v169, v[56:59], s[20:21]
	v_add_u32_e32 v169, 0x8000, v169
	s_waitcnt lgkmcnt(0)
	global_store_dwordx4 v169, v[60:63], s[20:21]
	v_add_u32_e32 v169, 0x8000, v169
	v_mul_f32_e32 v64, 0xbfb8aa3b, v64
	v_mul_f32_e32 v65, 0xbfb8aa3b, v65
	v_mul_f32_e32 v66, 0xbfb8aa3b, v66
	v_mul_f32_e32 v67, 0xbfb8aa3b, v67
	v_exp_f32_e32 v64, v64
	v_exp_f32_e32 v65, v65
	v_exp_f32_e32 v66, v66
	v_exp_f32_e32 v67, v67
	v_add_f32_e32 v64, 1.0, v64
	v_add_f32_e32 v65, 1.0, v65
	v_add_f32_e32 v66, 1.0, v66
	v_add_f32_e32 v67, 1.0, v67
	v_rcp_f32_e32 v64, v64
	v_rcp_f32_e32 v65, v65
	v_rcp_f32_e32 v66, v66
	v_rcp_f32_e32 v67, v67
	v_cvt_pk_bf16_f32 v64, v64, v65
	v_cvt_pk_bf16_f32 v65, v66, v67
	ds_write_b64 v170, v[64:65]
	v_mul_f32_e32 v68, 0xbfb8aa3b, v68
	v_mul_f32_e32 v69, 0xbfb8aa3b, v69
	v_mul_f32_e32 v70, 0xbfb8aa3b, v70
	v_mul_f32_e32 v71, 0xbfb8aa3b, v71
	v_exp_f32_e32 v68, v68
	v_exp_f32_e32 v69, v69
	v_exp_f32_e32 v70, v70
	v_exp_f32_e32 v71, v71
	v_add_f32_e32 v68, 1.0, v68
	v_add_f32_e32 v69, 1.0, v69
	v_add_f32_e32 v70, 1.0, v70
	v_add_f32_e32 v71, 1.0, v71
	v_rcp_f32_e32 v68, v68
	v_rcp_f32_e32 v69, v69
	v_rcp_f32_e32 v70, v70
	v_rcp_f32_e32 v71, v71
	v_cvt_pk_bf16_f32 v68, v68, v69
	v_cvt_pk_bf16_f32 v69, v70, v71
	ds_write_b64 v171, v[68:69]
	v_mul_f32_e32 v72, 0xbfb8aa3b, v72
	v_mul_f32_e32 v73, 0xbfb8aa3b, v73
	v_mul_f32_e32 v74, 0xbfb8aa3b, v74
	v_mul_f32_e32 v75, 0xbfb8aa3b, v75
	v_exp_f32_e32 v72, v72
	v_exp_f32_e32 v73, v73
	v_exp_f32_e32 v74, v74
	v_exp_f32_e32 v75, v75
	v_add_f32_e32 v72, 1.0, v72
	v_add_f32_e32 v73, 1.0, v73
	v_add_f32_e32 v74, 1.0, v74
	v_add_f32_e32 v75, 1.0, v75
	v_rcp_f32_e32 v72, v72
	v_rcp_f32_e32 v73, v73
	v_rcp_f32_e32 v74, v74
	v_rcp_f32_e32 v75, v75
	v_cvt_pk_bf16_f32 v72, v72, v73
	v_cvt_pk_bf16_f32 v73, v74, v75
	ds_write_b64 v172, v[72:73]
	v_mul_f32_e32 v76, 0xbfb8aa3b, v76
	v_mul_f32_e32 v77, 0xbfb8aa3b, v77
	v_mul_f32_e32 v78, 0xbfb8aa3b, v78
	v_mul_f32_e32 v79, 0xbfb8aa3b, v79
	v_exp_f32_e32 v76, v76
	v_exp_f32_e32 v77, v77
	v_exp_f32_e32 v78, v78
	v_exp_f32_e32 v79, v79
	v_add_f32_e32 v76, 1.0, v76
	v_add_f32_e32 v77, 1.0, v77
	v_add_f32_e32 v78, 1.0, v78
	v_add_f32_e32 v79, 1.0, v79
	v_rcp_f32_e32 v76, v76
	v_rcp_f32_e32 v77, v77
	v_rcp_f32_e32 v78, v78
	v_rcp_f32_e32 v79, v79
	v_cvt_pk_bf16_f32 v76, v76, v77
	v_cvt_pk_bf16_f32 v77, v78, v79
	ds_write_b64 v173, v[76:77]
	v_mul_f32_e32 v80, 0xbfb8aa3b, v80
	v_mul_f32_e32 v81, 0xbfb8aa3b, v81
	v_mul_f32_e32 v82, 0xbfb8aa3b, v82
	v_mul_f32_e32 v83, 0xbfb8aa3b, v83
	v_exp_f32_e32 v80, v80
	v_exp_f32_e32 v81, v81
	v_exp_f32_e32 v82, v82
	v_exp_f32_e32 v83, v83
	v_add_f32_e32 v80, 1.0, v80
	v_add_f32_e32 v81, 1.0, v81
	v_add_f32_e32 v82, 1.0, v82
	v_add_f32_e32 v83, 1.0, v83
	v_rcp_f32_e32 v80, v80
	v_rcp_f32_e32 v81, v81
	v_rcp_f32_e32 v82, v82
	v_rcp_f32_e32 v83, v83
	v_cvt_pk_bf16_f32 v80, v80, v81
	v_cvt_pk_bf16_f32 v81, v82, v83
	ds_write_b64 v170, v[80:81] offset:2048
	v_mul_f32_e32 v84, 0xbfb8aa3b, v84
	v_mul_f32_e32 v85, 0xbfb8aa3b, v85
	v_mul_f32_e32 v86, 0xbfb8aa3b, v86
	v_mul_f32_e32 v87, 0xbfb8aa3b, v87
	v_exp_f32_e32 v84, v84
	v_exp_f32_e32 v85, v85
	v_exp_f32_e32 v86, v86
	v_exp_f32_e32 v87, v87
	v_add_f32_e32 v84, 1.0, v84
	v_add_f32_e32 v85, 1.0, v85
	v_add_f32_e32 v86, 1.0, v86
	v_add_f32_e32 v87, 1.0, v87
	v_rcp_f32_e32 v84, v84
	v_rcp_f32_e32 v85, v85
	v_rcp_f32_e32 v86, v86
	v_rcp_f32_e32 v87, v87
	v_cvt_pk_bf16_f32 v84, v84, v85
	v_cvt_pk_bf16_f32 v85, v86, v87
	ds_write_b64 v171, v[84:85] offset:2048
	v_mul_f32_e32 v88, 0xbfb8aa3b, v88
	v_mul_f32_e32 v89, 0xbfb8aa3b, v89
	v_mul_f32_e32 v90, 0xbfb8aa3b, v90
	v_mul_f32_e32 v91, 0xbfb8aa3b, v91
	v_exp_f32_e32 v88, v88
	v_exp_f32_e32 v89, v89
	v_exp_f32_e32 v90, v90
	v_exp_f32_e32 v91, v91
	v_add_f32_e32 v88, 1.0, v88
	v_add_f32_e32 v89, 1.0, v89
	v_add_f32_e32 v90, 1.0, v90
	v_add_f32_e32 v91, 1.0, v91
	v_rcp_f32_e32 v88, v88
	v_rcp_f32_e32 v89, v89
	v_rcp_f32_e32 v90, v90
	v_rcp_f32_e32 v91, v91
	v_cvt_pk_bf16_f32 v88, v88, v89
	v_cvt_pk_bf16_f32 v89, v90, v91
	ds_write_b64 v172, v[88:89] offset:2048
	v_mul_f32_e32 v92, 0xbfb8aa3b, v92
	v_mul_f32_e32 v93, 0xbfb8aa3b, v93
	v_mul_f32_e32 v94, 0xbfb8aa3b, v94
	v_mul_f32_e32 v95, 0xbfb8aa3b, v95
	v_exp_f32_e32 v92, v92
	v_exp_f32_e32 v93, v93
	v_exp_f32_e32 v94, v94
	v_exp_f32_e32 v95, v95
	v_add_f32_e32 v92, 1.0, v92
	v_add_f32_e32 v93, 1.0, v93
	v_add_f32_e32 v94, 1.0, v94
	v_add_f32_e32 v95, 1.0, v95
	v_rcp_f32_e32 v92, v92
	v_rcp_f32_e32 v93, v93
	v_rcp_f32_e32 v94, v94
	v_rcp_f32_e32 v95, v95
	v_cvt_pk_bf16_f32 v92, v92, v93
	v_cvt_pk_bf16_f32 v93, v94, v95
	ds_write_b64 v173, v[92:93] offset:2048
	v_mul_f32_e32 v96, 0xbfb8aa3b, v96
	v_mul_f32_e32 v97, 0xbfb8aa3b, v97
; DEV u16 f2bf(float f) { return (u16)(pack2(f, f) & 0xffffu); }
; DEV float sigmoid_f(float x) { return __builtin_amdgcn_rcpf(1.f + __expf(-x)); }
; DEV void phase_p1(const Params& p, int g, char* smem) {
;     ...
;         acc_foreach(acc, m0, n0, [&](int m, int n, float& v) { GT[(size_t)m * 2048 + (n - 2560)] = f2bf(sigmoid_f(v)); });
	v_mul_f32_e32 v98, 0xbfb8aa3b, v98
	v_mul_f32_e32 v99, 0xbfb8aa3b, v99
	v_exp_f32_e32 v96, v96
	v_exp_f32_e32 v97, v97
	v_exp_f32_e32 v98, v98
	v_exp_f32_e32 v99, v99
	v_add_f32_e32 v96, 1.0, v96
	v_add_f32_e32 v97, 1.0, v97
	v_add_f32_e32 v98, 1.0, v98
	v_add_f32_e32 v99, 1.0, v99
	v_rcp_f32_e32 v96, v96
	v_rcp_f32_e32 v97, v97
	v_rcp_f32_e32 v98, v98
	v_rcp_f32_e32 v99, v99
	v_cvt_pk_bf16_f32 v96, v96, v97
	v_cvt_pk_bf16_f32 v97, v98, v99
	ds_write_b64 v170, v[96:97] offset:4096
	v_mul_f32_e32 v100, 0xbfb8aa3b, v100
	v_mul_f32_e32 v101, 0xbfb8aa3b, v101
	v_mul_f32_e32 v102, 0xbfb8aa3b, v102
	v_mul_f32_e32 v103, 0xbfb8aa3b, v103
	v_exp_f32_e32 v100, v100
	v_exp_f32_e32 v101, v101
	v_exp_f32_e32 v102, v102
	v_exp_f32_e32 v103, v103
	v_add_f32_e32 v100, 1.0, v100
	v_add_f32_e32 v101, 1.0, v101
	v_add_f32_e32 v102, 1.0, v102
	v_add_f32_e32 v103, 1.0, v103
	v_rcp_f32_e32 v100, v100
	v_rcp_f32_e32 v101, v101
	v_rcp_f32_e32 v102, v102
	v_rcp_f32_e32 v103, v103
	v_cvt_pk_bf16_f32 v100, v100, v101
	v_cvt_pk_bf16_f32 v101, v102, v103
	ds_write_b64 v171, v[100:101] offset:4096
	v_mul_f32_e32 v104, 0xbfb8aa3b, v104
	v_mul_f32_e32 v105, 0xbfb8aa3b, v105
	v_mul_f32_e32 v106, 0xbfb8aa3b, v106
	v_mul_f32_e32 v107, 0xbfb8aa3b, v107
	v_exp_f32_e32 v104, v104
	v_exp_f32_e32 v105, v105
	v_exp_f32_e32 v106, v106
	v_exp_f32_e32 v107, v107
	v_add_f32_e32 v104, 1.0, v104
	v_add_f32_e32 v105, 1.0, v105
	v_add_f32_e32 v106, 1.0, v106
	v_add_f32_e32 v107, 1.0, v107
	v_rcp_f32_e32 v104, v104
	v_rcp_f32_e32 v105, v105
	v_rcp_f32_e32 v106, v106
	v_rcp_f32_e32 v107, v107
	v_cvt_pk_bf16_f32 v104, v104, v105
	v_cvt_pk_bf16_f32 v105, v106, v107
	ds_write_b64 v172, v[104:105] offset:4096
	v_mul_f32_e32 v108, 0xbfb8aa3b, v108
	v_mul_f32_e32 v109, 0xbfb8aa3b, v109
	v_mul_f32_e32 v110, 0xbfb8aa3b, v110
	v_mul_f32_e32 v111, 0xbfb8aa3b, v111
	v_exp_f32_e32 v108, v108
	v_exp_f32_e32 v109, v109
	v_exp_f32_e32 v110, v110
	v_exp_f32_e32 v111, v111
	v_add_f32_e32 v108, 1.0, v108
	v_add_f32_e32 v109, 1.0, v109
	v_add_f32_e32 v110, 1.0, v110
	v_add_f32_e32 v111, 1.0, v111
	v_rcp_f32_e32 v108, v108
	v_rcp_f32_e32 v109, v109
	v_rcp_f32_e32 v110, v110
	v_rcp_f32_e32 v111, v111
	v_cvt_pk_bf16_f32 v108, v108, v109
	v_cvt_pk_bf16_f32 v109, v110, v111
	ds_write_b64 v173, v[108:109] offset:4096
	v_mul_f32_e32 v112, 0xbfb8aa3b, v112
	v_mul_f32_e32 v113, 0xbfb8aa3b, v113
	v_mul_f32_e32 v114, 0xbfb8aa3b, v114
	v_mul_f32_e32 v115, 0xbfb8aa3b, v115
	v_exp_f32_e32 v112, v112
	v_exp_f32_e32 v113, v113
	v_exp_f32_e32 v114, v114
	v_exp_f32_e32 v115, v115
	v_add_f32_e32 v112, 1.0, v112
	v_add_f32_e32 v113, 1.0, v113
	v_add_f32_e32 v114, 1.0, v114
	v_add_f32_e32 v115, 1.0, v115
	v_rcp_f32_e32 v112, v112
	v_rcp_f32_e32 v113, v113
	v_rcp_f32_e32 v114, v114
	v_rcp_f32_e32 v115, v115
	v_cvt_pk_bf16_f32 v112, v112, v113
	v_cvt_pk_bf16_f32 v113, v114, v115
	ds_write_b64 v170, v[112:113] offset:6144
	v_mul_f32_e32 v116, 0xbfb8aa3b, v116
	v_mul_f32_e32 v117, 0xbfb8aa3b, v117
	v_mul_f32_e32 v118, 0xbfb8aa3b, v118
	v_mul_f32_e32 v119, 0xbfb8aa3b, v119
	v_exp_f32_e32 v116, v116
	v_exp_f32_e32 v117, v117
	v_exp_f32_e32 v118, v118
	v_exp_f32_e32 v119, v119
	v_add_f32_e32 v116, 1.0, v116
	v_add_f32_e32 v117, 1.0, v117
	v_add_f32_e32 v118, 1.0, v118
	v_add_f32_e32 v119, 1.0, v119
	v_rcp_f32_e32 v116, v116
	v_rcp_f32_e32 v117, v117
	v_rcp_f32_e32 v118, v118
	v_rcp_f32_e32 v119, v119
	v_cvt_pk_bf16_f32 v116, v116, v117
	v_cvt_pk_bf16_f32 v117, v118, v119
	ds_write_b64 v171, v[116:117] offset:6144
	v_mul_f32_e32 v120, 0xbfb8aa3b, v120
	v_mul_f32_e32 v121, 0xbfb8aa3b, v121
	v_mul_f32_e32 v122, 0xbfb8aa3b, v122
	v_mul_f32_e32 v123, 0xbfb8aa3b, v123
	v_exp_f32_e32 v120, v120
	v_exp_f32_e32 v121, v121
	v_exp_f32_e32 v122, v122
	v_exp_f32_e32 v123, v123
	v_add_f32_e32 v120, 1.0, v120
	v_add_f32_e32 v121, 1.0, v121
	v_add_f32_e32 v122, 1.0, v122
	v_add_f32_e32 v123, 1.0, v123
	v_rcp_f32_e32 v120, v120
	v_rcp_f32_e32 v121, v121
	v_rcp_f32_e32 v122, v122
	v_rcp_f32_e32 v123, v123
	v_cvt_pk_bf16_f32 v120, v120, v121
	v_cvt_pk_bf16_f32 v121, v122, v123
	ds_write_b64 v172, v[120:121] offset:6144
	v_mul_f32_e32 v124, 0xbfb8aa3b, v124
	v_mul_f32_e32 v125, 0xbfb8aa3b, v125
	v_mul_f32_e32 v126, 0xbfb8aa3b, v126
	v_mul_f32_e32 v127, 0xbfb8aa3b, v127
	v_exp_f32_e32 v124, v124
	v_exp_f32_e32 v125, v125
	v_exp_f32_e32 v126, v126
	v_exp_f32_e32 v127, v127
	v_add_f32_e32 v124, 1.0, v124
	v_add_f32_e32 v125, 1.0, v125
	v_add_f32_e32 v126, 1.0, v126
	v_add_f32_e32 v127, 1.0, v127
	v_rcp_f32_e32 v124, v124
	v_rcp_f32_e32 v125, v125
	v_rcp_f32_e32 v126, v126
	v_rcp_f32_e32 v127, v127
	v_cvt_pk_bf16_f32 v124, v124, v125
	v_cvt_pk_bf16_f32 v125, v126, v127
	ds_write_b64 v173, v[124:125] offset:6144
	s_waitcnt lgkmcnt(0)
	ds_read_b128 v[64:67], v168
	ds_read_b128 v[68:71], v168 offset:1024
	ds_read_b128 v[72:75], v168 offset:2048
	ds_read_b128 v[76:79], v168 offset:3072
	ds_read_b128 v[80:83], v168 offset:4096
	ds_read_b128 v[84:87], v168 offset:5120
	ds_read_b128 v[88:91], v168 offset:6144
	ds_read_b128 v[92:95], v168 offset:7168
	s_waitcnt lgkmcnt(7)
	global_store_dwordx4 v169, v[64:67], s[20:21]
	v_add_u32_e32 v169, 0x8000, v169
	s_waitcnt lgkmcnt(6)
	global_store_dwordx4 v169, v[68:71], s[20:21]
	v_add_u32_e32 v169, 0x8000, v169
	s_waitcnt lgkmcnt(5)
	global_store_dwordx4 v169, v[72:75], s[20:21]
	v_add_u32_e32 v169, 0x8000, v169
	s_waitcnt lgkmcnt(4)
	global_store_dwordx4 v169, v[76:79], s[20:21]
	v_add_u32_e32 v169, 0x8000, v169
	s_waitcnt lgkmcnt(3)
	global_store_dwordx4 v169, v[80:83], s[20:21]
	v_add_u32_e32 v169, 0x8000, v169
	s_waitcnt lgkmcnt(2)
	global_store_dwordx4 v169, v[84:87], s[20:21]
	v_add_u32_e32 v169, 0x8000, v169
	s_waitcnt lgkmcnt(1)
	global_store_dwordx4 v169, v[88:91], s[20:21]
	v_add_u32_e32 v169, 0x8000, v169
	s_waitcnt lgkmcnt(0)
	s_barrier
	global_store_dwordx4 v169, v[92:95], s[20:21]
	v_add_u32_e32 v169, 0x8000, v169
	s_branch .LBB0_261

; template <class AL, class BL>
; DEV void gemm_mainloop_p(Acc& acc, const AL& al, const BL& bl, int m0, int n0, int m0n, int n0n, int K, char* lds,
;                          GemmPipe& gp) {
;   const int tid = tidx_full();
;   const int wave = tid >> 6, lane = tid & 63;
;   const int wm = (wave >> 2) * 128, wn = (wave & 3) * 64;
;   const int lr = lane & 31, lh = lane >> 5;
;   const int nk = K / BK;
;   if (!gp.primed) {
;     gp.ra = al.load(tid, m0, 0);
;     gp.rb = bl.load(tid, n0, 0);
;     __syncthreads();
;     al.store(tid, lds, gp.ra);
;     bl.store(tid, lds + TILE_BYTES, gp.rb);
;     gp.ra = al.load(tid, m0, BK);
;     gp.rb = bl.load(tid, n0, BK);
;     __syncthreads();
;   }
; DEV void phase_p1(const Params& p, int g, char* smem) {
;     ...
;     for (int iter = 0;; ++iter) {
;       int cm, tn, cmn, tnn;
;       if (!tile_map(iter, 6, 128, cm, tn)) break;
;       const bool more = tile_map(iter + 1, 6, 128, cmn, tnn);
;       if (!more) { cmn = cm; tnn = tn; }
;       Acc acc;
;       acc_zero(acc);
;       const int m0 = cm * 256, n0 = tn * 256;
;       RowLoader al{WinT, 1024}, bl{H, 1024};
;       gemm_mainloop_p(acc, al, bl, m0, n0, cmn * 256, tnn * 256, 1024, smem, gp);
.LBB0_560:
	s_and_b64 vcc, exec, s[2:3]
	s_lshl_b32 s11, s7, 8
	s_lshl_b32 s2, s8, 8
	v_lshrrev_b32_e32 v149, 6, v202
	v_and_b32_e32 v148, 63, v202
	s_nop 0
	v_readfirstlane_b32 s9, v149
	v_lshrrev_b32_e32 v150, 3, v148
	v_lshl_add_u32 v150, v149, 5, v150
	v_and_b32_e32 v151, 7, v148
	v_lshrrev_b32_e32 v128, 4, v148
	v_xor_b32_e32 v151, v128, v151
	v_lshlrev_b32_e32 v151, 4, v151
	s_lshl_b32 s9, s9, 12
	v_add_u32_e32 v128, s11, v150
	v_lshlrev_b32_e32 v128, 11, v128
	v_add_u32_e32 v128, v128, v151
	v_add_u32_e32 v129, 0x4000, v128
	v_add_u32_e32 v130, 0x8000, v128
	v_add_u32_e32 v131, 0xc000, v128
	v_xor_b32_e32 v129, 0x40, v129
	v_xor_b32_e32 v131, 0x40, v131
	v_add_u32_e32 v132, s2, v150
	v_lshlrev_b32_e32 v132, 11, v132
	v_add_u32_e32 v132, v132, v151
	v_add_u32_e32 v133, 0x4000, v132
	v_add_u32_e32 v134, 0x8000, v132
	v_add_u32_e32 v135, 0xc000, v132
	v_xor_b32_e32 v133, 0x40, v133
	v_xor_b32_e32 v135, 0x40, v135
	v_add_u32_e32 v136, 0x40000, v128
	v_add_u32_e32 v137, 0x40000, v129
	v_add_u32_e32 v138, 0x40000, v130
	v_add_u32_e32 v139, 0x40000, v131
	v_add_u32_e32 v140, 0x40000, v132
	v_add_u32_e32 v141, 0x40000, v133
	v_add_u32_e32 v142, 0x40000, v134
	v_add_u32_e32 v143, 0x40000, v135
	v_lshrrev_b32_e32 v161, 6, v202
	v_and_b32_e32 v160, 63, v202
	v_bfe_u32 v242, v160, 1, 3
	v_lshrrev_b32_e32 v243, 4, v160
	v_xor_b32_e32 v242, v242, v243
	v_lshlrev_b32_e32 v242, 4, v242
	v_and_b32_e32 v243, 15, v160
	v_lshlrev_b32_e32 v243, 7, v243
	v_lshrrev_b32_e32 v144, 2, v161
	v_lshl_add_u32 v144, v144, 14, v243
	v_and_b32_e32 v146, 3, v161
	v_lshl_add_u32 v146, v146, 13, v243
	v_add_u32_e32 v146, 0x10000, v146
	v_xor_b32_e32 v145, 0x40, v242
	v_add_u32_e32 v145, v144, v145
	v_add_u32_e32 v144, v144, v242
	v_xor_b32_e32 v147, 0x40, v242
	v_add_u32_e32 v147, v146, v147
	v_add_u32_e32 v146, v146, v242
	s_mov_b64 s[14:15], s[88:89]
	s_mov_b64 s[16:17], s[64:65]
	s_cbranch_vccnz .Lp1b_primed
	s_cmp_lt_u32 s9, 0x4000
	s_cbranch_scc0 .Lp1b_d1
	s_add_u32 m0, s9, 0x0
	s_nop 0
	global_load_lds_dwordx4 v128, s[14:15]
	s_add_u32 m0, m0, 0x400
	s_nop 0
	global_load_lds_dwordx4 v129, s[14:15]
	s_add_u32 m0, m0, 0x400
	s_nop 0
	global_load_lds_dwordx4 v130, s[14:15]
	s_add_u32 m0, m0, 0x400
	s_nop 0
	global_load_lds_dwordx4 v131, s[14:15]
	s_add_u32 m0, s9, 0x10000
	s_nop 0
	global_load_lds_dwordx4 v132, s[16:17]
	s_add_u32 m0, m0, 0x400
	s_nop 0
	global_load_lds_dwordx4 v133, s[16:17]
	s_add_u32 m0, m0, 0x400
	s_nop 0
	global_load_lds_dwordx4 v134, s[16:17]
	s_add_u32 m0, m0, 0x400
	s_nop 0
	global_load_lds_dwordx4 v135, s[16:17]
	s_add_u32 m0, s9, 0x4000
	s_nop 0
	global_load_lds_dwordx4 v136, s[14:15]
	s_add_u32 m0, m0, 0x400
	s_nop 0
	global_load_lds_dwordx4 v137, s[14:15]
	s_add_u32 m0, m0, 0x400
	s_nop 0
	global_load_lds_dwordx4 v138, s[14:15]
	s_add_u32 m0, m0, 0x400
	s_nop 0
	global_load_lds_dwordx4 v139, s[14:15]
	s_add_u32 m0, s9, 0x14000
	s_nop 0
	global_load_lds_dwordx4 v140, s[16:17]
	s_add_u32 m0, m0, 0x400
	s_nop 0
	global_load_lds_dwordx4 v141, s[16:17]
	s_add_u32 m0, m0, 0x400
	s_nop 0
	global_load_lds_dwordx4 v142, s[16:17]
	s_add_u32 m0, m0, 0x400
	s_nop 0
	global_load_lds_dwordx4 v143, s[16:17]
.Lp1b_d1:
.Lp1b_primed:
	s_add_u32 s14, s14, 0x80
	s_addc_u32 s15, s15, 0
	s_add_u32 s16, s16, 0x80
	s_addc_u32 s17, s17, 0
	v_mov_b32_e32 v0, 0
	v_mov_b32_e32 v1, 0
	v_mov_b64_e32 v[2:3], v[0:1]
	v_mov_b64_e32 v[4:5], v[0:1]
	v_mov_b64_e32 v[6:7], v[0:1]
	v_mov_b64_e32 v[8:9], v[0:1]
	v_mov_b64_e32 v[10:11], v[0:1]
	v_mov_b64_e32 v[12:13], v[0:1]
	v_mov_b64_e32 v[14:15], v[0:1]
	v_mov_b64_e32 v[16:17], v[0:1]
	v_mov_b64_e32 v[18:19], v[0:1]
	v_mov_b64_e32 v[20:21], v[0:1]
	v_mov_b64_e32 v[22:23], v[0:1]
	v_mov_b64_e32 v[24:25], v[0:1]
	v_mov_b64_e32 v[26:27], v[0:1]
	v_mov_b64_e32 v[28:29], v[0:1]
	v_mov_b64_e32 v[30:31], v[0:1]
	v_mov_b64_e32 v[32:33], v[0:1]
	v_mov_b64_e32 v[34:35], v[0:1]
	v_mov_b64_e32 v[36:37], v[0:1]
	v_mov_b64_e32 v[38:39], v[0:1]
	v_mov_b64_e32 v[40:41], v[0:1]
	v_mov_b64_e32 v[42:43], v[0:1]
	v_mov_b64_e32 v[44:45], v[0:1]
	v_mov_b64_e32 v[46:47], v[0:1]
	v_mov_b64_e32 v[48:49], v[0:1]
	v_mov_b64_e32 v[50:51], v[0:1]
	v_mov_b64_e32 v[52:53], v[0:1]
	v_mov_b64_e32 v[54:55], v[0:1]
	v_mov_b64_e32 v[56:57], v[0:1]
	v_mov_b64_e32 v[58:59], v[0:1]
	v_mov_b64_e32 v[60:61], v[0:1]
	v_mov_b64_e32 v[62:63], v[0:1]
	v_mov_b64_e32 v[64:65], v[0:1]
	v_mov_b64_e32 v[66:67], v[0:1]
	v_mov_b64_e32 v[68:69], v[0:1]
	v_mov_b64_e32 v[70:71], v[0:1]
	v_mov_b64_e32 v[72:73], v[0:1]
	v_mov_b64_e32 v[74:75], v[0:1]
	v_mov_b64_e32 v[76:77], v[0:1]
	v_mov_b64_e32 v[78:79], v[0:1]
	v_mov_b64_e32 v[80:81], v[0:1]
	v_mov_b64_e32 v[82:83], v[0:1]
	v_mov_b64_e32 v[84:85], v[0:1]
	v_mov_b64_e32 v[86:87], v[0:1]
	v_mov_b64_e32 v[88:89], v[0:1]
	v_mov_b64_e32 v[90:91], v[0:1]
	v_mov_b64_e32 v[92:93], v[0:1]
	v_mov_b64_e32 v[94:95], v[0:1]
	v_mov_b64_e32 v[96:97], v[0:1]
	v_mov_b64_e32 v[98:99], v[0:1]
	v_mov_b64_e32 v[100:101], v[0:1]
	v_mov_b64_e32 v[102:103], v[0:1]
	v_mov_b64_e32 v[104:105], v[0:1]
	v_mov_b64_e32 v[106:107], v[0:1]
	v_mov_b64_e32 v[108:109], v[0:1]
	v_mov_b64_e32 v[110:111], v[0:1]
	v_mov_b64_e32 v[112:113], v[0:1]
	v_mov_b64_e32 v[114:115], v[0:1]
	v_mov_b64_e32 v[116:117], v[0:1]
	v_mov_b64_e32 v[118:119], v[0:1]
	v_mov_b64_e32 v[120:121], v[0:1]
	v_mov_b64_e32 v[122:123], v[0:1]
	v_mov_b64_e32 v[124:125], v[0:1]
	v_mov_b64_e32 v[126:127], v[0:1]
	s_mov_b32 s10, 0
	s_waitcnt vmcnt(0)
	s_barrier
; template <class AL, class BL>
; DEV void gemm_ktile(Acc& acc, const char* A, const char* B, int wm, int wn, int lr, int lh, const AL& al, const BL& bl,
;                     int tid, int m0, int n0, int knext, char* nxt, R4& ra, R4& rb) {
;     ...
;   for (int ks = 0; ks < 4; ++ks) {
;     const int cur = ks & 1, nx = cur ^ 1;
;     if (ks < 3) {
; #pragma unroll
;       for (int i = 0; i < 4; ++i) a[nx][i] = *(const bf16x8*)(pa + 32 * i * LDSROW + (ks + 1) * 32);
; #pragma unroll
;       for (int j = 0; j < 2; ++j) b[nx][j] = *(const bf16x8*)(pb + 32 * j * LDSROW + (ks + 1) * 32);
;     }
;     __builtin_amdgcn_sched_barrier(0);
; #pragma unroll
;     for (int i = 0; i < 4; ++i)
; #pragma unroll
;       for (int j = 0; j < 2; ++j)
;         acc[i][j] = __builtin_amdgcn_mfma_f32_32x32x16_bf16(a[cur][i], b[cur][j], acc[i][j], 0, 0, 0);
;     __builtin_amdgcn_sched_barrier(0);
;     if (ks == 1) {
;       al.store(tid, nxt, ra);
;       bl.store(tid, nxt + TILE_BYTES, rb);
;       __builtin_amdgcn_sched_barrier(0);
;       ra = al.load(tid, m0, knext);
;       rb = bl.load(tid, n0, knext);
;       __builtin_amdgcn_sched_barrier(0);
;     }
; template <class AL, class BL>
; DEV void gemm_mainloop_p(Acc& acc, const AL& al, const BL& bl, int m0, int n0, int m0n, int n0n, int K, char* lds,
;                          GemmPipe& gp) {
;     ...
;   for (int kt = 0; kt < nk; ++kt) {
;     const char* cur = lds + (kt & 1) * 2 * TILE_BYTES;
;     char* nxt = lds + ((kt + 1) & 1) * 2 * TILE_BYTES;
;     const bool wrap = (kt + 2 >= nk);
;     const int kk = (wrap ? kt + 2 - nk : kt + 2) * BK;
;     const int mr = wrap ? m0n : m0, nr = wrap ? n0n : n0;
;     __builtin_amdgcn_sched_barrier(0);
;     gemm_ktile(acc, cur, cur + TILE_BYTES, wm, wn, lr, lh, al, bl, tid, mr, nr, kk, nxt, gp.ra, gp.rb);
;     __builtin_amdgcn_sched_barrier(0);
;     __syncthreads();
;   }
.Lp1b_kloop:
	s_cmp_lt_u32 s9, 0x4000
	s_cbranch_scc0 .Lp1b_d2
	s_add_u32 m0, s9, 0x8000
	s_nop 0
	global_load_lds_dwordx4 v128, s[14:15]
	s_add_u32 m0, m0, 0x400
	s_nop 0
	global_load_lds_dwordx4 v129, s[14:15]
	s_add_u32 m0, m0, 0x400
	s_nop 0
	global_load_lds_dwordx4 v130, s[14:15]
	s_add_u32 m0, m0, 0x400
	s_nop 0
	global_load_lds_dwordx4 v131, s[14:15]
	s_add_u32 m0, s9, 0x18000
	s_nop 0
	global_load_lds_dwordx4 v132, s[16:17]
	s_add_u32 m0, m0, 0x400
	s_nop 0
	global_load_lds_dwordx4 v133, s[16:17]
	s_add_u32 m0, m0, 0x400
	s_nop 0
	global_load_lds_dwordx4 v134, s[16:17]
	s_add_u32 m0, m0, 0x400
	s_nop 0
	global_load_lds_dwordx4 v135, s[16:17]
	s_add_u32 m0, s9, 0xc000
	s_nop 0
	global_load_lds_dwordx4 v136, s[14:15]
	s_add_u32 m0, m0, 0x400
	s_nop 0
	global_load_lds_dwordx4 v137, s[14:15]
	s_add_u32 m0, m0, 0x400
	s_nop 0
	global_load_lds_dwordx4 v138, s[14:15]
	s_add_u32 m0, m0, 0x400
	s_nop 0
	global_load_lds_dwordx4 v139, s[14:15]
	s_add_u32 m0, s9, 0x1c000
	s_nop 0
	global_load_lds_dwordx4 v140, s[16:17]
	s_add_u32 m0, m0, 0x400
	s_nop 0
	global_load_lds_dwordx4 v141, s[16:17]
	s_add_u32 m0, m0, 0x400
	s_nop 0
	global_load_lds_dwordx4 v142, s[16:17]
	s_add_u32 m0, m0, 0x400
	s_nop 0
	global_load_lds_dwordx4 v143, s[16:17]
.Lp1b_d2:
	s_add_u32 s14, s14, 0x80
	s_addc_u32 s15, s15, 0
	s_add_u32 s16, s16, 0x80
	s_addc_u32 s17, s17, 0
	ds_read_b128 v[166:169], v146
	ds_read_b128 v[170:173], v146 offset:2048
	ds_read_b128 v[174:177], v146 offset:4096
	ds_read_b128 v[178:181], v146 offset:6144
	ds_read_b128 v[222:225], v144
	ds_read_b128 v[226:229], v144 offset:2048
	ds_read_b128 v[230:233], v144 offset:4096
	ds_read_b128 v[234:237], v144 offset:6144
	ds_read_b128 v[238:241], v144 offset:8192
	ds_read_b128 v[198:201], v144 offset:10240
	ds_read_b128 v[152:155], v144 offset:12288
	ds_read_b128 v[156:159], v144 offset:14336
	ds_read_b128 v[182:185], v147
	ds_read_b128 v[186:189], v147 offset:2048
	ds_read_b128 v[190:193], v147 offset:4096
	ds_read_b128 v[194:197], v147 offset:6144
	s_waitcnt lgkmcnt(8)
	v_mfma_f32_16x16x32_bf16 v[0:3], v[166:169], v[222:225], v[0:3]
	v_mfma_f32_16x16x32_bf16 v[4:7], v[170:173], v[222:225], v[4:7]
	v_mfma_f32_16x16x32_bf16 v[8:11], v[174:177], v[222:225], v[8:11]
	v_mfma_f32_16x16x32_bf16 v[12:15], v[178:181], v[222:225], v[12:15]
	v_mfma_f32_16x16x32_bf16 v[16:19], v[166:169], v[226:229], v[16:19]
	v_mfma_f32_16x16x32_bf16 v[20:23], v[170:173], v[226:229], v[20:23]
	v_mfma_f32_16x16x32_bf16 v[24:27], v[174:177], v[226:229], v[24:27]
	v_mfma_f32_16x16x32_bf16 v[28:31], v[178:181], v[226:229], v[28:31]
	v_mfma_f32_16x16x32_bf16 v[32:35], v[166:169], v[230:233], v[32:35]
	v_mfma_f32_16x16x32_bf16 v[36:39], v[170:173], v[230:233], v[36:39]
	v_mfma_f32_16x16x32_bf16 v[40:43], v[174:177], v[230:233], v[40:43]
	v_mfma_f32_16x16x32_bf16 v[44:47], v[178:181], v[230:233], v[44:47]
	v_mfma_f32_16x16x32_bf16 v[48:51], v[166:169], v[234:237], v[48:51]
	v_mfma_f32_16x16x32_bf16 v[52:55], v[170:173], v[234:237], v[52:55]
	v_mfma_f32_16x16x32_bf16 v[56:59], v[174:177], v[234:237], v[56:59]
	v_mfma_f32_16x16x32_bf16 v[60:63], v[178:181], v[234:237], v[60:63]
	ds_read_b128 v[222:225], v145
	ds_read_b128 v[226:229], v145 offset:2048
	ds_read_b128 v[230:233], v145 offset:4096
	ds_read_b128 v[234:237], v145 offset:6144
	s_waitcnt lgkmcnt(8)
	v_mfma_f32_16x16x32_bf16 v[64:67], v[166:169], v[238:241], v[64:67]
	v_mfma_f32_16x16x32_bf16 v[68:71], v[170:173], v[238:241], v[68:71]
	v_mfma_f32_16x16x32_bf16 v[72:75], v[174:177], v[238:241], v[72:75]
	v_mfma_f32_16x16x32_bf16 v[76:79], v[178:181], v[238:241], v[76:79]
	v_mfma_f32_16x16x32_bf16 v[80:83], v[166:169], v[198:201], v[80:83]
	v_mfma_f32_16x16x32_bf16 v[84:87], v[170:173], v[198:201], v[84:87]
	v_mfma_f32_16x16x32_bf16 v[88:91], v[174:177], v[198:201], v[88:91]
	v_mfma_f32_16x16x32_bf16 v[92:95], v[178:181], v[198:201], v[92:95]
	v_mfma_f32_16x16x32_bf16 v[96:99], v[166:169], v[152:155], v[96:99]
	v_mfma_f32_16x16x32_bf16 v[100:103], v[170:173], v[152:155], v[100:103]
	v_mfma_f32_16x16x32_bf16 v[104:107], v[174:177], v[152:155], v[104:107]
	v_mfma_f32_16x16x32_bf16 v[108:111], v[178:181], v[152:155], v[108:111]
	v_mfma_f32_16x16x32_bf16 v[112:115], v[166:169], v[156:159], v[112:115]
	v_mfma_f32_16x16x32_bf16 v[116:119], v[170:173], v[156:159], v[116:119]
	v_mfma_f32_16x16x32_bf16 v[120:123], v[174:177], v[156:159], v[120:123]
	v_mfma_f32_16x16x32_bf16 v[124:127], v[178:181], v[156:159], v[124:127]
	ds_read_b128 v[238:241], v145 offset:8192
	ds_read_b128 v[198:201], v145 offset:10240
	ds_read_b128 v[152:155], v145 offset:12288
	ds_read_b128 v[156:159], v145 offset:14336
	s_waitcnt lgkmcnt(4)
	v_mfma_f32_16x16x32_bf16 v[0:3], v[182:185], v[222:225], v[0:3]
	v_mfma_f32_16x16x32_bf16 v[4:7], v[186:189], v[222:225], v[4:7]
	v_mfma_f32_16x16x32_bf16 v[8:11], v[190:193], v[222:225], v[8:11]
	v_mfma_f32_16x16x32_bf16 v[12:15], v[194:197], v[222:225], v[12:15]
	v_mfma_f32_16x16x32_bf16 v[16:19], v[182:185], v[226:229], v[16:19]
	v_mfma_f32_16x16x32_bf16 v[20:23], v[186:189], v[226:229], v[20:23]
	v_mfma_f32_16x16x32_bf16 v[24:27], v[190:193], v[226:229], v[24:27]
	v_mfma_f32_16x16x32_bf16 v[28:31], v[194:197], v[226:229], v[28:31]
	v_mfma_f32_16x16x32_bf16 v[32:35], v[182:185], v[230:233], v[32:35]
	v_mfma_f32_16x16x32_bf16 v[36:39], v[186:189], v[230:233], v[36:39]
	v_mfma_f32_16x16x32_bf16 v[40:43], v[190:193], v[230:233], v[40:43]
	v_mfma_f32_16x16x32_bf16 v[44:47], v[194:197], v[230:233], v[44:47]
	v_mfma_f32_16x16x32_bf16 v[48:51], v[182:185], v[234:237], v[48:51]
	v_mfma_f32_16x16x32_bf16 v[52:55], v[186:189], v[234:237], v[52:55]
	v_mfma_f32_16x16x32_bf16 v[56:59], v[190:193], v[234:237], v[56:59]
	v_mfma_f32_16x16x32_bf16 v[60:63], v[194:197], v[234:237], v[60:63]
	s_waitcnt lgkmcnt(0)
	v_mfma_f32_16x16x32_bf16 v[64:67], v[182:185], v[238:241], v[64:67]
	v_mfma_f32_16x16x32_bf16 v[68:71], v[186:189], v[238:241], v[68:71]
	v_mfma_f32_16x16x32_bf16 v[72:75], v[190:193], v[238:241], v[72:75]
	v_mfma_f32_16x16x32_bf16 v[76:79], v[194:197], v[238:241], v[76:79]
	v_mfma_f32_16x16x32_bf16 v[80:83], v[182:185], v[198:201], v[80:83]
	v_mfma_f32_16x16x32_bf16 v[84:87], v[186:189], v[198:201], v[84:87]
	v_mfma_f32_16x16x32_bf16 v[88:91], v[190:193], v[198:201], v[88:91]
	v_mfma_f32_16x16x32_bf16 v[92:95], v[194:197], v[198:201], v[92:95]
	v_mfma_f32_16x16x32_bf16 v[96:99], v[182:185], v[152:155], v[96:99]
	v_mfma_f32_16x16x32_bf16 v[100:103], v[186:189], v[152:155], v[100:103]
	v_mfma_f32_16x16x32_bf16 v[104:107], v[190:193], v[152:155], v[104:107]
	v_mfma_f32_16x16x32_bf16 v[108:111], v[194:197], v[152:155], v[108:111]
	v_mfma_f32_16x16x32_bf16 v[112:115], v[182:185], v[156:159], v[112:115]
	v_mfma_f32_16x16x32_bf16 v[116:119], v[186:189], v[156:159], v[116:119]
	v_mfma_f32_16x16x32_bf16 v[120:123], v[190:193], v[156:159], v[120:123]
	v_mfma_f32_16x16x32_bf16 v[124:127], v[194:197], v[156:159], v[124:127]
	s_waitcnt vmcnt(0)
	s_barrier
; template <class AL, class BL>
; DEV void gemm_ktile(Acc& acc, const char* A, const char* B, int wm, int wn, int lr, int lh, const AL& al, const BL& bl,
;                     int tid, int m0, int n0, int knext, char* nxt, R4& ra, R4& rb) {
;     ...
;   for (int ks = 0; ks < 4; ++ks) {
;     const int cur = ks & 1, nx = cur ^ 1;
;     if (ks < 3) {
; #pragma unroll
;       for (int i = 0; i < 4; ++i) a[nx][i] = *(const bf16x8*)(pa + 32 * i * LDSROW + (ks + 1) * 32);
; #pragma unroll
;       for (int j = 0; j < 2; ++j) b[nx][j] = *(const bf16x8*)(pb + 32 * j * LDSROW + (ks + 1) * 32);
;     }
;     __builtin_amdgcn_sched_barrier(0);
; #pragma unroll
;     for (int i = 0; i < 4; ++i)
; #pragma unroll
;       for (int j = 0; j < 2; ++j)
;         acc[i][j] = __builtin_amdgcn_mfma_f32_32x32x16_bf16(a[cur][i], b[cur][j], acc[i][j], 0, 0, 0);
;     __builtin_amdgcn_sched_barrier(0);
;     if (ks == 1) {
;       al.store(tid, nxt, ra);
;       bl.store(tid, nxt + TILE_BYTES, rb);
;       __builtin_amdgcn_sched_barrier(0);
;       ra = al.load(tid, m0, knext);
;       rb = bl.load(tid, n0, knext);
;       __builtin_amdgcn_sched_barrier(0);
;     }
; template <class AL, class BL>
; DEV void gemm_mainloop_p(Acc& acc, const AL& al, const BL& bl, int m0, int n0, int m0n, int n0n, int K, char* lds,
;                          GemmPipe& gp) {
;     ...
;   for (int kt = 0; kt < nk; ++kt) {
;     const char* cur = lds + (kt & 1) * 2 * TILE_BYTES;
;     char* nxt = lds + ((kt + 1) & 1) * 2 * TILE_BYTES;
;     const bool wrap = (kt + 2 >= nk);
;     const int kk = (wrap ? kt + 2 - nk : kt + 2) * BK;
;     const int mr = wrap ? m0n : m0, nr = wrap ? n0n : n0;
;     __builtin_amdgcn_sched_barrier(0);
;     gemm_ktile(acc, cur, cur + TILE_BYTES, wm, wn, lr, lh, al, bl, tid, mr, nr, kk, nxt, gp.ra, gp.rb);
;     __builtin_amdgcn_sched_barrier(0);
;     __syncthreads();
;   }
	s_cmp_eq_u32 s10, 7
	s_cbranch_scc1 .Lp1b_last
	s_cmp_lt_u32 s9, 0x4000
	s_cbranch_scc0 .Lp1b_d3
	s_add_u32 m0, s9, 0x0
	s_nop 0
	global_load_lds_dwordx4 v128, s[14:15]
	s_add_u32 m0, m0, 0x400
	s_nop 0
	global_load_lds_dwordx4 v129, s[14:15]
	s_add_u32 m0, m0, 0x400
	s_nop 0
	global_load_lds_dwordx4 v130, s[14:15]
	s_add_u32 m0, m0, 0x400
	s_nop 0
	global_load_lds_dwordx4 v131, s[14:15]
	s_add_u32 m0, s9, 0x10000
	s_nop 0
	global_load_lds_dwordx4 v132, s[16:17]
	s_add_u32 m0, m0, 0x400
	s_nop 0
	global_load_lds_dwordx4 v133, s[16:17]
	s_add_u32 m0, m0, 0x400
	s_nop 0
	global_load_lds_dwordx4 v134, s[16:17]
	s_add_u32 m0, m0, 0x400
	s_nop 0
	global_load_lds_dwordx4 v135, s[16:17]
	s_add_u32 m0, s9, 0x4000
	s_nop 0
	global_load_lds_dwordx4 v136, s[14:15]
	s_add_u32 m0, m0, 0x400
	s_nop 0
	global_load_lds_dwordx4 v137, s[14:15]
	s_add_u32 m0, m0, 0x400
	s_nop 0
	global_load_lds_dwordx4 v138, s[14:15]
	s_add_u32 m0, m0, 0x400
	s_nop 0
	global_load_lds_dwordx4 v139, s[14:15]
	s_add_u32 m0, s9, 0x14000
	s_nop 0
	global_load_lds_dwordx4 v140, s[16:17]
	s_add_u32 m0, m0, 0x400
	s_nop 0
	global_load_lds_dwordx4 v141, s[16:17]
	s_add_u32 m0, m0, 0x400
	s_nop 0
	global_load_lds_dwordx4 v142, s[16:17]
	s_add_u32 m0, m0, 0x400
	s_nop 0
	global_load_lds_dwordx4 v143, s[16:17]
.Lp1b_d3:
	s_add_u32 s14, s14, 0x80
	s_addc_u32 s15, s15, 0
	s_add_u32 s16, s16, 0x80
	s_addc_u32 s17, s17, 0
	ds_read_b128 v[166:169], v146 offset:32768
	ds_read_b128 v[170:173], v146 offset:34816
	ds_read_b128 v[174:177], v146 offset:36864
	ds_read_b128 v[178:181], v146 offset:38912
	ds_read_b128 v[222:225], v144 offset:32768
	ds_read_b128 v[226:229], v144 offset:34816
	ds_read_b128 v[230:233], v144 offset:36864
	ds_read_b128 v[234:237], v144 offset:38912
	ds_read_b128 v[238:241], v144 offset:40960
	ds_read_b128 v[198:201], v144 offset:43008
	ds_read_b128 v[152:155], v144 offset:45056
	ds_read_b128 v[156:159], v144 offset:47104
	ds_read_b128 v[182:185], v147 offset:32768
	ds_read_b128 v[186:189], v147 offset:34816
	ds_read_b128 v[190:193], v147 offset:36864
	ds_read_b128 v[194:197], v147 offset:38912
	s_waitcnt lgkmcnt(8)
	v_mfma_f32_16x16x32_bf16 v[0:3], v[166:169], v[222:225], v[0:3]
	v_mfma_f32_16x16x32_bf16 v[4:7], v[170:173], v[222:225], v[4:7]
	v_mfma_f32_16x16x32_bf16 v[8:11], v[174:177], v[222:225], v[8:11]
	v_mfma_f32_16x16x32_bf16 v[12:15], v[178:181], v[222:225], v[12:15]
	v_mfma_f32_16x16x32_bf16 v[16:19], v[166:169], v[226:229], v[16:19]
	v_mfma_f32_16x16x32_bf16 v[20:23], v[170:173], v[226:229], v[20:23]
	v_mfma_f32_16x16x32_bf16 v[24:27], v[174:177], v[226:229], v[24:27]
	v_mfma_f32_16x16x32_bf16 v[28:31], v[178:181], v[226:229], v[28:31]
	v_mfma_f32_16x16x32_bf16 v[32:35], v[166:169], v[230:233], v[32:35]
	v_mfma_f32_16x16x32_bf16 v[36:39], v[170:173], v[230:233], v[36:39]
	v_mfma_f32_16x16x32_bf16 v[40:43], v[174:177], v[230:233], v[40:43]
	v_mfma_f32_16x16x32_bf16 v[44:47], v[178:181], v[230:233], v[44:47]
	v_mfma_f32_16x16x32_bf16 v[48:51], v[166:169], v[234:237], v[48:51]
	v_mfma_f32_16x16x32_bf16 v[52:55], v[170:173], v[234:237], v[52:55]
	v_mfma_f32_16x16x32_bf16 v[56:59], v[174:177], v[234:237], v[56:59]
	v_mfma_f32_16x16x32_bf16 v[60:63], v[178:181], v[234:237], v[60:63]
	ds_read_b128 v[222:225], v145 offset:32768
	ds_read_b128 v[226:229], v145 offset:34816
	ds_read_b128 v[230:233], v145 offset:36864
	ds_read_b128 v[234:237], v145 offset:38912
	s_waitcnt lgkmcnt(8)
	v_mfma_f32_16x16x32_bf16 v[64:67], v[166:169], v[238:241], v[64:67]
	v_mfma_f32_16x16x32_bf16 v[68:71], v[170:173], v[238:241], v[68:71]
	v_mfma_f32_16x16x32_bf16 v[72:75], v[174:177], v[238:241], v[72:75]
	v_mfma_f32_16x16x32_bf16 v[76:79], v[178:181], v[238:241], v[76:79]
	v_mfma_f32_16x16x32_bf16 v[80:83], v[166:169], v[198:201], v[80:83]
	v_mfma_f32_16x16x32_bf16 v[84:87], v[170:173], v[198:201], v[84:87]
	v_mfma_f32_16x16x32_bf16 v[88:91], v[174:177], v[198:201], v[88:91]
	v_mfma_f32_16x16x32_bf16 v[92:95], v[178:181], v[198:201], v[92:95]
	v_mfma_f32_16x16x32_bf16 v[96:99], v[166:169], v[152:155], v[96:99]
	v_mfma_f32_16x16x32_bf16 v[100:103], v[170:173], v[152:155], v[100:103]
	v_mfma_f32_16x16x32_bf16 v[104:107], v[174:177], v[152:155], v[104:107]
	v_mfma_f32_16x16x32_bf16 v[108:111], v[178:181], v[152:155], v[108:111]
	v_mfma_f32_16x16x32_bf16 v[112:115], v[166:169], v[156:159], v[112:115]
	v_mfma_f32_16x16x32_bf16 v[116:119], v[170:173], v[156:159], v[116:119]
	v_mfma_f32_16x16x32_bf16 v[120:123], v[174:177], v[156:159], v[120:123]
	v_mfma_f32_16x16x32_bf16 v[124:127], v[178:181], v[156:159], v[124:127]
	ds_read_b128 v[238:241], v145 offset:40960
	ds_read_b128 v[198:201], v145 offset:43008
	ds_read_b128 v[152:155], v145 offset:45056
	ds_read_b128 v[156:159], v145 offset:47104
	s_waitcnt lgkmcnt(4)
	v_mfma_f32_16x16x32_bf16 v[0:3], v[182:185], v[222:225], v[0:3]
	v_mfma_f32_16x16x32_bf16 v[4:7], v[186:189], v[222:225], v[4:7]
	v_mfma_f32_16x16x32_bf16 v[8:11], v[190:193], v[222:225], v[8:11]
	v_mfma_f32_16x16x32_bf16 v[12:15], v[194:197], v[222:225], v[12:15]
	v_mfma_f32_16x16x32_bf16 v[16:19], v[182:185], v[226:229], v[16:19]
	v_mfma_f32_16x16x32_bf16 v[20:23], v[186:189], v[226:229], v[20:23]
	v_mfma_f32_16x16x32_bf16 v[24:27], v[190:193], v[226:229], v[24:27]
	v_mfma_f32_16x16x32_bf16 v[28:31], v[194:197], v[226:229], v[28:31]
	v_mfma_f32_16x16x32_bf16 v[32:35], v[182:185], v[230:233], v[32:35]
	v_mfma_f32_16x16x32_bf16 v[36:39], v[186:189], v[230:233], v[36:39]
	v_mfma_f32_16x16x32_bf16 v[40:43], v[190:193], v[230:233], v[40:43]
	v_mfma_f32_16x16x32_bf16 v[44:47], v[194:197], v[230:233], v[44:47]
	v_mfma_f32_16x16x32_bf16 v[48:51], v[182:185], v[234:237], v[48:51]
	v_mfma_f32_16x16x32_bf16 v[52:55], v[186:189], v[234:237], v[52:55]
	v_mfma_f32_16x16x32_bf16 v[56:59], v[190:193], v[234:237], v[56:59]
	v_mfma_f32_16x16x32_bf16 v[60:63], v[194:197], v[234:237], v[60:63]
	s_waitcnt lgkmcnt(0)
	v_mfma_f32_16x16x32_bf16 v[64:67], v[182:185], v[238:241], v[64:67]
	v_mfma_f32_16x16x32_bf16 v[68:71], v[186:189], v[238:241], v[68:71]
	v_mfma_f32_16x16x32_bf16 v[72:75], v[190:193], v[238:241], v[72:75]
	v_mfma_f32_16x16x32_bf16 v[76:79], v[194:197], v[238:241], v[76:79]
	v_mfma_f32_16x16x32_bf16 v[80:83], v[182:185], v[198:201], v[80:83]
	v_mfma_f32_16x16x32_bf16 v[84:87], v[186:189], v[198:201], v[84:87]
	v_mfma_f32_16x16x32_bf16 v[88:91], v[190:193], v[198:201], v[88:91]
	v_mfma_f32_16x16x32_bf16 v[92:95], v[194:197], v[198:201], v[92:95]
	v_mfma_f32_16x16x32_bf16 v[96:99], v[182:185], v[152:155], v[96:99]
	v_mfma_f32_16x16x32_bf16 v[100:103], v[186:189], v[152:155], v[100:103]
	v_mfma_f32_16x16x32_bf16 v[104:107], v[190:193], v[152:155], v[104:107]
	v_mfma_f32_16x16x32_bf16 v[108:111], v[194:197], v[152:155], v[108:111]
	v_mfma_f32_16x16x32_bf16 v[112:115], v[182:185], v[156:159], v[112:115]
	v_mfma_f32_16x16x32_bf16 v[116:119], v[186:189], v[156:159], v[116:119]
	v_mfma_f32_16x16x32_bf16 v[120:123], v[190:193], v[156:159], v[120:123]
	v_mfma_f32_16x16x32_bf16 v[124:127], v[194:197], v[156:159], v[124:127]
	s_add_i32 s10, s10, 1
	s_waitcnt vmcnt(0)
	s_barrier
; template <class AL, class BL>
; DEV void gemm_ktile(Acc& acc, const char* A, const char* B, int wm, int wn, int lr, int lh, const AL& al, const BL& bl,
;                     int tid, int m0, int n0, int knext, char* nxt, R4& ra, R4& rb) {
;     ...
;   for (int ks = 0; ks < 4; ++ks) {
;     const int cur = ks & 1, nx = cur ^ 1;
;     if (ks < 3) {
; #pragma unroll
;       for (int i = 0; i < 4; ++i) a[nx][i] = *(const bf16x8*)(pa + 32 * i * LDSROW + (ks + 1) * 32);
; #pragma unroll
;       for (int j = 0; j < 2; ++j) b[nx][j] = *(const bf16x8*)(pb + 32 * j * LDSROW + (ks + 1) * 32);
;     }
;     __builtin_amdgcn_sched_barrier(0);
; #pragma unroll
;     for (int i = 0; i < 4; ++i)
; #pragma unroll
;       for (int j = 0; j < 2; ++j)
;         acc[i][j] = __builtin_amdgcn_mfma_f32_32x32x16_bf16(a[cur][i], b[cur][j], acc[i][j], 0, 0, 0);
;     __builtin_amdgcn_sched_barrier(0);
	s_branch .Lp1b_kloop
.Lp1b_last:
	ds_read_b128 v[166:169], v146 offset:32768
	ds_read_b128 v[170:173], v146 offset:34816
	ds_read_b128 v[174:177], v146 offset:36864
	ds_read_b128 v[178:181], v146 offset:38912
	ds_read_b128 v[222:225], v144 offset:32768
	ds_read_b128 v[226:229], v144 offset:34816
	ds_read_b128 v[230:233], v144 offset:36864
	ds_read_b128 v[234:237], v144 offset:38912
	ds_read_b128 v[238:241], v144 offset:40960
	ds_read_b128 v[198:201], v144 offset:43008
	ds_read_b128 v[152:155], v144 offset:45056
	ds_read_b128 v[156:159], v144 offset:47104
	ds_read_b128 v[182:185], v147 offset:32768
	ds_read_b128 v[186:189], v147 offset:34816
	ds_read_b128 v[190:193], v147 offset:36864
	ds_read_b128 v[194:197], v147 offset:38912
	s_waitcnt lgkmcnt(8)
	v_mfma_f32_16x16x32_bf16 v[0:3], v[166:169], v[222:225], v[0:3]
	v_mfma_f32_16x16x32_bf16 v[4:7], v[170:173], v[222:225], v[4:7]
	v_mfma_f32_16x16x32_bf16 v[8:11], v[174:177], v[222:225], v[8:11]
	v_mfma_f32_16x16x32_bf16 v[12:15], v[178:181], v[222:225], v[12:15]
	v_mfma_f32_16x16x32_bf16 v[16:19], v[166:169], v[226:229], v[16:19]
	v_mfma_f32_16x16x32_bf16 v[20:23], v[170:173], v[226:229], v[20:23]
	v_mfma_f32_16x16x32_bf16 v[24:27], v[174:177], v[226:229], v[24:27]
	v_mfma_f32_16x16x32_bf16 v[28:31], v[178:181], v[226:229], v[28:31]
	v_mfma_f32_16x16x32_bf16 v[32:35], v[166:169], v[230:233], v[32:35]
	v_mfma_f32_16x16x32_bf16 v[36:39], v[170:173], v[230:233], v[36:39]
	v_mfma_f32_16x16x32_bf16 v[40:43], v[174:177], v[230:233], v[40:43]
	v_mfma_f32_16x16x32_bf16 v[44:47], v[178:181], v[230:233], v[44:47]
	v_mfma_f32_16x16x32_bf16 v[48:51], v[166:169], v[234:237], v[48:51]
	v_mfma_f32_16x16x32_bf16 v[52:55], v[170:173], v[234:237], v[52:55]
	v_mfma_f32_16x16x32_bf16 v[56:59], v[174:177], v[234:237], v[56:59]
	v_mfma_f32_16x16x32_bf16 v[60:63], v[178:181], v[234:237], v[60:63]
	ds_read_b128 v[222:225], v145 offset:32768
	ds_read_b128 v[226:229], v145 offset:34816
	ds_read_b128 v[230:233], v145 offset:36864
	ds_read_b128 v[234:237], v145 offset:38912
	s_waitcnt lgkmcnt(8)
	v_mfma_f32_16x16x32_bf16 v[64:67], v[166:169], v[238:241], v[64:67]
	v_mfma_f32_16x16x32_bf16 v[68:71], v[170:173], v[238:241], v[68:71]
	v_mfma_f32_16x16x32_bf16 v[72:75], v[174:177], v[238:241], v[72:75]
	v_mfma_f32_16x16x32_bf16 v[76:79], v[178:181], v[238:241], v[76:79]
	v_mfma_f32_16x16x32_bf16 v[80:83], v[166:169], v[198:201], v[80:83]
	v_mfma_f32_16x16x32_bf16 v[84:87], v[170:173], v[198:201], v[84:87]
	v_mfma_f32_16x16x32_bf16 v[88:91], v[174:177], v[198:201], v[88:91]
	v_mfma_f32_16x16x32_bf16 v[92:95], v[178:181], v[198:201], v[92:95]
	v_mfma_f32_16x16x32_bf16 v[96:99], v[166:169], v[152:155], v[96:99]
	v_mfma_f32_16x16x32_bf16 v[100:103], v[170:173], v[152:155], v[100:103]
	v_mfma_f32_16x16x32_bf16 v[104:107], v[174:177], v[152:155], v[104:107]
	v_mfma_f32_16x16x32_bf16 v[108:111], v[178:181], v[152:155], v[108:111]
	v_mfma_f32_16x16x32_bf16 v[112:115], v[166:169], v[156:159], v[112:115]
	v_mfma_f32_16x16x32_bf16 v[116:119], v[170:173], v[156:159], v[116:119]
	v_mfma_f32_16x16x32_bf16 v[120:123], v[174:177], v[156:159], v[120:123]
	v_mfma_f32_16x16x32_bf16 v[124:127], v[178:181], v[156:159], v[124:127]
	ds_read_b128 v[238:241], v145 offset:40960
	ds_read_b128 v[198:201], v145 offset:43008
	ds_read_b128 v[152:155], v145 offset:45056
	ds_read_b128 v[156:159], v145 offset:47104
	s_waitcnt lgkmcnt(4)
	v_mfma_f32_16x16x32_bf16 v[0:3], v[182:185], v[222:225], v[0:3]
	v_mfma_f32_16x16x32_bf16 v[4:7], v[186:189], v[222:225], v[4:7]
	v_mfma_f32_16x16x32_bf16 v[8:11], v[190:193], v[222:225], v[8:11]
	v_mfma_f32_16x16x32_bf16 v[12:15], v[194:197], v[222:225], v[12:15]
	v_mfma_f32_16x16x32_bf16 v[16:19], v[182:185], v[226:229], v[16:19]
	v_mfma_f32_16x16x32_bf16 v[20:23], v[186:189], v[226:229], v[20:23]
	v_mfma_f32_16x16x32_bf16 v[24:27], v[190:193], v[226:229], v[24:27]
	v_mfma_f32_16x16x32_bf16 v[28:31], v[194:197], v[226:229], v[28:31]
	v_mfma_f32_16x16x32_bf16 v[32:35], v[182:185], v[230:233], v[32:35]
	v_mfma_f32_16x16x32_bf16 v[36:39], v[186:189], v[230:233], v[36:39]
	v_mfma_f32_16x16x32_bf16 v[40:43], v[190:193], v[230:233], v[40:43]
	v_mfma_f32_16x16x32_bf16 v[44:47], v[194:197], v[230:233], v[44:47]
	v_mfma_f32_16x16x32_bf16 v[48:51], v[182:185], v[234:237], v[48:51]
	v_mfma_f32_16x16x32_bf16 v[52:55], v[186:189], v[234:237], v[52:55]
	v_mfma_f32_16x16x32_bf16 v[56:59], v[190:193], v[234:237], v[56:59]
	v_mfma_f32_16x16x32_bf16 v[60:63], v[194:197], v[234:237], v[60:63]
	s_waitcnt lgkmcnt(0)
	v_mfma_f32_16x16x32_bf16 v[64:67], v[182:185], v[238:241], v[64:67]
	v_mfma_f32_16x16x32_bf16 v[68:71], v[186:189], v[238:241], v[68:71]
	v_mfma_f32_16x16x32_bf16 v[72:75], v[190:193], v[238:241], v[72:75]
	v_mfma_f32_16x16x32_bf16 v[76:79], v[194:197], v[238:241], v[76:79]
	v_mfma_f32_16x16x32_bf16 v[80:83], v[182:185], v[198:201], v[80:83]
	v_mfma_f32_16x16x32_bf16 v[84:87], v[186:189], v[198:201], v[84:87]
	v_mfma_f32_16x16x32_bf16 v[88:91], v[190:193], v[198:201], v[88:91]
	v_mfma_f32_16x16x32_bf16 v[92:95], v[194:197], v[198:201], v[92:95]
	v_mfma_f32_16x16x32_bf16 v[96:99], v[182:185], v[152:155], v[96:99]
	v_mfma_f32_16x16x32_bf16 v[100:103], v[186:189], v[152:155], v[100:103]
	v_mfma_f32_16x16x32_bf16 v[104:107], v[190:193], v[152:155], v[104:107]
	v_mfma_f32_16x16x32_bf16 v[108:111], v[194:197], v[152:155], v[108:111]
	v_mfma_f32_16x16x32_bf16 v[112:115], v[182:185], v[156:159], v[112:115]
	v_mfma_f32_16x16x32_bf16 v[116:119], v[186:189], v[156:159], v[116:119]
	v_mfma_f32_16x16x32_bf16 v[120:123], v[190:193], v[156:159], v[120:123]
	v_mfma_f32_16x16x32_bf16 v[124:127], v[194:197], v[156:159], v[124:127]
	s_barrier
; DEV u16 f2bf(float f) { return (u16)(pack2(f, f) & 0xffffu); }
; template <class F>
; DEV void acc_foreach(Acc& acc, int m0, int n0, F f) {
;   asm volatile("s_nop 7\n\ts_nop 7\n\ts_nop 3" ::: "memory");
;   const int tid = tidx_full();
;   const int wave = tid >> 6, lane = tid & 63;
;   const int wm = (wave >> 2) * 128, wn = (wave & 3) * 64;
;   const int lr = lane & 31, lh = lane >> 5;
; #pragma unroll
;   for (int i = 0; i < 4; ++i)
; #pragma unroll
;     for (int j = 0; j < 2; ++j)
; #pragma unroll
;       for (int r = 0; r < 16; ++r) {
;         const int m = m0 + wm + 32 * i + (r & 3) + 8 * (r >> 2) + 4 * lh;
;         const int n = n0 + wn + 32 * j + lr;
;         float v = acc[i][j][r];
;         f(m, n, v);
;         acc[i][j][r] = v;
;       }
; }
; DEV void phase_p1(const Params& p, int g, char* smem) {
;     ...
;       if (!tile_map(iter, 6, 128, cm, tn)) break;
;       const bool more = tile_map(iter + 1, 6, 128, cmn, tnn);
;       if (!more) { cmn = cm; tnn = tn; }
;       Acc acc;
;       acc_zero(acc);
;       const int m0 = cm * 256, n0 = tn * 256;
;       RowLoader al{WinT, 1024}, bl{H, 1024};
;       gemm_mainloop_p(acc, al, bl, m0, n0, cmn * 256, tnn * 256, 1024, smem, gp);
;       gp.primed = more;
;       const int b = n0 / L, tb = n0 - b * L;
;       u16* dst = UHY + (size_t)b * 1536 * L + tb - n0;
;       acc_foreach(acc, m0, n0, [&](int m, int n, float& v) { dst[(size_t)m * L + n] = f2bf(v); });
	s_and_b64 vcc, exec, s[0:1]
	s_cbranch_vccz .Lp1b_nomore
	s_lshl_b32 s4, s12, 8
	s_lshl_b32 s5, s13, 8
	v_add_u32_e32 v128, s4, v150
	v_lshlrev_b32_e32 v128, 11, v128
	v_add_u32_e32 v128, v128, v151
	v_add_u32_e32 v129, 0x4000, v128
	v_add_u32_e32 v130, 0x8000, v128
	v_add_u32_e32 v131, 0xc000, v128
	v_xor_b32_e32 v129, 0x40, v129
	v_xor_b32_e32 v131, 0x40, v131
	v_add_u32_e32 v132, s5, v150
	v_lshlrev_b32_e32 v132, 11, v132
	v_add_u32_e32 v132, v132, v151
	v_add_u32_e32 v133, 0x4000, v132
	v_add_u32_e32 v134, 0x8000, v132
	v_add_u32_e32 v135, 0xc000, v132
	v_xor_b32_e32 v133, 0x40, v133
	v_xor_b32_e32 v135, 0x40, v135
	v_add_u32_e32 v136, 0x40000, v128
	v_add_u32_e32 v137, 0x40000, v129
	v_add_u32_e32 v138, 0x40000, v130
	v_add_u32_e32 v139, 0x40000, v131
	v_add_u32_e32 v140, 0x40000, v132
	v_add_u32_e32 v141, 0x40000, v133
	v_add_u32_e32 v142, 0x40000, v134
	v_add_u32_e32 v143, 0x40000, v135
	s_mov_b64 s[14:15], s[88:89]
	s_mov_b64 s[16:17], s[64:65]
	s_cmp_lt_u32 s9, 0x4000
	s_cbranch_scc0 .Lp1b_d4
	s_add_u32 m0, s9, 0x0
	s_nop 0
	global_load_lds_dwordx4 v128, s[14:15]
	s_add_u32 m0, m0, 0x400
	s_nop 0
	global_load_lds_dwordx4 v129, s[14:15]
	s_add_u32 m0, m0, 0x400
	s_nop 0
	global_load_lds_dwordx4 v130, s[14:15]
	s_add_u32 m0, m0, 0x400
	s_nop 0
	global_load_lds_dwordx4 v131, s[14:15]
	s_add_u32 m0, s9, 0x10000
	s_nop 0
	global_load_lds_dwordx4 v132, s[16:17]
	s_add_u32 m0, m0, 0x400
	s_nop 0
	global_load_lds_dwordx4 v133, s[16:17]
	s_add_u32 m0, m0, 0x400
	s_nop 0
	global_load_lds_dwordx4 v134, s[16:17]
	s_add_u32 m0, m0, 0x400
	s_nop 0
	global_load_lds_dwordx4 v135, s[16:17]
	s_add_u32 m0, s9, 0x4000
	s_nop 0
	global_load_lds_dwordx4 v136, s[14:15]
	s_add_u32 m0, m0, 0x400
	s_nop 0
	global_load_lds_dwordx4 v137, s[14:15]
	s_add_u32 m0, m0, 0x400
	s_nop 0
	global_load_lds_dwordx4 v138, s[14:15]
	s_add_u32 m0, m0, 0x400
	s_nop 0
	global_load_lds_dwordx4 v139, s[14:15]
	s_add_u32 m0, s9, 0x14000
	s_nop 0
	global_load_lds_dwordx4 v140, s[16:17]
	s_add_u32 m0, m0, 0x400
	s_nop 0
	global_load_lds_dwordx4 v141, s[16:17]
	s_add_u32 m0, m0, 0x400
	s_nop 0
	global_load_lds_dwordx4 v142, s[16:17]
	s_add_u32 m0, m0, 0x400
	s_nop 0
	global_load_lds_dwordx4 v143, s[16:17]
.Lp1b_d4:
.Lp1b_nomore:
	s_lshr_b32 s3, s2, s24
	s_lshl_b32 s4, s3, s24
	s_sub_u32 s4, s2, s4
	s_mul_i32 s5, s3, 0x600
	s_add_u32 s5, s5, s11
	s_add_u32 s12, s24, 1
	s_lshl_b32 s13, 8, s12
	s_nop 7
	s_nop 7
	s_nop 3
	v_and_b32_e32 v160, 63, v202
	v_lshrrev_b32_e32 v161, 6, v202
	v_and_b32_e32 v164, 3, v161
	v_lshlrev_b32_e32 v164, 13, v164
	v_add_u32_e32 v164, 0x8000, v164
	v_lshrrev_b32_e32 v160, 2, v161
	v_lshl_add_u32 v164, v160, 16, v164
	v_and_b32_e32 v160, 63, v202
	v_and_b32_e32 v166, 15, v160
	v_lshrrev_b32_e32 v167, 4, v160
	v_lshl_add_u32 v168, v166, 7, v164
	v_and_b32_e32 v169, 1, v167
	v_lshl_add_u32 v168, v169, 3, v168
	v_lshrrev_b32_e32 v167, 1, v167
	v_and_b32_e32 v166, 7, v166
	v_xor_b32_e32 v166, v166, v167
	v_lshlrev_b32_e32 v166, 4, v166
	v_add_u32_e32 v170, v168, v166
	v_xor_b32_e32 v167, 0x20, v166
	v_add_u32_e32 v171, v168, v167
	v_xor_b32_e32 v167, 0x40, v166
	v_add_u32_e32 v172, v168, v167
	v_xor_b32_e32 v167, 0x60, v166
	v_add_u32_e32 v173, v168, v167
	v_and_b32_e32 v166, 31, v160
	v_lshrrev_b32_e32 v167, 5, v160
	v_lshlrev_b32_e32 v168, 7, v166
	v_lshl_add_u32 v168, v167, 3, v168
	v_add_u32_e32 v168, v164, v168
	v_and_b32_e32 v166, 7, v166
	v_lshlrev_b32_e32 v166, 4, v166
	v_lshrrev_b32_e32 v166, 3, v160
	v_and_b32_e32 v167, 7, v160
	v_lshrrev_b32_e32 v169, 2, v161
	v_lshl_add_u32 v169, v169, 7, v166
	v_add_u32_e32 v169, s5, v169
	v_lshlrev_b32_e32 v169, s12, v169
	v_and_b32_e32 v168, 3, v161
	v_lshlrev_b32_e32 v168, 3, v168
	v_add_u32_e32 v168, v168, v167
	v_lshl_add_u32 v169, v168, 4, v169
	s_lshl_b32 s100, s4, 1
	v_add_u32_e32 v169, s100, v169
	v_xor_b32_e32 v167, v166, v167
	v_lshlrev_b32_e32 v167, 4, v167
	v_lshl_add_u32 v168, v166, 7, v167
	v_add_u32_e32 v168, v164, v168
	v_cvt_pk_bf16_f32 v0, v0, v1
	v_cvt_pk_bf16_f32 v1, v2, v3
	ds_write_b64 v170, v[0:1]
	v_cvt_pk_bf16_f32 v4, v4, v5
	v_cvt_pk_bf16_f32 v5, v6, v7
	ds_write_b64 v171, v[4:5]
	v_cvt_pk_bf16_f32 v8, v8, v9
	v_cvt_pk_bf16_f32 v9, v10, v11
	ds_write_b64 v172, v[8:9]
	v_cvt_pk_bf16_f32 v12, v12, v13
	v_cvt_pk_bf16_f32 v13, v14, v15
	ds_write_b64 v173, v[12:13]
	v_cvt_pk_bf16_f32 v16, v16, v17
	v_cvt_pk_bf16_f32 v17, v18, v19
	ds_write_b64 v170, v[16:17] offset:2048
	v_cvt_pk_bf16_f32 v20, v20, v21
	v_cvt_pk_bf16_f32 v21, v22, v23
	ds_write_b64 v171, v[20:21] offset:2048
	v_cvt_pk_bf16_f32 v24, v24, v25
	v_cvt_pk_bf16_f32 v25, v26, v27
	ds_write_b64 v172, v[24:25] offset:2048
	v_cvt_pk_bf16_f32 v28, v28, v29
	v_cvt_pk_bf16_f32 v29, v30, v31
	ds_write_b64 v173, v[28:29] offset:2048
	v_cvt_pk_bf16_f32 v32, v32, v33
	v_cvt_pk_bf16_f32 v33, v34, v35
	ds_write_b64 v170, v[32:33] offset:4096
	v_cvt_pk_bf16_f32 v36, v36, v37
	v_cvt_pk_bf16_f32 v37, v38, v39
	ds_write_b64 v171, v[36:37] offset:4096
	v_cvt_pk_bf16_f32 v40, v40, v41
	v_cvt_pk_bf16_f32 v41, v42, v43
	ds_write_b64 v172, v[40:41] offset:4096
	v_cvt_pk_bf16_f32 v44, v44, v45
	v_cvt_pk_bf16_f32 v45, v46, v47
	ds_write_b64 v173, v[44:45] offset:4096
	v_cvt_pk_bf16_f32 v48, v48, v49
	v_cvt_pk_bf16_f32 v49, v50, v51
	ds_write_b64 v170, v[48:49] offset:6144
	v_cvt_pk_bf16_f32 v52, v52, v53
	v_cvt_pk_bf16_f32 v53, v54, v55
	ds_write_b64 v171, v[52:53] offset:6144
	v_cvt_pk_bf16_f32 v56, v56, v57
	v_cvt_pk_bf16_f32 v57, v58, v59
	ds_write_b64 v172, v[56:57] offset:6144
	v_cvt_pk_bf16_f32 v60, v60, v61
	v_cvt_pk_bf16_f32 v61, v62, v63
	ds_write_b64 v173, v[60:61] offset:6144
	s_waitcnt lgkmcnt(0)
; DEV u16 f2bf(float f) { return (u16)(pack2(f, f) & 0xffffu); }
; template <class F>
; DEV void acc_foreach(Acc& acc, int m0, int n0, F f) {
;   asm volatile("s_nop 7\n\ts_nop 7\n\ts_nop 3" ::: "memory");
;   const int tid = tidx_full();
;   const int wave = tid >> 6, lane = tid & 63;
;   const int wm = (wave >> 2) * 128, wn = (wave & 3) * 64;
;   const int lr = lane & 31, lh = lane >> 5;
; #pragma unroll
;   for (int i = 0; i < 4; ++i)
; #pragma unroll
;     for (int j = 0; j < 2; ++j)
; #pragma unroll
;       for (int r = 0; r < 16; ++r) {
;         const int m = m0 + wm + 32 * i + (r & 3) + 8 * (r >> 2) + 4 * lh;
;         const int n = n0 + wn + 32 * j + lr;
;         float v = acc[i][j][r];
;         f(m, n, v);
;         acc[i][j][r] = v;
;       }
; }
; DEV void phase_p1(const Params& p, int g, char* smem) {
;     ...
;       const int b = n0 / L, tb = n0 - b * L;
;       u16* dst = UHY + (size_t)b * 1536 * L + tb - n0;
;       acc_foreach(acc, m0, n0, [&](int m, int n, float& v) { dst[(size_t)m * L + n] = f2bf(v); });
	ds_read_b128 v[32:35], v168
	ds_read_b128 v[36:39], v168 offset:1024
	ds_read_b128 v[40:43], v168 offset:2048
	ds_read_b128 v[44:47], v168 offset:3072
	ds_read_b128 v[48:51], v168 offset:4096
	ds_read_b128 v[52:55], v168 offset:5120
	ds_read_b128 v[56:59], v168 offset:6144
	ds_read_b128 v[60:63], v168 offset:7168
	s_waitcnt lgkmcnt(7)
	global_store_dwordx4 v169, v[32:35], s[74:75]
	v_add_u32_e32 v169, s13, v169
	s_waitcnt lgkmcnt(6)
	global_store_dwordx4 v169, v[36:39], s[74:75]
	v_add_u32_e32 v169, s13, v169
	s_waitcnt lgkmcnt(5)
	global_store_dwordx4 v169, v[40:43], s[74:75]
	v_add_u32_e32 v169, s13, v169
	s_waitcnt lgkmcnt(4)
	global_store_dwordx4 v169, v[44:47], s[74:75]
	v_add_u32_e32 v169, s13, v169
	s_waitcnt lgkmcnt(3)
	global_store_dwordx4 v169, v[48:51], s[74:75]
	v_add_u32_e32 v169, s13, v169
	s_waitcnt lgkmcnt(2)
	global_store_dwordx4 v169, v[52:55], s[74:75]
	v_add_u32_e32 v169, s13, v169
	s_waitcnt lgkmcnt(1)
	global_store_dwordx4 v169, v[56:59], s[74:75]
	v_add_u32_e32 v169, s13, v169
	s_waitcnt lgkmcnt(0)
	global_store_dwordx4 v169, v[60:63], s[74:75]
	v_add_u32_e32 v169, s13, v169
	v_cvt_pk_bf16_f32 v64, v64, v65
	v_cvt_pk_bf16_f32 v65, v66, v67
	ds_write_b64 v170, v[64:65]
	v_cvt_pk_bf16_f32 v68, v68, v69
	v_cvt_pk_bf16_f32 v69, v70, v71
	ds_write_b64 v171, v[68:69]
	v_cvt_pk_bf16_f32 v72, v72, v73
	v_cvt_pk_bf16_f32 v73, v74, v75
	ds_write_b64 v172, v[72:73]
	v_cvt_pk_bf16_f32 v76, v76, v77
	v_cvt_pk_bf16_f32 v77, v78, v79
	ds_write_b64 v173, v[76:77]
	v_cvt_pk_bf16_f32 v80, v80, v81
	v_cvt_pk_bf16_f32 v81, v82, v83
	ds_write_b64 v170, v[80:81] offset:2048
	v_cvt_pk_bf16_f32 v84, v84, v85
	v_cvt_pk_bf16_f32 v85, v86, v87
	ds_write_b64 v171, v[84:85] offset:2048
	v_cvt_pk_bf16_f32 v88, v88, v89
	v_cvt_pk_bf16_f32 v89, v90, v91
	ds_write_b64 v172, v[88:89] offset:2048
	v_cvt_pk_bf16_f32 v92, v92, v93
	v_cvt_pk_bf16_f32 v93, v94, v95
	ds_write_b64 v173, v[92:93] offset:2048
	v_cvt_pk_bf16_f32 v96, v96, v97
	v_cvt_pk_bf16_f32 v97, v98, v99
	ds_write_b64 v170, v[96:97] offset:4096
	v_cvt_pk_bf16_f32 v100, v100, v101
	v_cvt_pk_bf16_f32 v101, v102, v103
	ds_write_b64 v171, v[100:101] offset:4096
	v_cvt_pk_bf16_f32 v104, v104, v105
	v_cvt_pk_bf16_f32 v105, v106, v107
	ds_write_b64 v172, v[104:105] offset:4096
	v_cvt_pk_bf16_f32 v108, v108, v109
	v_cvt_pk_bf16_f32 v109, v110, v111
	ds_write_b64 v173, v[108:109] offset:4096
	v_cvt_pk_bf16_f32 v112, v112, v113
	v_cvt_pk_bf16_f32 v113, v114, v115
	ds_write_b64 v170, v[112:113] offset:6144
	v_cvt_pk_bf16_f32 v116, v116, v117
	v_cvt_pk_bf16_f32 v117, v118, v119
	ds_write_b64 v171, v[116:117] offset:6144
	v_cvt_pk_bf16_f32 v120, v120, v121
	v_cvt_pk_bf16_f32 v121, v122, v123
	ds_write_b64 v172, v[120:121] offset:6144
	v_cvt_pk_bf16_f32 v124, v124, v125
	v_cvt_pk_bf16_f32 v125, v126, v127
	ds_write_b64 v173, v[124:125] offset:6144
	s_waitcnt lgkmcnt(0)
	ds_read_b128 v[64:67], v168
	ds_read_b128 v[68:71], v168 offset:1024
	ds_read_b128 v[72:75], v168 offset:2048
	ds_read_b128 v[76:79], v168 offset:3072
	ds_read_b128 v[80:83], v168 offset:4096
	ds_read_b128 v[84:87], v168 offset:5120
	ds_read_b128 v[88:91], v168 offset:6144
	ds_read_b128 v[92:95], v168 offset:7168
	s_waitcnt lgkmcnt(7)
	global_store_dwordx4 v169, v[64:67], s[74:75]
	v_add_u32_e32 v169, s13, v169
	s_waitcnt lgkmcnt(6)
	global_store_dwordx4 v169, v[68:71], s[74:75]
	v_add_u32_e32 v169, s13, v169
	s_waitcnt lgkmcnt(5)
	global_store_dwordx4 v169, v[72:75], s[74:75]
	v_add_u32_e32 v169, s13, v169
	s_waitcnt lgkmcnt(4)
	global_store_dwordx4 v169, v[76:79], s[74:75]
	v_add_u32_e32 v169, s13, v169
	s_waitcnt lgkmcnt(3)
	global_store_dwordx4 v169, v[80:83], s[74:75]
	v_add_u32_e32 v169, s13, v169
	s_waitcnt lgkmcnt(2)
	global_store_dwordx4 v169, v[84:87], s[74:75]
	v_add_u32_e32 v169, s13, v169
	s_waitcnt lgkmcnt(1)
	global_store_dwordx4 v169, v[88:91], s[74:75]
	v_add_u32_e32 v169, s13, v169
	s_waitcnt lgkmcnt(0)
	s_barrier
	global_store_dwordx4 v169, v[92:95], s[74:75]
	v_add_u32_e32 v169, s13, v169
	s_mov_b64 s[4:5], 0
	s_branch .LBB0_544

; template <class AL, class BL>
; DEV void gemm_mainloop_p(Acc& acc, const AL& al, const BL& bl, int m0, int n0, int m0n, int n0n, int K, char* lds,
;                          GemmPipe& gp) {
;     ...
;   if (!gp.primed) {
;     gp.ra = al.load(tid, m0, 0);
;     gp.rb = bl.load(tid, n0, 0);
;     __syncthreads();
;     al.store(tid, lds, gp.ra);
;     bl.store(tid, lds + TILE_BYTES, gp.rb);
;     gp.ra = al.load(tid, m0, BK);
;     gp.rb = bl.load(tid, n0, BK);
;     __syncthreads();
;   }
; DEV void phase_ff1(const Params& p, int g, char* smem) {
;     ...
;   GemmPipe gp;
;   gp.primed = false;
;   for (int iter = 0;; ++iter) {
;     int mt, nt, mtn, ntn;
;     if (!tile_map(iter, 128, 16, mt, nt)) break;
;     const bool more = tile_map(iter + 1, 128, 16, mtn, ntn);
;     if (!more) { mtn = mt; ntn = nt; }
;     const int m0 = mt * 256, n0 = nt * 256;
;     Acc acc;
;     acc_zero(acc);
;     RowLoader al{H2, 1024}, bl{W, 1024};
;     gemm_mainloop_p(acc, al, bl, m0, n0, mtn * 256, ntn * 256, 1024, smem, gp);
.LBB0_1126:
	v_readlane_b32 s18, v249, 48
	v_readlane_b32 s19, v249, 49
	v_readlane_b32 s20, v251, 25
	v_readlane_b32 s21, v251, 26
	s_and_b64 vcc, exec, s[2:3]
	s_lshl_b32 s5, s9, 8
	s_lshl_b32 s4, s10, 8
	v_lshrrev_b32_e32 v149, 6, v202
	v_and_b32_e32 v148, 63, v202
	s_nop 0
	v_readfirstlane_b32 s13, v149
	v_lshrrev_b32_e32 v150, 3, v148
	v_lshl_add_u32 v150, v149, 5, v150
	v_and_b32_e32 v151, 7, v148
	v_lshrrev_b32_e32 v128, 4, v148
	v_xor_b32_e32 v151, v128, v151
	v_lshlrev_b32_e32 v151, 4, v151
	s_lshl_b32 s13, s13, 12
	v_add_u32_e32 v128, s5, v150
	v_lshlrev_b32_e32 v128, 11, v128
	v_add_u32_e32 v128, v128, v151
	v_add_u32_e32 v129, 0x4000, v128
	v_add_u32_e32 v130, 0x8000, v128
	v_add_u32_e32 v131, 0xc000, v128
	v_xor_b32_e32 v129, 0x40, v129
	v_xor_b32_e32 v131, 0x40, v131
	v_add_u32_e32 v132, s4, v150
	v_lshlrev_b32_e32 v132, 11, v132
	v_add_u32_e32 v132, v132, v151
	v_add_u32_e32 v133, 0x4000, v132
	v_add_u32_e32 v134, 0x8000, v132
	v_add_u32_e32 v135, 0xc000, v132
	v_xor_b32_e32 v133, 0x40, v133
	v_xor_b32_e32 v135, 0x40, v135
	v_add_u32_e32 v136, 0x40000, v128
	v_add_u32_e32 v137, 0x40000, v129
	v_add_u32_e32 v138, 0x40000, v130
	v_add_u32_e32 v139, 0x40000, v131
	v_add_u32_e32 v140, 0x40000, v132
	v_add_u32_e32 v141, 0x40000, v133
	v_add_u32_e32 v142, 0x40000, v134
	v_add_u32_e32 v143, 0x40000, v135
	v_lshrrev_b32_e32 v161, 6, v202
	v_and_b32_e32 v160, 63, v202
	v_bfe_u32 v242, v160, 1, 3
	v_lshrrev_b32_e32 v243, 4, v160
	v_xor_b32_e32 v242, v242, v243
	v_lshlrev_b32_e32 v242, 4, v242
	v_and_b32_e32 v243, 15, v160
	v_lshlrev_b32_e32 v243, 7, v243
	v_lshrrev_b32_e32 v144, 2, v161
	v_lshl_add_u32 v144, v144, 14, v243
	v_and_b32_e32 v146, 3, v161
	v_lshl_add_u32 v146, v146, 13, v243
	v_add_u32_e32 v146, 0x10000, v146
	v_xor_b32_e32 v145, 0x40, v242
	v_add_u32_e32 v145, v144, v145
	v_add_u32_e32 v144, v144, v242
	v_xor_b32_e32 v147, 0x40, v242
	v_add_u32_e32 v147, v146, v147
	v_add_u32_e32 v146, v146, v242
	s_mov_b64 s[22:23], s[18:19]
	s_mov_b64 s[14:15], s[20:21]
	s_cbranch_vccnz .Lff1_primed
	s_cmp_lt_u32 s13, 0x4000
	s_cbranch_scc0 .Lff1_d1
	s_add_u32 m0, s13, 0x0
	s_nop 0
	global_load_lds_dwordx4 v128, s[22:23]
	s_add_u32 m0, m0, 0x400
	s_nop 0
	global_load_lds_dwordx4 v129, s[22:23]
	s_add_u32 m0, m0, 0x400
	s_nop 0
	global_load_lds_dwordx4 v130, s[22:23]
	s_add_u32 m0, m0, 0x400
	s_nop 0
	global_load_lds_dwordx4 v131, s[22:23]
	s_add_u32 m0, s13, 0x10000
	s_nop 0
	global_load_lds_dwordx4 v132, s[14:15]
	s_add_u32 m0, m0, 0x400
	s_nop 0
	global_load_lds_dwordx4 v133, s[14:15]
	s_add_u32 m0, m0, 0x400
	s_nop 0
	global_load_lds_dwordx4 v134, s[14:15]
	s_add_u32 m0, m0, 0x400
	s_nop 0
	global_load_lds_dwordx4 v135, s[14:15]
	s_add_u32 m0, s13, 0x4000
	s_nop 0
	global_load_lds_dwordx4 v136, s[22:23]
	s_add_u32 m0, m0, 0x400
	s_nop 0
	global_load_lds_dwordx4 v137, s[22:23]
	s_add_u32 m0, m0, 0x400
	s_nop 0
	global_load_lds_dwordx4 v138, s[22:23]
	s_add_u32 m0, m0, 0x400
	s_nop 0
	global_load_lds_dwordx4 v139, s[22:23]
	s_add_u32 m0, s13, 0x14000
	s_nop 0
	global_load_lds_dwordx4 v140, s[14:15]
	s_add_u32 m0, m0, 0x400
	s_nop 0
	global_load_lds_dwordx4 v141, s[14:15]
	s_add_u32 m0, m0, 0x400
	s_nop 0
	global_load_lds_dwordx4 v142, s[14:15]
	s_add_u32 m0, m0, 0x400
	s_nop 0
	global_load_lds_dwordx4 v143, s[14:15]
.Lff1_d1:
.Lff1_primed:
	s_add_u32 s22, s22, 0x80
	s_addc_u32 s23, s23, 0
	s_add_u32 s14, s14, 0x80
	s_addc_u32 s15, s15, 0
	v_mov_b32_e32 v0, 0
	v_mov_b32_e32 v1, 0
	v_mov_b64_e32 v[2:3], v[0:1]
	v_mov_b64_e32 v[4:5], v[0:1]
	v_mov_b64_e32 v[6:7], v[0:1]
	v_mov_b64_e32 v[8:9], v[0:1]
	v_mov_b64_e32 v[10:11], v[0:1]
	v_mov_b64_e32 v[12:13], v[0:1]
	v_mov_b64_e32 v[14:15], v[0:1]
	v_mov_b64_e32 v[16:17], v[0:1]
	v_mov_b64_e32 v[18:19], v[0:1]
	v_mov_b64_e32 v[20:21], v[0:1]
	v_mov_b64_e32 v[22:23], v[0:1]
	v_mov_b64_e32 v[24:25], v[0:1]
	v_mov_b64_e32 v[26:27], v[0:1]
	v_mov_b64_e32 v[28:29], v[0:1]
	v_mov_b64_e32 v[30:31], v[0:1]
	v_mov_b64_e32 v[32:33], v[0:1]
	v_mov_b64_e32 v[34:35], v[0:1]
	v_mov_b64_e32 v[36:37], v[0:1]
	v_mov_b64_e32 v[38:39], v[0:1]
	v_mov_b64_e32 v[40:41], v[0:1]
	v_mov_b64_e32 v[42:43], v[0:1]
	v_mov_b64_e32 v[44:45], v[0:1]
	v_mov_b64_e32 v[46:47], v[0:1]
	v_mov_b64_e32 v[48:49], v[0:1]
	v_mov_b64_e32 v[50:51], v[0:1]
	v_mov_b64_e32 v[52:53], v[0:1]
	v_mov_b64_e32 v[54:55], v[0:1]
	v_mov_b64_e32 v[56:57], v[0:1]
	v_mov_b64_e32 v[58:59], v[0:1]
	v_mov_b64_e32 v[60:61], v[0:1]
	v_mov_b64_e32 v[62:63], v[0:1]
	v_mov_b64_e32 v[64:65], v[0:1]
	v_mov_b64_e32 v[66:67], v[0:1]
	v_mov_b64_e32 v[68:69], v[0:1]
	v_mov_b64_e32 v[70:71], v[0:1]
	v_mov_b64_e32 v[72:73], v[0:1]
	v_mov_b64_e32 v[74:75], v[0:1]
	v_mov_b64_e32 v[76:77], v[0:1]
	v_mov_b64_e32 v[78:79], v[0:1]
	v_mov_b64_e32 v[80:81], v[0:1]
	v_mov_b64_e32 v[82:83], v[0:1]
	v_mov_b64_e32 v[84:85], v[0:1]
	v_mov_b64_e32 v[86:87], v[0:1]
	v_mov_b64_e32 v[88:89], v[0:1]
	v_mov_b64_e32 v[90:91], v[0:1]
	v_mov_b64_e32 v[92:93], v[0:1]
	v_mov_b64_e32 v[94:95], v[0:1]
	v_mov_b64_e32 v[96:97], v[0:1]
	v_mov_b64_e32 v[98:99], v[0:1]
	v_mov_b64_e32 v[100:101], v[0:1]
	v_mov_b64_e32 v[102:103], v[0:1]
	v_mov_b64_e32 v[104:105], v[0:1]
	v_mov_b64_e32 v[106:107], v[0:1]
	v_mov_b64_e32 v[108:109], v[0:1]
	v_mov_b64_e32 v[110:111], v[0:1]
	v_mov_b64_e32 v[112:113], v[0:1]
	v_mov_b64_e32 v[114:115], v[0:1]
	v_mov_b64_e32 v[116:117], v[0:1]
	v_mov_b64_e32 v[118:119], v[0:1]
	v_mov_b64_e32 v[120:121], v[0:1]
	v_mov_b64_e32 v[122:123], v[0:1]
	v_mov_b64_e32 v[124:125], v[0:1]
	v_mov_b64_e32 v[126:127], v[0:1]
	s_mov_b32 s17, 0
	s_waitcnt vmcnt(0)
	s_barrier
; template <class AL, class BL>
; DEV void gemm_ktile(Acc& acc, const char* A, const char* B, int wm, int wn, int lr, int lh, const AL& al, const BL& bl,
;                     int tid, int m0, int n0, int knext, char* nxt, R4& ra, R4& rb) {
;     ...
;   for (int ks = 0; ks < 4; ++ks) {
;     const int cur = ks & 1, nx = cur ^ 1;
;     if (ks < 3) {
; #pragma unroll
;       for (int i = 0; i < 4; ++i) a[nx][i] = *(const bf16x8*)(pa + 32 * i * LDSROW + (ks + 1) * 32);
; #pragma unroll
;       for (int j = 0; j < 2; ++j) b[nx][j] = *(const bf16x8*)(pb + 32 * j * LDSROW + (ks + 1) * 32);
;     }
;     __builtin_amdgcn_sched_barrier(0);
; #pragma unroll
;     for (int i = 0; i < 4; ++i)
; #pragma unroll
;       for (int j = 0; j < 2; ++j)
;         acc[i][j] = __builtin_amdgcn_mfma_f32_32x32x16_bf16(a[cur][i], b[cur][j], acc[i][j], 0, 0, 0);
;     __builtin_amdgcn_sched_barrier(0);
;     if (ks == 1) {
;       al.store(tid, nxt, ra);
;       bl.store(tid, nxt + TILE_BYTES, rb);
;       __builtin_amdgcn_sched_barrier(0);
;       ra = al.load(tid, m0, knext);
;       rb = bl.load(tid, n0, knext);
;       __builtin_amdgcn_sched_barrier(0);
;     }
; template <class AL, class BL>
; DEV void gemm_mainloop_p(Acc& acc, const AL& al, const BL& bl, int m0, int n0, int m0n, int n0n, int K, char* lds,
;                          GemmPipe& gp) {
;     ...
;   for (int kt = 0; kt < nk; ++kt) {
;     const char* cur = lds + (kt & 1) * 2 * TILE_BYTES;
;     char* nxt = lds + ((kt + 1) & 1) * 2 * TILE_BYTES;
;     const bool wrap = (kt + 2 >= nk);
;     const int kk = (wrap ? kt + 2 - nk : kt + 2) * BK;
;     const int mr = wrap ? m0n : m0, nr = wrap ? n0n : n0;
;     __builtin_amdgcn_sched_barrier(0);
;     gemm_ktile(acc, cur, cur + TILE_BYTES, wm, wn, lr, lh, al, bl, tid, mr, nr, kk, nxt, gp.ra, gp.rb);
;     __builtin_amdgcn_sched_barrier(0);
;     __syncthreads();
;   }
.Lff1_kloop:
	s_cmp_lt_u32 s13, 0x4000
	s_cbranch_scc0 .Lff1_d2
	s_add_u32 m0, s13, 0x8000
	s_nop 0
	global_load_lds_dwordx4 v128, s[22:23]
	s_add_u32 m0, m0, 0x400
	s_nop 0
	global_load_lds_dwordx4 v129, s[22:23]
	s_add_u32 m0, m0, 0x400
	s_nop 0
	global_load_lds_dwordx4 v130, s[22:23]
	s_add_u32 m0, m0, 0x400
	s_nop 0
	global_load_lds_dwordx4 v131, s[22:23]
	s_add_u32 m0, s13, 0x18000
	s_nop 0
	global_load_lds_dwordx4 v132, s[14:15]
	s_add_u32 m0, m0, 0x400
	s_nop 0
	global_load_lds_dwordx4 v133, s[14:15]
	s_add_u32 m0, m0, 0x400
	s_nop 0
	global_load_lds_dwordx4 v134, s[14:15]
	s_add_u32 m0, m0, 0x400
	s_nop 0
	global_load_lds_dwordx4 v135, s[14:15]
	s_add_u32 m0, s13, 0xc000
	s_nop 0
	global_load_lds_dwordx4 v136, s[22:23]
	s_add_u32 m0, m0, 0x400
	s_nop 0
	global_load_lds_dwordx4 v137, s[22:23]
	s_add_u32 m0, m0, 0x400
	s_nop 0
	global_load_lds_dwordx4 v138, s[22:23]
	s_add_u32 m0, m0, 0x400
	s_nop 0
	global_load_lds_dwordx4 v139, s[22:23]
	s_add_u32 m0, s13, 0x1c000
	s_nop 0
	global_load_lds_dwordx4 v140, s[14:15]
	s_add_u32 m0, m0, 0x400
	s_nop 0
	global_load_lds_dwordx4 v141, s[14:15]
	s_add_u32 m0, m0, 0x400
	s_nop 0
	global_load_lds_dwordx4 v142, s[14:15]
	s_add_u32 m0, m0, 0x400
	s_nop 0
	global_load_lds_dwordx4 v143, s[14:15]
.Lff1_d2:
	s_add_u32 s22, s22, 0x80
	s_addc_u32 s23, s23, 0
	s_add_u32 s14, s14, 0x80
	s_addc_u32 s15, s15, 0
	ds_read_b128 v[166:169], v146
	ds_read_b128 v[170:173], v146 offset:2048
	ds_read_b128 v[174:177], v146 offset:4096
	ds_read_b128 v[178:181], v146 offset:6144
	ds_read_b128 v[222:225], v144
	ds_read_b128 v[226:229], v144 offset:2048
	ds_read_b128 v[230:233], v144 offset:4096
	ds_read_b128 v[234:237], v144 offset:6144
	ds_read_b128 v[238:241], v144 offset:8192
	ds_read_b128 v[198:201], v144 offset:10240
	ds_read_b128 v[152:155], v144 offset:12288
	ds_read_b128 v[156:159], v144 offset:14336
	ds_read_b128 v[182:185], v147
	ds_read_b128 v[186:189], v147 offset:2048
	ds_read_b128 v[190:193], v147 offset:4096
	ds_read_b128 v[194:197], v147 offset:6144
	s_waitcnt lgkmcnt(8)
	v_mfma_f32_16x16x32_bf16 v[0:3], v[166:169], v[222:225], v[0:3]
	v_mfma_f32_16x16x32_bf16 v[4:7], v[170:173], v[222:225], v[4:7]
	v_mfma_f32_16x16x32_bf16 v[8:11], v[174:177], v[222:225], v[8:11]
	v_mfma_f32_16x16x32_bf16 v[12:15], v[178:181], v[222:225], v[12:15]
	v_mfma_f32_16x16x32_bf16 v[16:19], v[166:169], v[226:229], v[16:19]
	v_mfma_f32_16x16x32_bf16 v[20:23], v[170:173], v[226:229], v[20:23]
	v_mfma_f32_16x16x32_bf16 v[24:27], v[174:177], v[226:229], v[24:27]
	v_mfma_f32_16x16x32_bf16 v[28:31], v[178:181], v[226:229], v[28:31]
	v_mfma_f32_16x16x32_bf16 v[32:35], v[166:169], v[230:233], v[32:35]
	v_mfma_f32_16x16x32_bf16 v[36:39], v[170:173], v[230:233], v[36:39]
	v_mfma_f32_16x16x32_bf16 v[40:43], v[174:177], v[230:233], v[40:43]
	v_mfma_f32_16x16x32_bf16 v[44:47], v[178:181], v[230:233], v[44:47]
	v_mfma_f32_16x16x32_bf16 v[48:51], v[166:169], v[234:237], v[48:51]
	v_mfma_f32_16x16x32_bf16 v[52:55], v[170:173], v[234:237], v[52:55]
	v_mfma_f32_16x16x32_bf16 v[56:59], v[174:177], v[234:237], v[56:59]
	v_mfma_f32_16x16x32_bf16 v[60:63], v[178:181], v[234:237], v[60:63]
	ds_read_b128 v[222:225], v145
	ds_read_b128 v[226:229], v145 offset:2048
	ds_read_b128 v[230:233], v145 offset:4096
	ds_read_b128 v[234:237], v145 offset:6144
	s_waitcnt lgkmcnt(8)
	v_mfma_f32_16x16x32_bf16 v[64:67], v[166:169], v[238:241], v[64:67]
	v_mfma_f32_16x16x32_bf16 v[68:71], v[170:173], v[238:241], v[68:71]
	v_mfma_f32_16x16x32_bf16 v[72:75], v[174:177], v[238:241], v[72:75]
	v_mfma_f32_16x16x32_bf16 v[76:79], v[178:181], v[238:241], v[76:79]
	v_mfma_f32_16x16x32_bf16 v[80:83], v[166:169], v[198:201], v[80:83]
	v_mfma_f32_16x16x32_bf16 v[84:87], v[170:173], v[198:201], v[84:87]
	v_mfma_f32_16x16x32_bf16 v[88:91], v[174:177], v[198:201], v[88:91]
	v_mfma_f32_16x16x32_bf16 v[92:95], v[178:181], v[198:201], v[92:95]
	v_mfma_f32_16x16x32_bf16 v[96:99], v[166:169], v[152:155], v[96:99]
	v_mfma_f32_16x16x32_bf16 v[100:103], v[170:173], v[152:155], v[100:103]
	v_mfma_f32_16x16x32_bf16 v[104:107], v[174:177], v[152:155], v[104:107]
	v_mfma_f32_16x16x32_bf16 v[108:111], v[178:181], v[152:155], v[108:111]
	v_mfma_f32_16x16x32_bf16 v[112:115], v[166:169], v[156:159], v[112:115]
	v_mfma_f32_16x16x32_bf16 v[116:119], v[170:173], v[156:159], v[116:119]
	v_mfma_f32_16x16x32_bf16 v[120:123], v[174:177], v[156:159], v[120:123]
	v_mfma_f32_16x16x32_bf16 v[124:127], v[178:181], v[156:159], v[124:127]
	ds_read_b128 v[238:241], v145 offset:8192
	ds_read_b128 v[198:201], v145 offset:10240
	ds_read_b128 v[152:155], v145 offset:12288
	ds_read_b128 v[156:159], v145 offset:14336
	s_waitcnt lgkmcnt(4)
	v_mfma_f32_16x16x32_bf16 v[0:3], v[182:185], v[222:225], v[0:3]
	v_mfma_f32_16x16x32_bf16 v[4:7], v[186:189], v[222:225], v[4:7]
	v_mfma_f32_16x16x32_bf16 v[8:11], v[190:193], v[222:225], v[8:11]
	v_mfma_f32_16x16x32_bf16 v[12:15], v[194:197], v[222:225], v[12:15]
	v_mfma_f32_16x16x32_bf16 v[16:19], v[182:185], v[226:229], v[16:19]
	v_mfma_f32_16x16x32_bf16 v[20:23], v[186:189], v[226:229], v[20:23]
	v_mfma_f32_16x16x32_bf16 v[24:27], v[190:193], v[226:229], v[24:27]
	v_mfma_f32_16x16x32_bf16 v[28:31], v[194:197], v[226:229], v[28:31]
	v_mfma_f32_16x16x32_bf16 v[32:35], v[182:185], v[230:233], v[32:35]
	v_mfma_f32_16x16x32_bf16 v[36:39], v[186:189], v[230:233], v[36:39]
	v_mfma_f32_16x16x32_bf16 v[40:43], v[190:193], v[230:233], v[40:43]
	v_mfma_f32_16x16x32_bf16 v[44:47], v[194:197], v[230:233], v[44:47]
	v_mfma_f32_16x16x32_bf16 v[48:51], v[182:185], v[234:237], v[48:51]
	v_mfma_f32_16x16x32_bf16 v[52:55], v[186:189], v[234:237], v[52:55]
	v_mfma_f32_16x16x32_bf16 v[56:59], v[190:193], v[234:237], v[56:59]
	v_mfma_f32_16x16x32_bf16 v[60:63], v[194:197], v[234:237], v[60:63]
	s_waitcnt lgkmcnt(0)
	v_mfma_f32_16x16x32_bf16 v[64:67], v[182:185], v[238:241], v[64:67]
	v_mfma_f32_16x16x32_bf16 v[68:71], v[186:189], v[238:241], v[68:71]
	v_mfma_f32_16x16x32_bf16 v[72:75], v[190:193], v[238:241], v[72:75]
	v_mfma_f32_16x16x32_bf16 v[76:79], v[194:197], v[238:241], v[76:79]
	v_mfma_f32_16x16x32_bf16 v[80:83], v[182:185], v[198:201], v[80:83]
	v_mfma_f32_16x16x32_bf16 v[84:87], v[186:189], v[198:201], v[84:87]
	v_mfma_f32_16x16x32_bf16 v[88:91], v[190:193], v[198:201], v[88:91]
	v_mfma_f32_16x16x32_bf16 v[92:95], v[194:197], v[198:201], v[92:95]
	v_mfma_f32_16x16x32_bf16 v[96:99], v[182:185], v[152:155], v[96:99]
	v_mfma_f32_16x16x32_bf16 v[100:103], v[186:189], v[152:155], v[100:103]
	v_mfma_f32_16x16x32_bf16 v[104:107], v[190:193], v[152:155], v[104:107]
	v_mfma_f32_16x16x32_bf16 v[108:111], v[194:197], v[152:155], v[108:111]
	v_mfma_f32_16x16x32_bf16 v[112:115], v[182:185], v[156:159], v[112:115]
	v_mfma_f32_16x16x32_bf16 v[116:119], v[186:189], v[156:159], v[116:119]
	v_mfma_f32_16x16x32_bf16 v[120:123], v[190:193], v[156:159], v[120:123]
	v_mfma_f32_16x16x32_bf16 v[124:127], v[194:197], v[156:159], v[124:127]
	s_waitcnt vmcnt(0)
	s_barrier
; template <class AL, class BL>
; DEV void gemm_ktile(Acc& acc, const char* A, const char* B, int wm, int wn, int lr, int lh, const AL& al, const BL& bl,
;                     int tid, int m0, int n0, int knext, char* nxt, R4& ra, R4& rb) {
;     ...
;   for (int ks = 0; ks < 4; ++ks) {
;     const int cur = ks & 1, nx = cur ^ 1;
;     if (ks < 3) {
; #pragma unroll
;       for (int i = 0; i < 4; ++i) a[nx][i] = *(const bf16x8*)(pa + 32 * i * LDSROW + (ks + 1) * 32);
; #pragma unroll
;       for (int j = 0; j < 2; ++j) b[nx][j] = *(const bf16x8*)(pb + 32 * j * LDSROW + (ks + 1) * 32);
;     }
;     __builtin_amdgcn_sched_barrier(0);
; #pragma unroll
;     for (int i = 0; i < 4; ++i)
; #pragma unroll
;       for (int j = 0; j < 2; ++j)
;         acc[i][j] = __builtin_amdgcn_mfma_f32_32x32x16_bf16(a[cur][i], b[cur][j], acc[i][j], 0, 0, 0);
;     __builtin_amdgcn_sched_barrier(0);
;     if (ks == 1) {
;       al.store(tid, nxt, ra);
;       bl.store(tid, nxt + TILE_BYTES, rb);
;       __builtin_amdgcn_sched_barrier(0);
;       ra = al.load(tid, m0, knext);
;       rb = bl.load(tid, n0, knext);
;       __builtin_amdgcn_sched_barrier(0);
;     }
; template <class AL, class BL>
; DEV void gemm_mainloop_p(Acc& acc, const AL& al, const BL& bl, int m0, int n0, int m0n, int n0n, int K, char* lds,
;                          GemmPipe& gp) {
;     ...
;   for (int kt = 0; kt < nk; ++kt) {
;     const char* cur = lds + (kt & 1) * 2 * TILE_BYTES;
;     char* nxt = lds + ((kt + 1) & 1) * 2 * TILE_BYTES;
;     const bool wrap = (kt + 2 >= nk);
;     const int kk = (wrap ? kt + 2 - nk : kt + 2) * BK;
;     const int mr = wrap ? m0n : m0, nr = wrap ? n0n : n0;
;     __builtin_amdgcn_sched_barrier(0);
;     gemm_ktile(acc, cur, cur + TILE_BYTES, wm, wn, lr, lh, al, bl, tid, mr, nr, kk, nxt, gp.ra, gp.rb);
;     __builtin_amdgcn_sched_barrier(0);
;     __syncthreads();
;   }
	s_cmp_eq_u32 s17, 7
	s_cbranch_scc1 .Lff1_last
	s_cmp_lt_u32 s13, 0x4000
	s_cbranch_scc0 .Lff1_d3
	s_add_u32 m0, s13, 0x0
	s_nop 0
	global_load_lds_dwordx4 v128, s[22:23]
	s_add_u32 m0, m0, 0x400
	s_nop 0
	global_load_lds_dwordx4 v129, s[22:23]
	s_add_u32 m0, m0, 0x400
	s_nop 0
	global_load_lds_dwordx4 v130, s[22:23]
	s_add_u32 m0, m0, 0x400
	s_nop 0
	global_load_lds_dwordx4 v131, s[22:23]
	s_add_u32 m0, s13, 0x10000
	s_nop 0
	global_load_lds_dwordx4 v132, s[14:15]
	s_add_u32 m0, m0, 0x400
	s_nop 0
	global_load_lds_dwordx4 v133, s[14:15]
	s_add_u32 m0, m0, 0x400
	s_nop 0
	global_load_lds_dwordx4 v134, s[14:15]
	s_add_u32 m0, m0, 0x400
	s_nop 0
	global_load_lds_dwordx4 v135, s[14:15]
	s_add_u32 m0, s13, 0x4000
	s_nop 0
	global_load_lds_dwordx4 v136, s[22:23]
	s_add_u32 m0, m0, 0x400
	s_nop 0
	global_load_lds_dwordx4 v137, s[22:23]
	s_add_u32 m0, m0, 0x400
	s_nop 0
	global_load_lds_dwordx4 v138, s[22:23]
	s_add_u32 m0, m0, 0x400
	s_nop 0
	global_load_lds_dwordx4 v139, s[22:23]
	s_add_u32 m0, s13, 0x14000
	s_nop 0
	global_load_lds_dwordx4 v140, s[14:15]
	s_add_u32 m0, m0, 0x400
	s_nop 0
	global_load_lds_dwordx4 v141, s[14:15]
	s_add_u32 m0, m0, 0x400
	s_nop 0
	global_load_lds_dwordx4 v142, s[14:15]
	s_add_u32 m0, m0, 0x400
	s_nop 0
	global_load_lds_dwordx4 v143, s[14:15]
.Lff1_d3:
	s_add_u32 s22, s22, 0x80
	s_addc_u32 s23, s23, 0
	s_add_u32 s14, s14, 0x80
	s_addc_u32 s15, s15, 0
	ds_read_b128 v[166:169], v146 offset:32768
	ds_read_b128 v[170:173], v146 offset:34816
	ds_read_b128 v[174:177], v146 offset:36864
	ds_read_b128 v[178:181], v146 offset:38912
	ds_read_b128 v[222:225], v144 offset:32768
	ds_read_b128 v[226:229], v144 offset:34816
	ds_read_b128 v[230:233], v144 offset:36864
	ds_read_b128 v[234:237], v144 offset:38912
	ds_read_b128 v[238:241], v144 offset:40960
	ds_read_b128 v[198:201], v144 offset:43008
	ds_read_b128 v[152:155], v144 offset:45056
	ds_read_b128 v[156:159], v144 offset:47104
	ds_read_b128 v[182:185], v147 offset:32768
	ds_read_b128 v[186:189], v147 offset:34816
	ds_read_b128 v[190:193], v147 offset:36864
	ds_read_b128 v[194:197], v147 offset:38912
	s_waitcnt lgkmcnt(8)
	v_mfma_f32_16x16x32_bf16 v[0:3], v[166:169], v[222:225], v[0:3]
	v_mfma_f32_16x16x32_bf16 v[4:7], v[170:173], v[222:225], v[4:7]
	v_mfma_f32_16x16x32_bf16 v[8:11], v[174:177], v[222:225], v[8:11]
	v_mfma_f32_16x16x32_bf16 v[12:15], v[178:181], v[222:225], v[12:15]
	v_mfma_f32_16x16x32_bf16 v[16:19], v[166:169], v[226:229], v[16:19]
	v_mfma_f32_16x16x32_bf16 v[20:23], v[170:173], v[226:229], v[20:23]
	v_mfma_f32_16x16x32_bf16 v[24:27], v[174:177], v[226:229], v[24:27]
	v_mfma_f32_16x16x32_bf16 v[28:31], v[178:181], v[226:229], v[28:31]
	v_mfma_f32_16x16x32_bf16 v[32:35], v[166:169], v[230:233], v[32:35]
	v_mfma_f32_16x16x32_bf16 v[36:39], v[170:173], v[230:233], v[36:39]
	v_mfma_f32_16x16x32_bf16 v[40:43], v[174:177], v[230:233], v[40:43]
	v_mfma_f32_16x16x32_bf16 v[44:47], v[178:181], v[230:233], v[44:47]
	v_mfma_f32_16x16x32_bf16 v[48:51], v[166:169], v[234:237], v[48:51]
	v_mfma_f32_16x16x32_bf16 v[52:55], v[170:173], v[234:237], v[52:55]
	v_mfma_f32_16x16x32_bf16 v[56:59], v[174:177], v[234:237], v[56:59]
	v_mfma_f32_16x16x32_bf16 v[60:63], v[178:181], v[234:237], v[60:63]
	ds_read_b128 v[222:225], v145 offset:32768
	ds_read_b128 v[226:229], v145 offset:34816
	ds_read_b128 v[230:233], v145 offset:36864
	ds_read_b128 v[234:237], v145 offset:38912
	s_waitcnt lgkmcnt(8)
	v_mfma_f32_16x16x32_bf16 v[64:67], v[166:169], v[238:241], v[64:67]
	v_mfma_f32_16x16x32_bf16 v[68:71], v[170:173], v[238:241], v[68:71]
	v_mfma_f32_16x16x32_bf16 v[72:75], v[174:177], v[238:241], v[72:75]
	v_mfma_f32_16x16x32_bf16 v[76:79], v[178:181], v[238:241], v[76:79]
	v_mfma_f32_16x16x32_bf16 v[80:83], v[166:169], v[198:201], v[80:83]
	v_mfma_f32_16x16x32_bf16 v[84:87], v[170:173], v[198:201], v[84:87]
	v_mfma_f32_16x16x32_bf16 v[88:91], v[174:177], v[198:201], v[88:91]
	v_mfma_f32_16x16x32_bf16 v[92:95], v[178:181], v[198:201], v[92:95]
	v_mfma_f32_16x16x32_bf16 v[96:99], v[166:169], v[152:155], v[96:99]
	v_mfma_f32_16x16x32_bf16 v[100:103], v[170:173], v[152:155], v[100:103]
	v_mfma_f32_16x16x32_bf16 v[104:107], v[174:177], v[152:155], v[104:107]
	v_mfma_f32_16x16x32_bf16 v[108:111], v[178:181], v[152:155], v[108:111]
	v_mfma_f32_16x16x32_bf16 v[112:115], v[166:169], v[156:159], v[112:115]
	v_mfma_f32_16x16x32_bf16 v[116:119], v[170:173], v[156:159], v[116:119]
	v_mfma_f32_16x16x32_bf16 v[120:123], v[174:177], v[156:159], v[120:123]
	v_mfma_f32_16x16x32_bf16 v[124:127], v[178:181], v[156:159], v[124:127]
	ds_read_b128 v[238:241], v145 offset:40960
	ds_read_b128 v[198:201], v145 offset:43008
	ds_read_b128 v[152:155], v145 offset:45056
	ds_read_b128 v[156:159], v145 offset:47104
	s_waitcnt lgkmcnt(4)
	v_mfma_f32_16x16x32_bf16 v[0:3], v[182:185], v[222:225], v[0:3]
	v_mfma_f32_16x16x32_bf16 v[4:7], v[186:189], v[222:225], v[4:7]
	v_mfma_f32_16x16x32_bf16 v[8:11], v[190:193], v[222:225], v[8:11]
	v_mfma_f32_16x16x32_bf16 v[12:15], v[194:197], v[222:225], v[12:15]
	v_mfma_f32_16x16x32_bf16 v[16:19], v[182:185], v[226:229], v[16:19]
	v_mfma_f32_16x16x32_bf16 v[20:23], v[186:189], v[226:229], v[20:23]
	v_mfma_f32_16x16x32_bf16 v[24:27], v[190:193], v[226:229], v[24:27]
	v_mfma_f32_16x16x32_bf16 v[28:31], v[194:197], v[226:229], v[28:31]
	v_mfma_f32_16x16x32_bf16 v[32:35], v[182:185], v[230:233], v[32:35]
	v_mfma_f32_16x16x32_bf16 v[36:39], v[186:189], v[230:233], v[36:39]
	v_mfma_f32_16x16x32_bf16 v[40:43], v[190:193], v[230:233], v[40:43]
	v_mfma_f32_16x16x32_bf16 v[44:47], v[194:197], v[230:233], v[44:47]
	v_mfma_f32_16x16x32_bf16 v[48:51], v[182:185], v[234:237], v[48:51]
	v_mfma_f32_16x16x32_bf16 v[52:55], v[186:189], v[234:237], v[52:55]
	v_mfma_f32_16x16x32_bf16 v[56:59], v[190:193], v[234:237], v[56:59]
	v_mfma_f32_16x16x32_bf16 v[60:63], v[194:197], v[234:237], v[60:63]
	s_waitcnt lgkmcnt(0)
	v_mfma_f32_16x16x32_bf16 v[64:67], v[182:185], v[238:241], v[64:67]
	v_mfma_f32_16x16x32_bf16 v[68:71], v[186:189], v[238:241], v[68:71]
	v_mfma_f32_16x16x32_bf16 v[72:75], v[190:193], v[238:241], v[72:75]
	v_mfma_f32_16x16x32_bf16 v[76:79], v[194:197], v[238:241], v[76:79]
	v_mfma_f32_16x16x32_bf16 v[80:83], v[182:185], v[198:201], v[80:83]
	v_mfma_f32_16x16x32_bf16 v[84:87], v[186:189], v[198:201], v[84:87]
	v_mfma_f32_16x16x32_bf16 v[88:91], v[190:193], v[198:201], v[88:91]
	v_mfma_f32_16x16x32_bf16 v[92:95], v[194:197], v[198:201], v[92:95]
	v_mfma_f32_16x16x32_bf16 v[96:99], v[182:185], v[152:155], v[96:99]
	v_mfma_f32_16x16x32_bf16 v[100:103], v[186:189], v[152:155], v[100:103]
	v_mfma_f32_16x16x32_bf16 v[104:107], v[190:193], v[152:155], v[104:107]
	v_mfma_f32_16x16x32_bf16 v[108:111], v[194:197], v[152:155], v[108:111]
	v_mfma_f32_16x16x32_bf16 v[112:115], v[182:185], v[156:159], v[112:115]
	v_mfma_f32_16x16x32_bf16 v[116:119], v[186:189], v[156:159], v[116:119]
	v_mfma_f32_16x16x32_bf16 v[120:123], v[190:193], v[156:159], v[120:123]
	v_mfma_f32_16x16x32_bf16 v[124:127], v[194:197], v[156:159], v[124:127]
	s_add_i32 s17, s17, 1
	s_waitcnt vmcnt(0)
	s_barrier
; template <class AL, class BL>
; DEV void gemm_ktile(Acc& acc, const char* A, const char* B, int wm, int wn, int lr, int lh, const AL& al, const BL& bl,
;                     int tid, int m0, int n0, int knext, char* nxt, R4& ra, R4& rb) {
;     ...
;   for (int ks = 0; ks < 4; ++ks) {
;     const int cur = ks & 1, nx = cur ^ 1;
;     if (ks < 3) {
; #pragma unroll
;       for (int i = 0; i < 4; ++i) a[nx][i] = *(const bf16x8*)(pa + 32 * i * LDSROW + (ks + 1) * 32);
; #pragma unroll
;       for (int j = 0; j < 2; ++j) b[nx][j] = *(const bf16x8*)(pb + 32 * j * LDSROW + (ks + 1) * 32);
;     }
;     __builtin_amdgcn_sched_barrier(0);
; #pragma unroll
;     for (int i = 0; i < 4; ++i)
; #pragma unroll
;       for (int j = 0; j < 2; ++j)
;         acc[i][j] = __builtin_amdgcn_mfma_f32_32x32x16_bf16(a[cur][i], b[cur][j], acc[i][j], 0, 0, 0);
;     __builtin_amdgcn_sched_barrier(0);
	s_branch .Lff1_kloop
.Lff1_last:
	ds_read_b128 v[166:169], v146 offset:32768
	ds_read_b128 v[170:173], v146 offset:34816
	ds_read_b128 v[174:177], v146 offset:36864
	ds_read_b128 v[178:181], v146 offset:38912
	ds_read_b128 v[222:225], v144 offset:32768
	ds_read_b128 v[226:229], v144 offset:34816
	ds_read_b128 v[230:233], v144 offset:36864
	ds_read_b128 v[234:237], v144 offset:38912
	ds_read_b128 v[238:241], v144 offset:40960
	ds_read_b128 v[198:201], v144 offset:43008
	ds_read_b128 v[152:155], v144 offset:45056
	ds_read_b128 v[156:159], v144 offset:47104
	ds_read_b128 v[182:185], v147 offset:32768
	ds_read_b128 v[186:189], v147 offset:34816
	ds_read_b128 v[190:193], v147 offset:36864
	ds_read_b128 v[194:197], v147 offset:38912
	s_waitcnt lgkmcnt(8)
	v_mfma_f32_16x16x32_bf16 v[0:3], v[166:169], v[222:225], v[0:3]
	v_mfma_f32_16x16x32_bf16 v[4:7], v[170:173], v[222:225], v[4:7]
	v_mfma_f32_16x16x32_bf16 v[8:11], v[174:177], v[222:225], v[8:11]
	v_mfma_f32_16x16x32_bf16 v[12:15], v[178:181], v[222:225], v[12:15]
	v_mfma_f32_16x16x32_bf16 v[16:19], v[166:169], v[226:229], v[16:19]
	v_mfma_f32_16x16x32_bf16 v[20:23], v[170:173], v[226:229], v[20:23]
	v_mfma_f32_16x16x32_bf16 v[24:27], v[174:177], v[226:229], v[24:27]
	v_mfma_f32_16x16x32_bf16 v[28:31], v[178:181], v[226:229], v[28:31]
	v_mfma_f32_16x16x32_bf16 v[32:35], v[166:169], v[230:233], v[32:35]
	v_mfma_f32_16x16x32_bf16 v[36:39], v[170:173], v[230:233], v[36:39]
	v_mfma_f32_16x16x32_bf16 v[40:43], v[174:177], v[230:233], v[40:43]
	v_mfma_f32_16x16x32_bf16 v[44:47], v[178:181], v[230:233], v[44:47]
	v_mfma_f32_16x16x32_bf16 v[48:51], v[166:169], v[234:237], v[48:51]
	v_mfma_f32_16x16x32_bf16 v[52:55], v[170:173], v[234:237], v[52:55]
	v_mfma_f32_16x16x32_bf16 v[56:59], v[174:177], v[234:237], v[56:59]
	v_mfma_f32_16x16x32_bf16 v[60:63], v[178:181], v[234:237], v[60:63]
	ds_read_b128 v[222:225], v145 offset:32768
	ds_read_b128 v[226:229], v145 offset:34816
	ds_read_b128 v[230:233], v145 offset:36864
	ds_read_b128 v[234:237], v145 offset:38912
	s_waitcnt lgkmcnt(8)
	v_mfma_f32_16x16x32_bf16 v[64:67], v[166:169], v[238:241], v[64:67]
	v_mfma_f32_16x16x32_bf16 v[68:71], v[170:173], v[238:241], v[68:71]
	v_mfma_f32_16x16x32_bf16 v[72:75], v[174:177], v[238:241], v[72:75]
	v_mfma_f32_16x16x32_bf16 v[76:79], v[178:181], v[238:241], v[76:79]
	v_mfma_f32_16x16x32_bf16 v[80:83], v[166:169], v[198:201], v[80:83]
	v_mfma_f32_16x16x32_bf16 v[84:87], v[170:173], v[198:201], v[84:87]
	v_mfma_f32_16x16x32_bf16 v[88:91], v[174:177], v[198:201], v[88:91]
	v_mfma_f32_16x16x32_bf16 v[92:95], v[178:181], v[198:201], v[92:95]
	v_mfma_f32_16x16x32_bf16 v[96:99], v[166:169], v[152:155], v[96:99]
	v_mfma_f32_16x16x32_bf16 v[100:103], v[170:173], v[152:155], v[100:103]
	v_mfma_f32_16x16x32_bf16 v[104:107], v[174:177], v[152:155], v[104:107]
	v_mfma_f32_16x16x32_bf16 v[108:111], v[178:181], v[152:155], v[108:111]
	v_mfma_f32_16x16x32_bf16 v[112:115], v[166:169], v[156:159], v[112:115]
	v_mfma_f32_16x16x32_bf16 v[116:119], v[170:173], v[156:159], v[116:119]
	v_mfma_f32_16x16x32_bf16 v[120:123], v[174:177], v[156:159], v[120:123]
	v_mfma_f32_16x16x32_bf16 v[124:127], v[178:181], v[156:159], v[124:127]
	ds_read_b128 v[238:241], v145 offset:40960
	ds_read_b128 v[198:201], v145 offset:43008
	ds_read_b128 v[152:155], v145 offset:45056
	ds_read_b128 v[156:159], v145 offset:47104
	s_waitcnt lgkmcnt(4)
	v_mfma_f32_16x16x32_bf16 v[0:3], v[182:185], v[222:225], v[0:3]
	v_mfma_f32_16x16x32_bf16 v[4:7], v[186:189], v[222:225], v[4:7]
	v_mfma_f32_16x16x32_bf16 v[8:11], v[190:193], v[222:225], v[8:11]
	v_mfma_f32_16x16x32_bf16 v[12:15], v[194:197], v[222:225], v[12:15]
	v_mfma_f32_16x16x32_bf16 v[16:19], v[182:185], v[226:229], v[16:19]
	v_mfma_f32_16x16x32_bf16 v[20:23], v[186:189], v[226:229], v[20:23]
	v_mfma_f32_16x16x32_bf16 v[24:27], v[190:193], v[226:229], v[24:27]
	v_mfma_f32_16x16x32_bf16 v[28:31], v[194:197], v[226:229], v[28:31]
	v_mfma_f32_16x16x32_bf16 v[32:35], v[182:185], v[230:233], v[32:35]
	v_mfma_f32_16x16x32_bf16 v[36:39], v[186:189], v[230:233], v[36:39]
	v_mfma_f32_16x16x32_bf16 v[40:43], v[190:193], v[230:233], v[40:43]
	v_mfma_f32_16x16x32_bf16 v[44:47], v[194:197], v[230:233], v[44:47]
	v_mfma_f32_16x16x32_bf16 v[48:51], v[182:185], v[234:237], v[48:51]
	v_mfma_f32_16x16x32_bf16 v[52:55], v[186:189], v[234:237], v[52:55]
	v_mfma_f32_16x16x32_bf16 v[56:59], v[190:193], v[234:237], v[56:59]
	v_mfma_f32_16x16x32_bf16 v[60:63], v[194:197], v[234:237], v[60:63]
	s_waitcnt lgkmcnt(0)
	v_mfma_f32_16x16x32_bf16 v[64:67], v[182:185], v[238:241], v[64:67]
	v_mfma_f32_16x16x32_bf16 v[68:71], v[186:189], v[238:241], v[68:71]
	v_mfma_f32_16x16x32_bf16 v[72:75], v[190:193], v[238:241], v[72:75]
	v_mfma_f32_16x16x32_bf16 v[76:79], v[194:197], v[238:241], v[76:79]
	v_mfma_f32_16x16x32_bf16 v[80:83], v[182:185], v[198:201], v[80:83]
	v_mfma_f32_16x16x32_bf16 v[84:87], v[186:189], v[198:201], v[84:87]
	v_mfma_f32_16x16x32_bf16 v[88:91], v[190:193], v[198:201], v[88:91]
	v_mfma_f32_16x16x32_bf16 v[92:95], v[194:197], v[198:201], v[92:95]
	v_mfma_f32_16x16x32_bf16 v[96:99], v[182:185], v[152:155], v[96:99]
	v_mfma_f32_16x16x32_bf16 v[100:103], v[186:189], v[152:155], v[100:103]
	v_mfma_f32_16x16x32_bf16 v[104:107], v[190:193], v[152:155], v[104:107]
	v_mfma_f32_16x16x32_bf16 v[108:111], v[194:197], v[152:155], v[108:111]
	v_mfma_f32_16x16x32_bf16 v[112:115], v[182:185], v[156:159], v[112:115]
	v_mfma_f32_16x16x32_bf16 v[116:119], v[186:189], v[156:159], v[116:119]
	v_mfma_f32_16x16x32_bf16 v[120:123], v[190:193], v[156:159], v[120:123]
	v_mfma_f32_16x16x32_bf16 v[124:127], v[194:197], v[156:159], v[124:127]
	s_barrier
; DEV u16 f2bf(float f) { return (u16)(pack2(f, f) & 0xffffu); }
; template <class F>
; DEV void acc_foreach(Acc& acc, int m0, int n0, F f) {
;   asm volatile("s_nop 7\n\ts_nop 7\n\ts_nop 3" ::: "memory");
;   const int tid = tidx_full();
;   const int wave = tid >> 6, lane = tid & 63;
;   const int wm = (wave >> 2) * 128, wn = (wave & 3) * 64;
;   const int lr = lane & 31, lh = lane >> 5;
; #pragma unroll
;   for (int i = 0; i < 4; ++i)
; #pragma unroll
;     for (int j = 0; j < 2; ++j)
; #pragma unroll
;       for (int r = 0; r < 16; ++r) {
;         const int m = m0 + wm + 32 * i + (r & 3) + 8 * (r >> 2) + 4 * lh;
;         const int n = n0 + wn + 32 * j + lr;
;         float v = acc[i][j][r];
;         f(m, n, v);
;         acc[i][j][r] = v;
;       }
; }
; DEV void phase_ff1(const Params& p, int g, char* smem) {
;     ...
;     const bool more = tile_map(iter + 1, 128, 16, mtn, ntn);
;     if (!more) { mtn = mt; ntn = nt; }
;     const int m0 = mt * 256, n0 = nt * 256;
;     Acc acc;
;     acc_zero(acc);
;     RowLoader al{H2, 1024}, bl{W, 1024};
;     gemm_mainloop_p(acc, al, bl, m0, n0, mtn * 256, ntn * 256, 1024, smem, gp);
;     gp.primed = more;
;     acc_foreach(acc, m0, n0, [&](int m, int n, float& v) {
;       const float r = fmaxf(v, 0.f);
;       AB[(size_t)m * 4096 + n] = f2bf(r * r);
;     });
	s_and_b64 vcc, exec, s[0:1]
	s_cbranch_vccz .Lff1_nomore
	s_lshl_b32 s7, s11, 8
	s_lshl_b32 s8, s12, 8
	v_add_u32_e32 v128, s7, v150
	v_lshlrev_b32_e32 v128, 11, v128
	v_add_u32_e32 v128, v128, v151
	v_add_u32_e32 v129, 0x4000, v128
	v_add_u32_e32 v130, 0x8000, v128
	v_add_u32_e32 v131, 0xc000, v128
	v_xor_b32_e32 v129, 0x40, v129
	v_xor_b32_e32 v131, 0x40, v131
	v_add_u32_e32 v132, s8, v150
	v_lshlrev_b32_e32 v132, 11, v132
	v_add_u32_e32 v132, v132, v151
	v_add_u32_e32 v133, 0x4000, v132
	v_add_u32_e32 v134, 0x8000, v132
	v_add_u32_e32 v135, 0xc000, v132
	v_xor_b32_e32 v133, 0x40, v133
	v_xor_b32_e32 v135, 0x40, v135
	v_add_u32_e32 v136, 0x40000, v128
	v_add_u32_e32 v137, 0x40000, v129
	v_add_u32_e32 v138, 0x40000, v130
	v_add_u32_e32 v139, 0x40000, v131
	v_add_u32_e32 v140, 0x40000, v132
	v_add_u32_e32 v141, 0x40000, v133
	v_add_u32_e32 v142, 0x40000, v134
	v_add_u32_e32 v143, 0x40000, v135
	s_mov_b64 s[22:23], s[18:19]
	s_mov_b64 s[14:15], s[20:21]
	s_cmp_lt_u32 s13, 0x4000
	s_cbranch_scc0 .Lff1_d4
	s_add_u32 m0, s13, 0x0
	s_nop 0
	global_load_lds_dwordx4 v128, s[22:23]
	s_add_u32 m0, m0, 0x400
	s_nop 0
	global_load_lds_dwordx4 v129, s[22:23]
	s_add_u32 m0, m0, 0x400
	s_nop 0
	global_load_lds_dwordx4 v130, s[22:23]
	s_add_u32 m0, m0, 0x400
	s_nop 0
	global_load_lds_dwordx4 v131, s[22:23]
	s_add_u32 m0, s13, 0x10000
	s_nop 0
	global_load_lds_dwordx4 v132, s[14:15]
	s_add_u32 m0, m0, 0x400
	s_nop 0
	global_load_lds_dwordx4 v133, s[14:15]
	s_add_u32 m0, m0, 0x400
	s_nop 0
	global_load_lds_dwordx4 v134, s[14:15]
	s_add_u32 m0, m0, 0x400
	s_nop 0
	global_load_lds_dwordx4 v135, s[14:15]
	s_add_u32 m0, s13, 0x4000
	s_nop 0
	global_load_lds_dwordx4 v136, s[22:23]
	s_add_u32 m0, m0, 0x400
	s_nop 0
	global_load_lds_dwordx4 v137, s[22:23]
	s_add_u32 m0, m0, 0x400
	s_nop 0
	global_load_lds_dwordx4 v138, s[22:23]
	s_add_u32 m0, m0, 0x400
	s_nop 0
	global_load_lds_dwordx4 v139, s[22:23]
	s_add_u32 m0, s13, 0x14000
	s_nop 0
	global_load_lds_dwordx4 v140, s[14:15]
	s_add_u32 m0, m0, 0x400
	s_nop 0
	global_load_lds_dwordx4 v141, s[14:15]
	s_add_u32 m0, m0, 0x400
	s_nop 0
	global_load_lds_dwordx4 v142, s[14:15]
	s_add_u32 m0, m0, 0x400
	s_nop 0
	global_load_lds_dwordx4 v143, s[14:15]
.Lff1_d4:
.Lff1_nomore:
	s_nop 7
	s_nop 7
	s_nop 3
	v_and_b32_e32 v160, 63, v202
	v_lshrrev_b32_e32 v161, 6, v202
	v_and_b32_e32 v164, 3, v161
	v_lshlrev_b32_e32 v164, 13, v164
	v_add_u32_e32 v164, 0x8000, v164
	v_lshrrev_b32_e32 v160, 2, v161
	v_lshl_add_u32 v164, v160, 16, v164
	v_and_b32_e32 v160, 63, v202
	v_and_b32_e32 v166, 15, v160
	v_lshrrev_b32_e32 v167, 4, v160
	v_lshl_add_u32 v168, v166, 7, v164
	v_and_b32_e32 v169, 1, v167
	v_lshl_add_u32 v168, v169, 3, v168
	v_lshrrev_b32_e32 v167, 1, v167
	v_and_b32_e32 v166, 7, v166
	v_xor_b32_e32 v166, v166, v167
	v_lshlrev_b32_e32 v166, 4, v166
	v_add_u32_e32 v170, v168, v166
	v_xor_b32_e32 v167, 0x20, v166
	v_add_u32_e32 v171, v168, v167
	v_xor_b32_e32 v167, 0x40, v166
	v_add_u32_e32 v172, v168, v167
	v_xor_b32_e32 v167, 0x60, v166
	v_add_u32_e32 v173, v168, v167
	v_and_b32_e32 v166, 31, v160
	v_lshrrev_b32_e32 v167, 5, v160
	v_lshlrev_b32_e32 v168, 7, v166
	v_lshl_add_u32 v168, v167, 3, v168
	v_add_u32_e32 v168, v164, v168
	v_and_b32_e32 v166, 7, v166
	v_lshlrev_b32_e32 v166, 4, v166
	v_lshrrev_b32_e32 v166, 3, v160
	v_and_b32_e32 v167, 7, v160
	v_lshrrev_b32_e32 v169, 2, v161
	v_lshl_add_u32 v169, v169, 7, v166
	v_add_u32_e32 v169, s5, v169
	v_mul_u32_u24_e32 v169, 0x2000, v169
	v_and_b32_e32 v168, 3, v161
	v_lshlrev_b32_e32 v168, 3, v168
	v_add_u32_e32 v168, v168, v167
	v_lshl_add_u32 v169, v168, 4, v169
	s_lshl_b32 s100, s4, 1
	v_add_u32_e32 v169, s100, v169
	v_xor_b32_e32 v167, v166, v167
	v_lshlrev_b32_e32 v167, 4, v167
	v_lshl_add_u32 v168, v166, 7, v167
	v_add_u32_e32 v168, v164, v168
	v_max_f32_e32 v0, 0, v0
	v_max_f32_e32 v1, 0, v1
	v_max_f32_e32 v2, 0, v2
	v_max_f32_e32 v3, 0, v3
	v_mul_f32_e32 v0, v0, v0
	v_mul_f32_e32 v1, v1, v1
	v_mul_f32_e32 v2, v2, v2
	v_mul_f32_e32 v3, v3, v3
	v_cvt_pk_bf16_f32 v0, v0, v1
	v_cvt_pk_bf16_f32 v1, v2, v3
	ds_write_b64 v170, v[0:1]
	v_max_f32_e32 v4, 0, v4
	v_max_f32_e32 v5, 0, v5
	v_max_f32_e32 v6, 0, v6
	v_max_f32_e32 v7, 0, v7
	v_mul_f32_e32 v4, v4, v4
	v_mul_f32_e32 v5, v5, v5
	v_mul_f32_e32 v6, v6, v6
	v_mul_f32_e32 v7, v7, v7
	v_cvt_pk_bf16_f32 v4, v4, v5
	v_cvt_pk_bf16_f32 v5, v6, v7
	ds_write_b64 v171, v[4:5]
	v_max_f32_e32 v8, 0, v8
	v_max_f32_e32 v9, 0, v9
	v_max_f32_e32 v10, 0, v10
	v_max_f32_e32 v11, 0, v11
	v_mul_f32_e32 v8, v8, v8
	v_mul_f32_e32 v9, v9, v9
	v_mul_f32_e32 v10, v10, v10
	v_mul_f32_e32 v11, v11, v11
	v_cvt_pk_bf16_f32 v8, v8, v9
	v_cvt_pk_bf16_f32 v9, v10, v11
	ds_write_b64 v172, v[8:9]
	v_max_f32_e32 v12, 0, v12
	v_max_f32_e32 v13, 0, v13
	v_max_f32_e32 v14, 0, v14
	v_max_f32_e32 v15, 0, v15
	v_mul_f32_e32 v12, v12, v12
	v_mul_f32_e32 v13, v13, v13
	v_mul_f32_e32 v14, v14, v14
	v_mul_f32_e32 v15, v15, v15
	v_cvt_pk_bf16_f32 v12, v12, v13
	v_cvt_pk_bf16_f32 v13, v14, v15
	ds_write_b64 v173, v[12:13]
	v_max_f32_e32 v16, 0, v16
	v_max_f32_e32 v17, 0, v17
	v_max_f32_e32 v18, 0, v18
	v_max_f32_e32 v19, 0, v19
	v_mul_f32_e32 v16, v16, v16
	v_mul_f32_e32 v17, v17, v17
	v_mul_f32_e32 v18, v18, v18
	v_mul_f32_e32 v19, v19, v19
	v_cvt_pk_bf16_f32 v16, v16, v17
	v_cvt_pk_bf16_f32 v17, v18, v19
	ds_write_b64 v170, v[16:17] offset:2048
	v_max_f32_e32 v20, 0, v20
	v_max_f32_e32 v21, 0, v21
	v_max_f32_e32 v22, 0, v22
	v_max_f32_e32 v23, 0, v23
	v_mul_f32_e32 v20, v20, v20
	v_mul_f32_e32 v21, v21, v21
	v_mul_f32_e32 v22, v22, v22
	v_mul_f32_e32 v23, v23, v23
	v_cvt_pk_bf16_f32 v20, v20, v21
	v_cvt_pk_bf16_f32 v21, v22, v23
	ds_write_b64 v171, v[20:21] offset:2048
; DEV u16 f2bf(float f) { return (u16)(pack2(f, f) & 0xffffu); }
; template <class F>
; DEV void acc_foreach(Acc& acc, int m0, int n0, F f) {
;   asm volatile("s_nop 7\n\ts_nop 7\n\ts_nop 3" ::: "memory");
;   const int tid = tidx_full();
;   const int wave = tid >> 6, lane = tid & 63;
;   const int wm = (wave >> 2) * 128, wn = (wave & 3) * 64;
;   const int lr = lane & 31, lh = lane >> 5;
; #pragma unroll
;   for (int i = 0; i < 4; ++i)
; #pragma unroll
;     for (int j = 0; j < 2; ++j)
; #pragma unroll
;       for (int r = 0; r < 16; ++r) {
;         const int m = m0 + wm + 32 * i + (r & 3) + 8 * (r >> 2) + 4 * lh;
;         const int n = n0 + wn + 32 * j + lr;
;         float v = acc[i][j][r];
;         f(m, n, v);
;         acc[i][j][r] = v;
;       }
; }
; DEV void phase_ff1(const Params& p, int g, char* smem) {
;     ...
;     acc_foreach(acc, m0, n0, [&](int m, int n, float& v) {
;       const float r = fmaxf(v, 0.f);
;       AB[(size_t)m * 4096 + n] = f2bf(r * r);
;     });
	v_max_f32_e32 v24, 0, v24
	v_max_f32_e32 v25, 0, v25
	v_max_f32_e32 v26, 0, v26
	v_max_f32_e32 v27, 0, v27
	v_mul_f32_e32 v24, v24, v24
	v_mul_f32_e32 v25, v25, v25
	v_mul_f32_e32 v26, v26, v26
	v_mul_f32_e32 v27, v27, v27
	v_cvt_pk_bf16_f32 v24, v24, v25
	v_cvt_pk_bf16_f32 v25, v26, v27
	ds_write_b64 v172, v[24:25] offset:2048
	v_max_f32_e32 v28, 0, v28
	v_max_f32_e32 v29, 0, v29
	v_max_f32_e32 v30, 0, v30
	v_max_f32_e32 v31, 0, v31
	v_mul_f32_e32 v28, v28, v28
	v_mul_f32_e32 v29, v29, v29
	v_mul_f32_e32 v30, v30, v30
	v_mul_f32_e32 v31, v31, v31
	v_cvt_pk_bf16_f32 v28, v28, v29
	v_cvt_pk_bf16_f32 v29, v30, v31
	ds_write_b64 v173, v[28:29] offset:2048
	v_max_f32_e32 v32, 0, v32
	v_max_f32_e32 v33, 0, v33
	v_max_f32_e32 v34, 0, v34
	v_max_f32_e32 v35, 0, v35
	v_mul_f32_e32 v32, v32, v32
	v_mul_f32_e32 v33, v33, v33
	v_mul_f32_e32 v34, v34, v34
	v_mul_f32_e32 v35, v35, v35
	v_cvt_pk_bf16_f32 v32, v32, v33
	v_cvt_pk_bf16_f32 v33, v34, v35
	ds_write_b64 v170, v[32:33] offset:4096
	v_max_f32_e32 v36, 0, v36
	v_max_f32_e32 v37, 0, v37
	v_max_f32_e32 v38, 0, v38
	v_max_f32_e32 v39, 0, v39
	v_mul_f32_e32 v36, v36, v36
	v_mul_f32_e32 v37, v37, v37
	v_mul_f32_e32 v38, v38, v38
	v_mul_f32_e32 v39, v39, v39
	v_cvt_pk_bf16_f32 v36, v36, v37
	v_cvt_pk_bf16_f32 v37, v38, v39
	ds_write_b64 v171, v[36:37] offset:4096
	v_max_f32_e32 v40, 0, v40
	v_max_f32_e32 v41, 0, v41
	v_max_f32_e32 v42, 0, v42
	v_max_f32_e32 v43, 0, v43
	v_mul_f32_e32 v40, v40, v40
	v_mul_f32_e32 v41, v41, v41
	v_mul_f32_e32 v42, v42, v42
	v_mul_f32_e32 v43, v43, v43
	v_cvt_pk_bf16_f32 v40, v40, v41
	v_cvt_pk_bf16_f32 v41, v42, v43
	ds_write_b64 v172, v[40:41] offset:4096
	v_max_f32_e32 v44, 0, v44
	v_max_f32_e32 v45, 0, v45
	v_max_f32_e32 v46, 0, v46
	v_max_f32_e32 v47, 0, v47
	v_mul_f32_e32 v44, v44, v44
	v_mul_f32_e32 v45, v45, v45
	v_mul_f32_e32 v46, v46, v46
	v_mul_f32_e32 v47, v47, v47
	v_cvt_pk_bf16_f32 v44, v44, v45
	v_cvt_pk_bf16_f32 v45, v46, v47
	ds_write_b64 v173, v[44:45] offset:4096
	v_max_f32_e32 v48, 0, v48
	v_max_f32_e32 v49, 0, v49
	v_max_f32_e32 v50, 0, v50
	v_max_f32_e32 v51, 0, v51
	v_mul_f32_e32 v48, v48, v48
	v_mul_f32_e32 v49, v49, v49
	v_mul_f32_e32 v50, v50, v50
	v_mul_f32_e32 v51, v51, v51
	v_cvt_pk_bf16_f32 v48, v48, v49
	v_cvt_pk_bf16_f32 v49, v50, v51
	ds_write_b64 v170, v[48:49] offset:6144
	v_max_f32_e32 v52, 0, v52
	v_max_f32_e32 v53, 0, v53
	v_max_f32_e32 v54, 0, v54
	v_max_f32_e32 v55, 0, v55
	v_mul_f32_e32 v52, v52, v52
	v_mul_f32_e32 v53, v53, v53
	v_mul_f32_e32 v54, v54, v54
	v_mul_f32_e32 v55, v55, v55
	v_cvt_pk_bf16_f32 v52, v52, v53
	v_cvt_pk_bf16_f32 v53, v54, v55
	ds_write_b64 v171, v[52:53] offset:6144
	v_max_f32_e32 v56, 0, v56
	v_max_f32_e32 v57, 0, v57
	v_max_f32_e32 v58, 0, v58
	v_max_f32_e32 v59, 0, v59
	v_mul_f32_e32 v56, v56, v56
	v_mul_f32_e32 v57, v57, v57
	v_mul_f32_e32 v58, v58, v58
	v_mul_f32_e32 v59, v59, v59
	v_cvt_pk_bf16_f32 v56, v56, v57
	v_cvt_pk_bf16_f32 v57, v58, v59
	ds_write_b64 v172, v[56:57] offset:6144
	v_max_f32_e32 v60, 0, v60
	v_max_f32_e32 v61, 0, v61
	v_max_f32_e32 v62, 0, v62
	v_max_f32_e32 v63, 0, v63
	v_mul_f32_e32 v60, v60, v60
	v_mul_f32_e32 v61, v61, v61
	v_mul_f32_e32 v62, v62, v62
	v_mul_f32_e32 v63, v63, v63
	v_cvt_pk_bf16_f32 v60, v60, v61
	v_cvt_pk_bf16_f32 v61, v62, v63
	ds_write_b64 v173, v[60:61] offset:6144
	s_waitcnt lgkmcnt(0)
	ds_read_b128 v[32:35], v168
	ds_read_b128 v[36:39], v168 offset:1024
	ds_read_b128 v[40:43], v168 offset:2048
	ds_read_b128 v[44:47], v168 offset:3072
	ds_read_b128 v[48:51], v168 offset:4096
	ds_read_b128 v[52:55], v168 offset:5120
	ds_read_b128 v[56:59], v168 offset:6144
	ds_read_b128 v[60:63], v168 offset:7168
	s_waitcnt lgkmcnt(7)
	global_store_dwordx4 v169, v[32:35], s[74:75]
	v_add_u32_e32 v169, 0x10000, v169
	s_waitcnt lgkmcnt(6)
	global_store_dwordx4 v169, v[36:39], s[74:75]
	v_add_u32_e32 v169, 0x10000, v169
	s_waitcnt lgkmcnt(5)
	global_store_dwordx4 v169, v[40:43], s[74:75]
	v_add_u32_e32 v169, 0x10000, v169
	s_waitcnt lgkmcnt(4)
	global_store_dwordx4 v169, v[44:47], s[74:75]
	v_add_u32_e32 v169, 0x10000, v169
	s_waitcnt lgkmcnt(3)
	global_store_dwordx4 v169, v[48:51], s[74:75]
	v_add_u32_e32 v169, 0x10000, v169
	s_waitcnt lgkmcnt(2)
	global_store_dwordx4 v169, v[52:55], s[74:75]
	v_add_u32_e32 v169, 0x10000, v169
	s_waitcnt lgkmcnt(1)
	global_store_dwordx4 v169, v[56:59], s[74:75]
	v_add_u32_e32 v169, 0x10000, v169
	s_waitcnt lgkmcnt(0)
; DEV u16 f2bf(float f) { return (u16)(pack2(f, f) & 0xffffu); }
; template <class F>
; DEV void acc_foreach(Acc& acc, int m0, int n0, F f) {
;   asm volatile("s_nop 7\n\ts_nop 7\n\ts_nop 3" ::: "memory");
;   const int tid = tidx_full();
;   const int wave = tid >> 6, lane = tid & 63;
;   const int wm = (wave >> 2) * 128, wn = (wave & 3) * 64;
;   const int lr = lane & 31, lh = lane >> 5;
; #pragma unroll
;   for (int i = 0; i < 4; ++i)
; #pragma unroll
;     for (int j = 0; j < 2; ++j)
; #pragma unroll
;       for (int r = 0; r < 16; ++r) {
;         const int m = m0 + wm + 32 * i + (r & 3) + 8 * (r >> 2) + 4 * lh;
;         const int n = n0 + wn + 32 * j + lr;
;         float v = acc[i][j][r];
;         f(m, n, v);
;         acc[i][j][r] = v;
;       }
; }
; DEV void phase_ff1(const Params& p, int g, char* smem) {
;     ...
;     acc_foreach(acc, m0, n0, [&](int m, int n, float& v) {
;       const float r = fmaxf(v, 0.f);
;       AB[(size_t)m * 4096 + n] = f2bf(r * r);
;     });
	global_store_dwordx4 v169, v[60:63], s[74:75]
	v_add_u32_e32 v169, 0x10000, v169
	v_max_f32_e32 v64, 0, v64
	v_max_f32_e32 v65, 0, v65
	v_max_f32_e32 v66, 0, v66
	v_max_f32_e32 v67, 0, v67
	v_mul_f32_e32 v64, v64, v64
	v_mul_f32_e32 v65, v65, v65
	v_mul_f32_e32 v66, v66, v66
	v_mul_f32_e32 v67, v67, v67
	v_cvt_pk_bf16_f32 v64, v64, v65
	v_cvt_pk_bf16_f32 v65, v66, v67
	ds_write_b64 v170, v[64:65]
	v_max_f32_e32 v68, 0, v68
	v_max_f32_e32 v69, 0, v69
	v_max_f32_e32 v70, 0, v70
	v_max_f32_e32 v71, 0, v71
	v_mul_f32_e32 v68, v68, v68
	v_mul_f32_e32 v69, v69, v69
	v_mul_f32_e32 v70, v70, v70
	v_mul_f32_e32 v71, v71, v71
	v_cvt_pk_bf16_f32 v68, v68, v69
	v_cvt_pk_bf16_f32 v69, v70, v71
	ds_write_b64 v171, v[68:69]
	v_max_f32_e32 v72, 0, v72
	v_max_f32_e32 v73, 0, v73
	v_max_f32_e32 v74, 0, v74
	v_max_f32_e32 v75, 0, v75
	v_mul_f32_e32 v72, v72, v72
	v_mul_f32_e32 v73, v73, v73
	v_mul_f32_e32 v74, v74, v74
	v_mul_f32_e32 v75, v75, v75
	v_cvt_pk_bf16_f32 v72, v72, v73
	v_cvt_pk_bf16_f32 v73, v74, v75
	ds_write_b64 v172, v[72:73]
	v_max_f32_e32 v76, 0, v76
	v_max_f32_e32 v77, 0, v77
	v_max_f32_e32 v78, 0, v78
	v_max_f32_e32 v79, 0, v79
	v_mul_f32_e32 v76, v76, v76
	v_mul_f32_e32 v77, v77, v77
	v_mul_f32_e32 v78, v78, v78
	v_mul_f32_e32 v79, v79, v79
	v_cvt_pk_bf16_f32 v76, v76, v77
	v_cvt_pk_bf16_f32 v77, v78, v79
	ds_write_b64 v173, v[76:77]
	v_max_f32_e32 v80, 0, v80
	v_max_f32_e32 v81, 0, v81
	v_max_f32_e32 v82, 0, v82
	v_max_f32_e32 v83, 0, v83
	v_mul_f32_e32 v80, v80, v80
	v_mul_f32_e32 v81, v81, v81
	v_mul_f32_e32 v82, v82, v82
	v_mul_f32_e32 v83, v83, v83
	v_cvt_pk_bf16_f32 v80, v80, v81
	v_cvt_pk_bf16_f32 v81, v82, v83
	ds_write_b64 v170, v[80:81] offset:2048
	v_max_f32_e32 v84, 0, v84
	v_max_f32_e32 v85, 0, v85
	v_max_f32_e32 v86, 0, v86
	v_max_f32_e32 v87, 0, v87
	v_mul_f32_e32 v84, v84, v84
	v_mul_f32_e32 v85, v85, v85
	v_mul_f32_e32 v86, v86, v86
	v_mul_f32_e32 v87, v87, v87
	v_cvt_pk_bf16_f32 v84, v84, v85
	v_cvt_pk_bf16_f32 v85, v86, v87
	ds_write_b64 v171, v[84:85] offset:2048
	v_max_f32_e32 v88, 0, v88
	v_max_f32_e32 v89, 0, v89
	v_max_f32_e32 v90, 0, v90
	v_max_f32_e32 v91, 0, v91
	v_mul_f32_e32 v88, v88, v88
	v_mul_f32_e32 v89, v89, v89
	v_mul_f32_e32 v90, v90, v90
	v_mul_f32_e32 v91, v91, v91
	v_cvt_pk_bf16_f32 v88, v88, v89
	v_cvt_pk_bf16_f32 v89, v90, v91
	ds_write_b64 v172, v[88:89] offset:2048
	v_max_f32_e32 v92, 0, v92
	v_max_f32_e32 v93, 0, v93
	v_max_f32_e32 v94, 0, v94
	v_max_f32_e32 v95, 0, v95
	v_mul_f32_e32 v92, v92, v92
	v_mul_f32_e32 v93, v93, v93
	v_mul_f32_e32 v94, v94, v94
	v_mul_f32_e32 v95, v95, v95
	v_cvt_pk_bf16_f32 v92, v92, v93
	v_cvt_pk_bf16_f32 v93, v94, v95
	ds_write_b64 v173, v[92:93] offset:2048
	v_max_f32_e32 v96, 0, v96
	v_max_f32_e32 v97, 0, v97
	v_max_f32_e32 v98, 0, v98
	v_max_f32_e32 v99, 0, v99
	v_mul_f32_e32 v96, v96, v96
	v_mul_f32_e32 v97, v97, v97
	v_mul_f32_e32 v98, v98, v98
	v_mul_f32_e32 v99, v99, v99
	v_cvt_pk_bf16_f32 v96, v96, v97
	v_cvt_pk_bf16_f32 v97, v98, v99
	ds_write_b64 v170, v[96:97] offset:4096
	v_max_f32_e32 v100, 0, v100
	v_max_f32_e32 v101, 0, v101
	v_max_f32_e32 v102, 0, v102
	v_max_f32_e32 v103, 0, v103
	v_mul_f32_e32 v100, v100, v100
	v_mul_f32_e32 v101, v101, v101
	v_mul_f32_e32 v102, v102, v102
	v_mul_f32_e32 v103, v103, v103
	v_cvt_pk_bf16_f32 v100, v100, v101
	v_cvt_pk_bf16_f32 v101, v102, v103
	ds_write_b64 v171, v[100:101] offset:4096
	v_max_f32_e32 v104, 0, v104
	v_max_f32_e32 v105, 0, v105
	v_max_f32_e32 v106, 0, v106
	v_max_f32_e32 v107, 0, v107
	v_mul_f32_e32 v104, v104, v104
	v_mul_f32_e32 v105, v105, v105
	v_mul_f32_e32 v106, v106, v106
	v_mul_f32_e32 v107, v107, v107
	v_cvt_pk_bf16_f32 v104, v104, v105
	v_cvt_pk_bf16_f32 v105, v106, v107
	ds_write_b64 v172, v[104:105] offset:4096
	v_max_f32_e32 v108, 0, v108
	v_max_f32_e32 v109, 0, v109
	v_max_f32_e32 v110, 0, v110
	v_max_f32_e32 v111, 0, v111
	v_mul_f32_e32 v108, v108, v108
	v_mul_f32_e32 v109, v109, v109
	v_mul_f32_e32 v110, v110, v110
	v_mul_f32_e32 v111, v111, v111
	v_cvt_pk_bf16_f32 v108, v108, v109
	v_cvt_pk_bf16_f32 v109, v110, v111
	ds_write_b64 v173, v[108:109] offset:4096
	v_max_f32_e32 v112, 0, v112
	v_max_f32_e32 v113, 0, v113
	v_max_f32_e32 v114, 0, v114
	v_max_f32_e32 v115, 0, v115
	v_mul_f32_e32 v112, v112, v112
	v_mul_f32_e32 v113, v113, v113
	v_mul_f32_e32 v114, v114, v114
	v_mul_f32_e32 v115, v115, v115
	v_cvt_pk_bf16_f32 v112, v112, v113
	v_cvt_pk_bf16_f32 v113, v114, v115
	ds_write_b64 v170, v[112:113] offset:6144
	v_max_f32_e32 v116, 0, v116
	v_max_f32_e32 v117, 0, v117
	v_max_f32_e32 v118, 0, v118
	v_max_f32_e32 v119, 0, v119
	v_mul_f32_e32 v116, v116, v116
	v_mul_f32_e32 v117, v117, v117
	v_mul_f32_e32 v118, v118, v118
	v_mul_f32_e32 v119, v119, v119
	v_cvt_pk_bf16_f32 v116, v116, v117
	v_cvt_pk_bf16_f32 v117, v118, v119
	ds_write_b64 v171, v[116:117] offset:6144
	v_max_f32_e32 v120, 0, v120
	v_max_f32_e32 v121, 0, v121
	v_max_f32_e32 v122, 0, v122
	v_max_f32_e32 v123, 0, v123
	v_mul_f32_e32 v120, v120, v120
	v_mul_f32_e32 v121, v121, v121
	v_mul_f32_e32 v122, v122, v122
	v_mul_f32_e32 v123, v123, v123
	v_cvt_pk_bf16_f32 v120, v120, v121
	v_cvt_pk_bf16_f32 v121, v122, v123
	ds_write_b64 v172, v[120:121] offset:6144
	v_max_f32_e32 v124, 0, v124
	v_max_f32_e32 v125, 0, v125
	v_max_f32_e32 v126, 0, v126
	v_max_f32_e32 v127, 0, v127
	v_mul_f32_e32 v124, v124, v124
	v_mul_f32_e32 v125, v125, v125
	v_mul_f32_e32 v126, v126, v126
	v_mul_f32_e32 v127, v127, v127
	v_cvt_pk_bf16_f32 v124, v124, v125
	v_cvt_pk_bf16_f32 v125, v126, v127
	ds_write_b64 v173, v[124:125] offset:6144
	s_waitcnt lgkmcnt(0)
	ds_read_b128 v[64:67], v168
	ds_read_b128 v[68:71], v168 offset:1024
	ds_read_b128 v[72:75], v168 offset:2048
	ds_read_b128 v[76:79], v168 offset:3072
	ds_read_b128 v[80:83], v168 offset:4096
	ds_read_b128 v[84:87], v168 offset:5120
	ds_read_b128 v[88:91], v168 offset:6144
	ds_read_b128 v[92:95], v168 offset:7168
	s_waitcnt lgkmcnt(7)
	global_store_dwordx4 v169, v[64:67], s[74:75]
	v_add_u32_e32 v169, 0x10000, v169
	s_waitcnt lgkmcnt(6)
	global_store_dwordx4 v169, v[68:71], s[74:75]
	v_add_u32_e32 v169, 0x10000, v169
	s_waitcnt lgkmcnt(5)
	global_store_dwordx4 v169, v[72:75], s[74:75]
	v_add_u32_e32 v169, 0x10000, v169
	s_waitcnt lgkmcnt(4)
	global_store_dwordx4 v169, v[76:79], s[74:75]
	v_add_u32_e32 v169, 0x10000, v169
	s_waitcnt lgkmcnt(3)
	global_store_dwordx4 v169, v[80:83], s[74:75]
	v_add_u32_e32 v169, 0x10000, v169
	s_waitcnt lgkmcnt(2)
	global_store_dwordx4 v169, v[84:87], s[74:75]
	v_add_u32_e32 v169, 0x10000, v169
	s_waitcnt lgkmcnt(1)
	global_store_dwordx4 v169, v[88:91], s[74:75]
	v_add_u32_e32 v169, 0x10000, v169
	s_waitcnt lgkmcnt(0)
	s_barrier
	global_store_dwordx4 v169, v[92:95], s[74:75]
	v_add_u32_e32 v169, 0x10000, v169
	s_mov_b64 s[4:5], 0
	s_branch .LBB0_1110
